# topk S-row prefetch + tightened bisect16 count loops (cmp->SGPR/addc pipelined, no s_nop)
# baseline (speedup 1.0000x reference)
; #define LAS __attribute__((address_space(3)))
; template <int CTRL> __device__ __forceinline__ int dpp_i(int x) { return __builtin_amdgcn_update_dpp(0, x, CTRL, 0xf, 0xf, false); }
; __device__ __forceinline__ void peer_select(const float* S, const int row, const int lane, LAS float* sv, LAS int* si, LAS float* fvL, LAS int* eL, int& e0o, int& e1o, float& g0o, float& g1o) {
;         {
;             const int grp = lane >> 2, qtr = lane & 3;
;             float x[32];
;             const float* sp = S + (size_t)row * NPQ + grp * 128 + qtr * 32;
; #pragma unroll
;             for (int k = 0; k < 8; ++k) { const f32x4 v = *(const f32x4*)(sp + 4 * k); x[4 * k] = v[0]; x[4 * k + 1] = v[1]; x[4 * k + 2] = v[2]; x[4 * k + 3] = v[3]; }
;             float lo, hi;
;             bisect16<4>(x, lo, hi);
;             int cA = 0, cB = 0;
; #pragma unroll
;             for (int j = 0; j < 32; ++j) { cA += (x[j] >= hi) ? 1 : 0; cB += (x[j] >= lo && x[j] < hi) ? 1 : 0; }
;             const int pk = cA | (cB << 8);
;             const int q0 = dpp_i<0x00>(pk), q1 = dpp_i<0x55>(pk), q2 = dpp_i<0xAA>(pk), q3 = dpp_i<0xFF>(pk);
;             const int tot = q0 + q1 + q2 + q3, pre = (qtr > 0 ? q0 : 0) + (qtr > 1 ? q1 : 0) + (qtr > 2 ? q2 : 0);
;             int pA = pre & 255, pB = (tot & 255) + (pre >> 8);
;             asm volatile("" : "+v"(lo), "+v"(hi));
; #pragma unroll
;             for (int j = 0; j < 32; ++j) {
;                 const bool isA = x[j] >= hi, isB = !isA && x[j] >= lo;
;                 const int slot = isA ? pA : pB;
;                 if ((isA || isB) && slot < 16) { sv[grp * 16 + slot] = x[j]; si[grp * 16 + slot] = qtr * 32 + j; }
; __device__ __forceinline__ void peer_topk_w(const Args& a, LAS unsigned char* lds, const int widx, const int nwtot, const int row_lo, const int row_hi) {
;     const int tid = threadIdx.x, lane = tid & 63;
;     unsigned char* ws = a.ws;
;     const float* S = (const float*)(ws + WS_S);
;     LAS float* sv = (LAS float*)(lds + __builtin_amdgcn_readfirstlane(tid >> 6) * 3072); LAS int* si = (LAS int*)(sv + 256); LAS float* fvL = (LAS float*)(si + 256); LAS int* eL = (LAS int*)(fvL + 128);
;     for (int row = row_lo + widx; row < row_hi; row += nwtot) {
.LBB0_930:
	v_lshrrev_b32_e32 v1, 2, v88
	v_and_b32_e32 v6, 3, v0
	v_lshlrev_b32_e32 v2, 9, v1
	v_mov_b32_e32 v3, 0
	v_lshl_add_u64 v[4:5], s[24:25], 0, v[2:3]
	v_lshlrev_b32_e32 v2, 7, v6
	v_lshl_add_u64 v[4:5], v[4:5], 0, v[2:3]
	s_mov_b64 s[0:1], 0x12146000
	v_lshlrev_b32_e32 v39, 4, v1
	v_lshrrev_b32_e32 v1, 3, v88
	s_mulk_i32 s4, 0xc00
	v_lshl_add_u64 v[34:35], v[4:5], 0, s[0:1]
	v_and_b32_e32 v2, 7, v0
	v_lshlrev_b32_e32 v4, 7, v1
	s_add_i32 s22, s4, 0
	v_lshl_or_b32 v5, v2, 3, v4
	v_cmp_eq_u32_e64 s[10:11], 0, v2
	v_cmp_lt_u32_e64 s[12:13], 1, v2
	v_cmp_lt_u32_e64 s[14:15], 3, v2
	v_lshlrev_b32_e32 v73, 4, v1
	v_lshlrev_b32_e32 v2, 2, v88
	v_mbcnt_lo_u32_b32 v1, -1, 0
	v_lshlrev_b32_e32 v38, 5, v6
	v_add_u32_e32 v74, s22, v2
	v_mov_b32_e32 v89, v3
	v_lshl_add_u64 v[2:3], s[24:25], 0, v[2:3]
	s_mov_b64 s[0:1], 0x1b346000
	v_mbcnt_hi_u32_b32 v1, -1, v1
	v_cmp_eq_u32_e64 s[4:5], 0, v6
	v_cmp_lt_u32_e64 s[6:7], 1, v6
	v_cmp_eq_u32_e64 s[8:9], 3, v6
	v_or_b32_e32 v40, 1, v38
	v_or_b32_e32 v41, 2, v38
	v_or_b32_e32 v42, 3, v38
	v_or_b32_e32 v43, 4, v38
	v_or_b32_e32 v44, 5, v38
	v_or_b32_e32 v45, 6, v38
	v_or_b32_e32 v46, 7, v38
	v_or_b32_e32 v47, 8, v38
	v_or_b32_e32 v48, 9, v38
	v_or_b32_e32 v49, 10, v38
	v_or_b32_e32 v50, 11, v38
	v_or_b32_e32 v51, 12, v38
	v_or_b32_e32 v52, 13, v38
	v_or_b32_e32 v53, 14, v38
	v_or_b32_e32 v54, 15, v38
	v_or_b32_e32 v55, 16, v38
	v_or_b32_e32 v56, 17, v38
	v_or_b32_e32 v57, 18, v38
	v_or_b32_e32 v58, 19, v38
	v_or_b32_e32 v59, 20, v38
	v_or_b32_e32 v60, 21, v38
	v_or_b32_e32 v61, 22, v38
	v_or_b32_e32 v62, 23, v38
	v_or_b32_e32 v63, 24, v38
	v_or_b32_e32 v64, 25, v38
	v_or_b32_e32 v65, 26, v38
	v_or_b32_e32 v66, 27, v38
	v_or_b32_e32 v67, 28, v38
	v_or_b32_e32 v68, 29, v38
	v_or_b32_e32 v69, 30, v38
	v_or_b32_e32 v70, 31, v38
	v_add_u32_e32 v71, s22, v5
	v_add_u32_e32 v72, s22, v4
	v_lshl_add_u64 v[36:37], v[2:3], 0, s[0:1]
	v_lshl_or_b32 v75, v1, 2, 28
	s_ashr_i32 s35, s34, 31
	s_lshl_b64 s[0:1], s[34:35], 13
	v_lshl_add_u64 v[152:153], v[34:35], 0, s[0:1]
	global_load_dwordx4 v[120:123], v[152:153], off
	global_load_dwordx4 v[124:127], v[152:153], off offset:16
	global_load_dwordx4 v[128:131], v[152:153], off offset:32
	global_load_dwordx4 v[132:135], v[152:153], off offset:48
	global_load_dwordx4 v[136:139], v[152:153], off offset:64
	global_load_dwordx4 v[140:143], v[152:153], off offset:80
	global_load_dwordx4 v[144:147], v[152:153], off offset:96
	global_load_dwordx4 v[148:151], v[152:153], off offset:112
	s_branch .LBB0_932

; template <int GS> __device__ __forceinline__ int grp_sum_i(int v) { v += dpp_i<0xB1>(v); v += dpp_i<0x4E>(v); if (GS == 8) v += dpp_i<0x141>(v); return v; }
; template <int GS> __device__ __forceinline__ float grp_max_f(float v) { v = fmaxf(v, dpp_f<0xB1>(v)); v = fmaxf(v, dpp_f<0x4E>(v)); if (GS == 8) v = fmaxf(v, dpp_f<0x141>(v)); return v; }
; template <int GS> __device__ __forceinline__ float grp_min_f(float v) { v = fminf(v, dpp_f<0xB1>(v)); v = fminf(v, dpp_f<0x4E>(v)); if (GS == 8) v = fminf(v, dpp_f<0x141>(v)); return v; }
; template <int GS> __device__ __forceinline__ void bisect16(const float (&x)[32], float& lo, float& hi) {
;     float mx = x[0], mn = x[0];
; #pragma unroll
;     for (int j = 1; j < 32; ++j) { mx = fmaxf(mx, x[j]); mn = fminf(mn, x[j]); }
;     hi = grp_max_f<GS>(mx); lo = grp_min_f<GS>(mn);
;     bool done = false;
; #pragma unroll 1
;     for (int it = 0; it < 48; ++it) {
;         const float t = 0.5f * (lo + hi);
;         const bool conv = !(t > lo && t < hi);
;         int cnt = 0;
; #pragma unroll
;         for (int j = 0; j < 32; ++j) cnt += (x[j] >= t) ? 1 : 0;
;         cnt = grp_sum_i<GS>(cnt);
;         const bool upd = !done && !conv, ex = cnt == 16, gt = cnt > 16;
;         const float nlo = (ex || gt) ? t : lo, nhi = (ex || !gt) ? t : hi;
;         lo = upd ? nlo : lo; hi = upd ? nhi : hi;
;         done = done || conv || ex;
;         if (__ballot(!done) == 0ull) break;
;     }
; __device__ __forceinline__ void peer_select(const float* S, const int row, const int lane, LAS float* sv, LAS int* si, LAS float* fvL, LAS int* eL, int& e0o, int& e1o, float& g0o, float& g1o) {
;     ...
;             const int grp = lane >> 2, qtr = lane & 3;
;             float x[32];
;             const float* sp = S + (size_t)row * NPQ + grp * 128 + qtr * 32;
; #pragma unroll
;             for (int k = 0; k < 8; ++k) { const f32x4 v = *(const f32x4*)(sp + 4 * k); x[4 * k] = v[0]; x[4 * k + 1] = v[1]; x[4 * k + 2] = v[2]; x[4 * k + 3] = v[3]; }
.LBB0_932:
	s_ashr_i32 s35, s34, 31
	s_waitcnt vmcnt(0)
	v_mov_b64_e32 v[30:31], v[120:121]
	v_mov_b64_e32 v[32:33], v[122:123]
	v_mov_b64_e32 v[26:27], v[124:125]
	v_mov_b64_e32 v[28:29], v[126:127]
	v_mov_b64_e32 v[22:23], v[128:129]
	v_mov_b64_e32 v[24:25], v[130:131]
	v_mov_b64_e32 v[18:19], v[132:133]
	v_mov_b64_e32 v[20:21], v[134:135]
	v_mov_b64_e32 v[14:15], v[136:137]
	v_mov_b64_e32 v[16:17], v[138:139]
	v_mov_b64_e32 v[10:11], v[140:141]
	v_mov_b64_e32 v[12:13], v[142:143]
	v_mov_b64_e32 v[6:7], v[144:145]
	v_mov_b64_e32 v[8:9], v[146:147]
	v_mov_b64_e32 v[2:3], v[148:149]
	v_mov_b64_e32 v[4:5], v[150:151]
	s_add_i32 s0, s34, s2
	s_cmpk_lt_i32 s0, 0x4000
	s_cselect_b32 s0, s0, s34
	s_ashr_i32 s1, s0, 31
	s_lshl_b64 s[0:1], s[0:1], 13
	v_lshl_add_u64 v[152:153], v[34:35], 0, s[0:1]
	global_load_dwordx4 v[120:123], v[152:153], off
	global_load_dwordx4 v[124:127], v[152:153], off offset:16
	global_load_dwordx4 v[128:131], v[152:153], off offset:32
	global_load_dwordx4 v[132:135], v[152:153], off offset:48
	global_load_dwordx4 v[136:139], v[152:153], off offset:64
	global_load_dwordx4 v[140:143], v[152:153], off offset:80
	global_load_dwordx4 v[144:147], v[152:153], off offset:96
	global_load_dwordx4 v[148:151], v[152:153], off offset:112
	v_mov_b32_e32 v76, 0
	v_mov_b32_e32 v79, 0
	v_mov_b32_e32 v77, 0
	v_mov_b32_e32 v80, 0
	v_mov_b32_e32 v78, 47
	s_mov_b64 s[0:1], 0
	v_max_f32_e32 v81, v31, v31
	v_max_f32_e32 v82, v30, v30
	v_max_f32_e32 v83, v82, v81
	v_min_f32_e32 v81, v82, v81
	v_max3_f32 v82, v83, v32, v33
	v_min3_f32 v81, v81, v32, v33
	v_max3_f32 v82, v82, v26, v27
	v_min3_f32 v81, v81, v26, v27
	v_max3_f32 v82, v82, v28, v29
	v_min3_f32 v81, v81, v28, v29
	v_max3_f32 v82, v82, v22, v23
	v_min3_f32 v81, v81, v22, v23
	v_max3_f32 v82, v82, v24, v25
	v_min3_f32 v81, v81, v24, v25
	v_max3_f32 v82, v82, v18, v19
	v_min3_f32 v81, v81, v18, v19
	v_max3_f32 v82, v82, v20, v21
	v_min3_f32 v81, v81, v20, v21
	v_max3_f32 v82, v82, v14, v15
	v_min3_f32 v81, v81, v14, v15
	v_max3_f32 v82, v82, v16, v17
	v_min3_f32 v81, v81, v16, v17
	v_max3_f32 v82, v82, v10, v11
	v_min3_f32 v81, v81, v10, v11
	v_max3_f32 v82, v82, v12, v13
	v_min3_f32 v81, v81, v12, v13
	v_max3_f32 v82, v82, v6, v7
	v_min3_f32 v81, v81, v6, v7
	v_max3_f32 v82, v82, v8, v9
	v_min3_f32 v81, v81, v8, v9
	v_max3_f32 v82, v82, v2, v3
	v_min3_f32 v81, v81, v2, v3
	v_max3_f32 v82, v82, v4, v5
	v_min3_f32 v81, v81, v4, v5
	s_nop 0
	v_mov_b32_dpp v76, v82 quad_perm:[1,0,3,2] row_mask:0xf bank_mask:0xf
	v_mov_b32_dpp v79, v81 quad_perm:[1,0,3,2] row_mask:0xf bank_mask:0xf
	v_max_f32_e32 v76, v76, v76
	v_max_f32_e32 v79, v79, v79
	v_max_f32_e32 v76, v82, v76
	v_min_f32_e32 v79, v81, v79
	s_nop 0
	v_mov_b32_dpp v77, v76 quad_perm:[2,3,0,1] row_mask:0xf bank_mask:0xf
	v_mov_b32_dpp v80, v79 quad_perm:[2,3,0,1] row_mask:0xf bank_mask:0xf
	v_max_f32_e32 v77, v77, v77
	v_max_f32_e32 v80, v80, v80
	v_max_f32_e32 v76, v76, v77
	v_min_f32_e32 v77, v79, v80
.LBB0_933:
	v_add_f32_e32 v79, v77, v76
	v_mul_f32_e32 v79, 0.5, v79
	v_cmp_nlt_f32_e64 s[16:17], v79, v76
	v_cmp_ngt_f32_e64 s[18:19], v79, v77
	v_subrev_co_u32_e32 v78, vcc, 1, v78
	v_mov_b32_e32 v80, 0
	s_or_b64 s[28:29], s[18:19], s[16:17]
	v_cmp_ge_f32_e64 s[18:19], v31, v79
	v_cmp_ge_f32_e64 s[20:21], v30, v79
	v_cmp_ge_f32_e64 s[16:17], v32, v79
	v_addc_co_u32_e64 v80, s[18:19], 0, v80, s[18:19]
	v_cmp_ge_f32_e64 s[18:19], v26, v79
	v_addc_co_u32_e64 v80, s[20:21], 0, v80, s[20:21]
	v_cmp_ge_f32_e64 s[20:21], v28, v79
	v_addc_co_u32_e64 v80, s[16:17], 0, v80, s[16:17]
	v_cmp_ge_f32_e64 s[16:17], v22, v79
	v_addc_co_u32_e64 v80, s[18:19], 0, v80, s[18:19]
	v_cmp_ge_f32_e64 s[18:19], v24, v79
	v_addc_co_u32_e64 v80, s[20:21], 0, v80, s[20:21]
	v_cmp_ge_f32_e64 s[20:21], v18, v79
	v_addc_co_u32_e64 v80, s[16:17], 0, v80, s[16:17]
	v_cmp_ge_f32_e64 s[16:17], v20, v79
	v_addc_co_u32_e64 v80, s[18:19], 0, v80, s[18:19]
	v_cmp_ge_f32_e64 s[18:19], v14, v79
	v_addc_co_u32_e64 v80, s[20:21], 0, v80, s[20:21]
	v_cmp_ge_f32_e64 s[20:21], v16, v79
	v_addc_co_u32_e64 v80, s[16:17], 0, v80, s[16:17]
	v_cmp_ge_f32_e64 s[16:17], v10, v79
	v_addc_co_u32_e64 v80, s[18:19], 0, v80, s[18:19]
	v_cmp_ge_f32_e64 s[18:19], v12, v79
	v_addc_co_u32_e64 v80, s[20:21], 0, v80, s[20:21]
	v_cmp_ge_f32_e64 s[20:21], v6, v79
	v_addc_co_u32_e64 v80, s[16:17], 0, v80, s[16:17]
	v_cmp_ge_f32_e64 s[16:17], v8, v79
	v_addc_co_u32_e64 v80, s[18:19], 0, v80, s[18:19]
	v_cmp_ge_f32_e64 s[18:19], v2, v79
	v_addc_co_u32_e64 v80, s[20:21], 0, v80, s[20:21]
	v_cmp_ge_f32_e64 s[20:21], v4, v79
	v_addc_co_u32_e64 v80, s[16:17], 0, v80, s[16:17]
	v_cmp_ge_f32_e64 s[16:17], v33, v79
	v_addc_co_u32_e64 v80, s[18:19], 0, v80, s[18:19]
	v_cmp_ge_f32_e64 s[18:19], v27, v79
	v_addc_co_u32_e64 v80, s[20:21], 0, v80, s[20:21]
	v_cmp_ge_f32_e64 s[20:21], v29, v79
	v_addc_co_u32_e64 v80, s[16:17], 0, v80, s[16:17]
	v_cmp_ge_f32_e64 s[16:17], v23, v79
	v_addc_co_u32_e64 v80, s[18:19], 0, v80, s[18:19]
	v_cmp_ge_f32_e64 s[18:19], v25, v79
	v_addc_co_u32_e64 v80, s[20:21], 0, v80, s[20:21]
	v_cmp_ge_f32_e64 s[20:21], v19, v79
	v_addc_co_u32_e64 v80, s[16:17], 0, v80, s[16:17]
	v_cmp_ge_f32_e64 s[16:17], v21, v79
	v_addc_co_u32_e64 v80, s[18:19], 0, v80, s[18:19]
	v_cmp_ge_f32_e64 s[18:19], v15, v79
	v_addc_co_u32_e64 v80, s[20:21], 0, v80, s[20:21]
	v_cmp_ge_f32_e64 s[20:21], v17, v79
	v_addc_co_u32_e64 v80, s[16:17], 0, v80, s[16:17]
	v_cmp_ge_f32_e64 s[16:17], v11, v79
	v_addc_co_u32_e64 v80, s[18:19], 0, v80, s[18:19]
	v_cmp_ge_f32_e64 s[18:19], v13, v79
	v_addc_co_u32_e64 v80, s[20:21], 0, v80, s[20:21]
	v_cmp_ge_f32_e64 s[20:21], v7, v79
	v_addc_co_u32_e64 v80, s[16:17], 0, v80, s[16:17]
	v_cmp_ge_f32_e64 s[16:17], v9, v79
	v_addc_co_u32_e64 v80, s[18:19], 0, v80, s[18:19]
	v_cmp_ge_f32_e64 s[18:19], v3, v79
	v_addc_co_u32_e64 v80, s[20:21], 0, v80, s[20:21]
	v_cmp_ge_f32_e64 s[20:21], v5, v79
	v_addc_co_u32_e64 v80, s[16:17], 0, v80, s[16:17]
	v_addc_co_u32_e64 v80, s[18:19], 0, v80, s[18:19]
	v_addc_co_u32_e64 v80, s[20:21], 0, v80, s[20:21]
	s_nop 1
	v_add_u32_dpp v80, v80, v80 quad_perm:[1,0,3,2] row_mask:0xf bank_mask:0xf bound_ctrl:1
	s_nop 1
	v_add_u32_dpp v80, v80, v80 quad_perm:[2,3,0,1] row_mask:0xf bank_mask:0xf bound_ctrl:1
	v_cmp_lt_i32_e64 s[20:21], 15, v80
	v_cmp_eq_u32_e64 s[16:17], 16, v80
	v_cmp_lt_i32_e64 s[18:19], 16, v80
	v_cndmask_b32_e64 v80, v77, v79, s[20:21]
	s_or_b64 s[20:21], s[0:1], s[28:29]
	s_or_b64 s[0:1], s[20:21], s[16:17]
	s_xor_b64 s[16:17], s[0:1], -1
	v_cndmask_b32_e64 v77, v80, v77, s[20:21]
	v_cndmask_b32_e64 v80, 0, 1, s[16:17]
	s_or_b64 s[18:19], s[20:21], s[18:19]
	v_cmp_ne_u32_e64 s[16:17], 0, v80
	s_cmp_eq_u64 s[16:17], 0
	s_cselect_b64 s[16:17], -1, 0
	s_or_b64 s[16:17], s[16:17], vcc
	s_andn2_b64 vcc, exec, s[16:17]
	v_cndmask_b32_e64 v76, v79, v76, s[18:19]
	s_cbranch_vccnz .LBB0_933
; __device__ __forceinline__ void peer_select(const float* S, const int row, const int lane, LAS float* sv, LAS int* si, LAS float* fvL, LAS int* eL, int& e0o, int& e1o, float& g0o, float& g1o) {
;     ...
;             int cA = 0, cB = 0;
; #pragma unroll
;             for (int j = 0; j < 32; ++j) { cA += (x[j] >= hi) ? 1 : 0; cB += (x[j] >= lo && x[j] < hi) ? 1 : 0; }
;             const int pk = cA | (cB << 8);
	v_cmp_ge_f32_e64 s[18:19], v31, v76
	v_cmp_lt_f32_e64 s[20:21], v31, v76
	v_cmp_ge_f32_e32 vcc, v30, v77
	v_cndmask_b32_e64 v78, 0, 1, s[18:19]
	v_cmp_ge_f32_e64 s[18:19], v30, v76
	v_cmp_lt_f32_e64 s[16:17], v30, v76
	s_and_b64 vcc, vcc, s[16:17]
	v_addc_co_u32_e64 v78, s[18:19], 0, v78, s[18:19]
	v_cmp_ge_f32_e64 s[18:19], v31, v77
	s_and_b64 s[0:1], s[18:19], s[20:21]
	v_cndmask_b32_e64 v79, 0, 1, s[0:1]
	v_addc_co_u32_e32 v79, vcc, 0, v79, vcc
	v_cmp_ge_f32_e32 vcc, v32, v76
	v_cmp_lt_f32_e64 s[16:17], v32, v76
	v_mov_b32_e32 v82, 0
	v_cndmask_b32_e64 v80, 0, 1, vcc
	v_cmp_ge_f32_e32 vcc, v32, v77
	s_and_b64 s[0:1], vcc, s[16:17]
	v_cmp_ge_f32_e32 vcc, v33, v76
	v_cmp_lt_f32_e64 s[16:17], v33, v76
	v_cndmask_b32_e64 v81, 0, 1, s[0:1]
	v_addc_co_u32_e32 v78, vcc, v78, v80, vcc
	v_cmp_ge_f32_e32 vcc, v33, v77
	s_and_b64 vcc, vcc, s[16:17]
	v_cmp_lt_f32_e64 s[16:17], v26, v76
	v_addc_co_u32_e32 v79, vcc, v79, v81, vcc
	v_cmp_ge_f32_e32 vcc, v26, v76
	s_nop 1
	v_cndmask_b32_e64 v80, 0, 1, vcc
	v_cmp_ge_f32_e32 vcc, v26, v77
	s_and_b64 s[0:1], vcc, s[16:17]
	v_cmp_ge_f32_e32 vcc, v27, v76
	v_cmp_lt_f32_e64 s[16:17], v27, v76
	v_cndmask_b32_e64 v81, 0, 1, s[0:1]
	v_addc_co_u32_e32 v78, vcc, v78, v80, vcc
	v_cmp_ge_f32_e32 vcc, v27, v77
	s_and_b64 vcc, vcc, s[16:17]
	v_cmp_lt_f32_e64 s[16:17], v28, v76
	v_addc_co_u32_e32 v79, vcc, v79, v81, vcc
	v_cmp_ge_f32_e32 vcc, v28, v76
	s_nop 1
	v_cndmask_b32_e64 v80, 0, 1, vcc
	v_cmp_ge_f32_e32 vcc, v28, v77
	s_and_b64 s[0:1], vcc, s[16:17]
	v_cmp_ge_f32_e32 vcc, v29, v76
	v_cmp_lt_f32_e64 s[16:17], v29, v76
	v_cndmask_b32_e64 v81, 0, 1, s[0:1]
	v_addc_co_u32_e32 v78, vcc, v78, v80, vcc
	v_cmp_ge_f32_e32 vcc, v29, v77
	s_and_b64 vcc, vcc, s[16:17]
	v_cmp_lt_f32_e64 s[16:17], v22, v76
	v_addc_co_u32_e32 v79, vcc, v79, v81, vcc
	v_cmp_ge_f32_e32 vcc, v22, v76
	s_nop 1
	v_cndmask_b32_e64 v80, 0, 1, vcc
	v_cmp_ge_f32_e32 vcc, v22, v77
	s_and_b64 s[0:1], vcc, s[16:17]
	v_cmp_ge_f32_e32 vcc, v23, v76
	v_cmp_lt_f32_e64 s[16:17], v23, v76
	v_cndmask_b32_e64 v81, 0, 1, s[0:1]
	v_addc_co_u32_e32 v78, vcc, v78, v80, vcc
	v_cmp_ge_f32_e32 vcc, v23, v77
	s_and_b64 vcc, vcc, s[16:17]
	v_cmp_lt_f32_e64 s[16:17], v24, v76
	v_addc_co_u32_e32 v79, vcc, v79, v81, vcc
	v_cmp_ge_f32_e32 vcc, v24, v76
	s_nop 1
	v_cndmask_b32_e64 v80, 0, 1, vcc
	v_cmp_ge_f32_e32 vcc, v24, v77
	s_and_b64 s[0:1], vcc, s[16:17]
	v_cmp_ge_f32_e32 vcc, v25, v76
	v_cmp_lt_f32_e64 s[16:17], v25, v76
	v_cndmask_b32_e64 v81, 0, 1, s[0:1]
	v_addc_co_u32_e32 v78, vcc, v78, v80, vcc
	v_cmp_ge_f32_e32 vcc, v25, v77
	s_and_b64 vcc, vcc, s[16:17]
	v_cmp_lt_f32_e64 s[16:17], v18, v76
	v_addc_co_u32_e32 v79, vcc, v79, v81, vcc
	v_cmp_ge_f32_e32 vcc, v18, v76
	s_nop 1
	v_cndmask_b32_e64 v80, 0, 1, vcc
	v_cmp_ge_f32_e32 vcc, v18, v77
	s_and_b64 s[0:1], vcc, s[16:17]
	v_cmp_ge_f32_e32 vcc, v19, v76
	v_cmp_lt_f32_e64 s[16:17], v19, v76
	v_cndmask_b32_e64 v81, 0, 1, s[0:1]
	v_addc_co_u32_e32 v78, vcc, v78, v80, vcc
	v_cmp_ge_f32_e32 vcc, v19, v77
	s_and_b64 vcc, vcc, s[16:17]
	v_cmp_lt_f32_e64 s[16:17], v20, v76
	v_addc_co_u32_e32 v79, vcc, v79, v81, vcc
	v_cmp_ge_f32_e32 vcc, v20, v76
	s_nop 1
	v_cndmask_b32_e64 v80, 0, 1, vcc
	v_cmp_ge_f32_e32 vcc, v20, v77
	s_and_b64 s[0:1], vcc, s[16:17]
	v_cmp_ge_f32_e32 vcc, v21, v76
	v_cmp_lt_f32_e64 s[16:17], v21, v76
	v_cndmask_b32_e64 v81, 0, 1, s[0:1]
	v_addc_co_u32_e32 v78, vcc, v78, v80, vcc
	v_cmp_ge_f32_e32 vcc, v21, v77
	s_and_b64 vcc, vcc, s[16:17]
	v_cmp_lt_f32_e64 s[16:17], v14, v76
	v_addc_co_u32_e32 v79, vcc, v79, v81, vcc
	v_cmp_ge_f32_e32 vcc, v14, v76
	s_nop 1
	v_cndmask_b32_e64 v80, 0, 1, vcc
	v_cmp_ge_f32_e32 vcc, v14, v77
	s_and_b64 s[0:1], vcc, s[16:17]
	v_cmp_ge_f32_e32 vcc, v15, v76
	v_cmp_lt_f32_e64 s[16:17], v15, v76
	v_cndmask_b32_e64 v81, 0, 1, s[0:1]
	v_addc_co_u32_e32 v78, vcc, v78, v80, vcc
	v_cmp_ge_f32_e32 vcc, v15, v77
	s_and_b64 vcc, vcc, s[16:17]
	v_cmp_lt_f32_e64 s[16:17], v16, v76
	v_addc_co_u32_e32 v79, vcc, v79, v81, vcc
	v_cmp_ge_f32_e32 vcc, v16, v76
	s_nop 1
	v_cndmask_b32_e64 v80, 0, 1, vcc
	v_cmp_ge_f32_e32 vcc, v16, v77
	s_and_b64 s[0:1], vcc, s[16:17]
	v_cmp_ge_f32_e32 vcc, v17, v76
	v_cmp_lt_f32_e64 s[16:17], v17, v76
	v_cndmask_b32_e64 v81, 0, 1, s[0:1]
	v_addc_co_u32_e32 v78, vcc, v78, v80, vcc
	v_cmp_ge_f32_e32 vcc, v17, v77
	s_and_b64 vcc, vcc, s[16:17]
	v_cmp_lt_f32_e64 s[16:17], v10, v76
	v_addc_co_u32_e32 v79, vcc, v79, v81, vcc
	v_cmp_ge_f32_e32 vcc, v10, v76
	s_nop 1
	v_cndmask_b32_e64 v80, 0, 1, vcc
	v_cmp_ge_f32_e32 vcc, v10, v77
	s_and_b64 s[0:1], vcc, s[16:17]
	v_cmp_ge_f32_e32 vcc, v11, v76
	v_cmp_lt_f32_e64 s[16:17], v11, v76
	v_cndmask_b32_e64 v81, 0, 1, s[0:1]
	v_addc_co_u32_e32 v78, vcc, v78, v80, vcc
	v_cmp_ge_f32_e32 vcc, v11, v77
	s_and_b64 vcc, vcc, s[16:17]
	v_cmp_lt_f32_e64 s[16:17], v12, v76
	v_addc_co_u32_e32 v79, vcc, v79, v81, vcc
	v_cmp_ge_f32_e32 vcc, v12, v76
	s_nop 1
	v_cndmask_b32_e64 v80, 0, 1, vcc
	v_cmp_ge_f32_e32 vcc, v12, v77
	s_and_b64 s[0:1], vcc, s[16:17]
	v_cmp_ge_f32_e32 vcc, v13, v76
	v_cmp_lt_f32_e64 s[16:17], v13, v76
	v_cndmask_b32_e64 v81, 0, 1, s[0:1]
	v_addc_co_u32_e32 v78, vcc, v78, v80, vcc
	v_cmp_ge_f32_e32 vcc, v13, v77
	s_and_b64 vcc, vcc, s[16:17]
	v_cmp_lt_f32_e64 s[16:17], v6, v76
	v_addc_co_u32_e32 v79, vcc, v79, v81, vcc
	v_cmp_ge_f32_e32 vcc, v6, v76
	s_nop 1
	v_cndmask_b32_e64 v80, 0, 1, vcc
	v_cmp_ge_f32_e32 vcc, v6, v77
	s_and_b64 s[0:1], vcc, s[16:17]
	v_cmp_ge_f32_e32 vcc, v7, v76
	v_cmp_lt_f32_e64 s[16:17], v7, v76
	v_cndmask_b32_e64 v81, 0, 1, s[0:1]
	v_addc_co_u32_e32 v78, vcc, v78, v80, vcc
	v_cmp_ge_f32_e32 vcc, v7, v77
	s_and_b64 vcc, vcc, s[16:17]
	v_cmp_lt_f32_e64 s[16:17], v8, v76
; template <int CTRL> __device__ __forceinline__ int dpp_i(int x) { return __builtin_amdgcn_update_dpp(0, x, CTRL, 0xf, 0xf, false); }
; __device__ __forceinline__ void peer_select(const float* S, const int row, const int lane, LAS float* sv, LAS int* si, LAS float* fvL, LAS int* eL, int& e0o, int& e1o, float& g0o, float& g1o) {
;     ...
;             for (int j = 0; j < 32; ++j) { cA += (x[j] >= hi) ? 1 : 0; cB += (x[j] >= lo && x[j] < hi) ? 1 : 0; }
;             const int pk = cA | (cB << 8);
;             const int q0 = dpp_i<0x00>(pk), q1 = dpp_i<0x55>(pk), q2 = dpp_i<0xAA>(pk), q3 = dpp_i<0xFF>(pk);
;             const int tot = q0 + q1 + q2 + q3, pre = (qtr > 0 ? q0 : 0) + (qtr > 1 ? q1 : 0) + (qtr > 2 ? q2 : 0);
;             int pA = pre & 255, pB = (tot & 255) + (pre >> 8);
;             asm volatile("" : "+v"(lo), "+v"(hi));
; #pragma unroll
;             for (int j = 0; j < 32; ++j) {
;                 const bool isA = x[j] >= hi, isB = !isA && x[j] >= lo;
;                 const int slot = isA ? pA : pB;
;                 if ((isA || isB) && slot < 16) { sv[grp * 16 + slot] = x[j]; si[grp * 16 + slot] = qtr * 32 + j; }
;                 pA += isA ? 1 : 0; pB += isB ? 1 : 0;
	v_addc_co_u32_e32 v79, vcc, v79, v81, vcc
	v_cmp_ge_f32_e32 vcc, v8, v76
	s_nop 1
	v_cndmask_b32_e64 v80, 0, 1, vcc
	v_cmp_ge_f32_e32 vcc, v8, v77
	s_and_b64 s[0:1], vcc, s[16:17]
	v_cmp_ge_f32_e32 vcc, v9, v76
	v_cmp_lt_f32_e64 s[16:17], v9, v76
	v_cndmask_b32_e64 v81, 0, 1, s[0:1]
	v_addc_co_u32_e32 v78, vcc, v78, v80, vcc
	v_cmp_ge_f32_e32 vcc, v9, v77
	s_and_b64 vcc, vcc, s[16:17]
	v_cmp_lt_f32_e64 s[16:17], v2, v76
	v_addc_co_u32_e32 v79, vcc, v79, v81, vcc
	v_cmp_ge_f32_e32 vcc, v2, v76
	s_nop 1
	v_cndmask_b32_e64 v80, 0, 1, vcc
	v_cmp_ge_f32_e32 vcc, v2, v77
	s_and_b64 s[0:1], vcc, s[16:17]
	v_cmp_ge_f32_e32 vcc, v3, v76
	v_cmp_lt_f32_e64 s[16:17], v3, v76
	v_cndmask_b32_e64 v81, 0, 1, s[0:1]
	v_addc_co_u32_e32 v78, vcc, v78, v80, vcc
	v_cmp_ge_f32_e32 vcc, v3, v77
	s_and_b64 vcc, vcc, s[16:17]
	v_cmp_lt_f32_e64 s[16:17], v4, v76
	v_addc_co_u32_e32 v79, vcc, v79, v81, vcc
	v_cmp_ge_f32_e32 vcc, v4, v76
	s_nop 1
	v_cndmask_b32_e64 v80, 0, 1, vcc
	v_cmp_ge_f32_e32 vcc, v4, v77
	s_and_b64 s[0:1], vcc, s[16:17]
	v_cmp_ge_f32_e32 vcc, v5, v76
	v_cmp_lt_f32_e64 s[16:17], v5, v76
	v_cndmask_b32_e64 v81, 0, 1, s[0:1]
	v_addc_co_u32_e32 v78, vcc, v78, v80, vcc
	v_cmp_ge_f32_e32 vcc, v5, v77
	s_and_b64 vcc, vcc, s[16:17]
	v_mov_b32_e32 v80, 0
	v_addc_co_u32_e32 v79, vcc, v79, v81, vcc
	v_lshl_or_b32 v78, v79, 8, v78
	v_mov_b32_e32 v79, 0
	v_mov_b32_e32 v81, 0
	v_mov_b32_dpp v80, v78 quad_perm:[1,1,1,1] row_mask:0xf bank_mask:0xf
	v_mov_b32_dpp v79, v78 quad_perm:[0,0,0,0] row_mask:0xf bank_mask:0xf
	v_mov_b32_dpp v81, v78 quad_perm:[2,2,2,2] row_mask:0xf bank_mask:0xf
	v_mov_b32_dpp v82, v78 quad_perm:[3,3,3,3] row_mask:0xf bank_mask:0xf
	v_add_u32_e32 v78, v80, v79
	v_add3_u32 v82, v78, v81, v82
	v_cndmask_b32_e64 v78, v79, 0, s[4:5]
	v_cndmask_b32_e64 v79, 0, v80, s[6:7]
	v_cndmask_b32_e64 v80, 0, v81, s[8:9]
	v_add3_u32 v79, v79, v78, v80
	v_and_b32_e32 v78, 0xff, v79
	v_ashrrev_i32_e32 v79, 8, v79
	v_add_u32_sdwa v79, v82, v79 dst_sel:DWORD dst_unused:UNUSED_PAD src0_sel:BYTE_0 src1_sel:DWORD
	s_nop 0
	v_cmp_ge_f32_e32 vcc, v30, v76
	v_cmp_ge_f32_e64 s[16:17], v30, v77
	s_or_b64 s[0:1], vcc, s[16:17]
	v_cndmask_b32_e32 v80, v79, v78, vcc
	v_cmp_gt_i32_e64 s[18:19], 16, v80
	s_and_b64 s[18:19], s[0:1], s[18:19]
	s_and_saveexec_b64 s[0:1], s[18:19]
	v_add_u32_e32 v80, v80, v39
	v_lshl_add_u32 v80, v80, 2, s22
	ds_write2st64_b32 v80, v30, v38 offset1:4
	s_or_b64 exec, exec, s[0:1]
	s_xor_b64 s[0:1], vcc, -1
	s_and_b64 s[0:1], s[0:1], s[16:17]
	v_cndmask_b32_e64 v80, 0, 1, s[0:1]
	v_cndmask_b32_e64 v30, 0, 1, vcc
	v_add_u32_e32 v30, v78, v30
	v_add_u32_e32 v78, v79, v80
	v_cmp_ge_f32_e32 vcc, v31, v76
	v_cmp_ge_f32_e64 s[16:17], v31, v77
	s_or_b64 s[0:1], vcc, s[16:17]
	v_cndmask_b32_e32 v79, v78, v30, vcc
	v_cmp_gt_i32_e64 s[18:19], 16, v79
	s_and_b64 s[18:19], s[0:1], s[18:19]
	s_and_saveexec_b64 s[0:1], s[18:19]
	v_add_u32_e32 v79, v79, v39
	v_lshl_add_u32 v79, v79, 2, s22
	ds_write2st64_b32 v79, v31, v40 offset1:4
	s_or_b64 exec, exec, s[0:1]
	s_xor_b64 s[0:1], vcc, -1
	s_and_b64 s[0:1], s[0:1], s[16:17]
	v_cndmask_b32_e64 v31, 0, 1, s[0:1]
	v_cndmask_b32_e64 v79, 0, 1, vcc
	v_add_u32_e32 v30, v30, v79
	v_add_u32_e32 v31, v78, v31
	v_cmp_ge_f32_e32 vcc, v32, v76
	v_cmp_ge_f32_e64 s[16:17], v32, v77
	s_or_b64 s[0:1], vcc, s[16:17]
	v_cndmask_b32_e32 v78, v31, v30, vcc
	v_cmp_gt_i32_e64 s[18:19], 16, v78
	s_and_b64 s[18:19], s[0:1], s[18:19]
	s_and_saveexec_b64 s[0:1], s[18:19]
	v_add_u32_e32 v78, v78, v39
	v_lshl_add_u32 v78, v78, 2, s22
	ds_write2st64_b32 v78, v32, v41 offset1:4
	s_or_b64 exec, exec, s[0:1]
	s_xor_b64 s[0:1], vcc, -1
	s_and_b64 s[0:1], s[0:1], s[16:17]
	v_cndmask_b32_e64 v32, 0, 1, s[0:1]
	v_cndmask_b32_e64 v78, 0, 1, vcc
	v_add_u32_e32 v30, v30, v78
	v_add_u32_e32 v31, v31, v32
	v_cmp_ge_f32_e32 vcc, v33, v76
	v_cmp_ge_f32_e64 s[16:17], v33, v77
	s_or_b64 s[0:1], vcc, s[16:17]
	v_cndmask_b32_e32 v32, v31, v30, vcc
	v_cmp_gt_i32_e64 s[18:19], 16, v32
	s_and_b64 s[18:19], s[0:1], s[18:19]
	s_and_saveexec_b64 s[0:1], s[18:19]
	v_add_u32_e32 v32, v32, v39
	v_lshl_add_u32 v32, v32, 2, s22
	ds_write2st64_b32 v32, v33, v42 offset1:4
	s_or_b64 exec, exec, s[0:1]
	s_xor_b64 s[0:1], vcc, -1
	s_and_b64 s[0:1], s[0:1], s[16:17]
	v_cndmask_b32_e64 v32, 0, 1, s[0:1]
	v_cndmask_b32_e64 v33, 0, 1, vcc
	v_add_u32_e32 v30, v30, v33
	v_add_u32_e32 v31, v31, v32
	v_cmp_ge_f32_e32 vcc, v26, v76
	v_cmp_ge_f32_e64 s[16:17], v26, v77
	s_or_b64 s[0:1], vcc, s[16:17]
	v_cndmask_b32_e32 v32, v31, v30, vcc
	v_cmp_gt_i32_e64 s[18:19], 16, v32
	s_and_b64 s[18:19], s[0:1], s[18:19]
	s_and_saveexec_b64 s[0:1], s[18:19]
	v_add_u32_e32 v32, v32, v39
	v_lshl_add_u32 v32, v32, 2, s22
	ds_write2st64_b32 v32, v26, v43 offset1:4
	s_or_b64 exec, exec, s[0:1]
	s_xor_b64 s[0:1], vcc, -1
	s_and_b64 s[0:1], s[0:1], s[16:17]
	v_cndmask_b32_e64 v32, 0, 1, s[0:1]
	v_cndmask_b32_e64 v26, 0, 1, vcc
	v_add_u32_e32 v26, v30, v26
	v_add_u32_e32 v30, v31, v32
	v_cmp_ge_f32_e32 vcc, v27, v76
	v_cmp_ge_f32_e64 s[16:17], v27, v77
	s_or_b64 s[0:1], vcc, s[16:17]
	v_cndmask_b32_e32 v31, v30, v26, vcc
	v_cmp_gt_i32_e64 s[18:19], 16, v31
	s_and_b64 s[18:19], s[0:1], s[18:19]
	s_and_saveexec_b64 s[0:1], s[18:19]
	v_add_u32_e32 v31, v31, v39
	v_lshl_add_u32 v31, v31, 2, s22
	ds_write2st64_b32 v31, v27, v44 offset1:4
	s_or_b64 exec, exec, s[0:1]
	s_xor_b64 s[0:1], vcc, -1
	s_and_b64 s[0:1], s[0:1], s[16:17]
	v_cndmask_b32_e64 v27, 0, 1, s[0:1]
	v_cndmask_b32_e64 v31, 0, 1, vcc
	v_add_u32_e32 v26, v26, v31
	v_add_u32_e32 v27, v30, v27
	v_cmp_ge_f32_e32 vcc, v28, v76
	v_cmp_ge_f32_e64 s[16:17], v28, v77
	s_or_b64 s[0:1], vcc, s[16:17]
	v_cndmask_b32_e32 v30, v27, v26, vcc
; __device__ __forceinline__ void peer_select(const float* S, const int row, const int lane, LAS float* sv, LAS int* si, LAS float* fvL, LAS int* eL, int& e0o, int& e1o, float& g0o, float& g1o) {
;     ...
; #pragma unroll
;             for (int j = 0; j < 32; ++j) {
;                 const bool isA = x[j] >= hi, isB = !isA && x[j] >= lo;
;                 const int slot = isA ? pA : pB;
;                 if ((isA || isB) && slot < 16) { sv[grp * 16 + slot] = x[j]; si[grp * 16 + slot] = qtr * 32 + j; }
;                 pA += isA ? 1 : 0; pB += isB ? 1 : 0;
;             }
	v_cmp_gt_i32_e64 s[18:19], 16, v30
	s_and_b64 s[18:19], s[0:1], s[18:19]
	s_and_saveexec_b64 s[0:1], s[18:19]
	v_add_u32_e32 v30, v30, v39
	v_lshl_add_u32 v30, v30, 2, s22
	ds_write2st64_b32 v30, v28, v45 offset1:4
	s_or_b64 exec, exec, s[0:1]
	s_xor_b64 s[0:1], vcc, -1
	s_and_b64 s[0:1], s[0:1], s[16:17]
	v_cndmask_b32_e64 v28, 0, 1, s[0:1]
	v_cndmask_b32_e64 v30, 0, 1, vcc
	v_add_u32_e32 v26, v26, v30
	v_add_u32_e32 v27, v27, v28
	v_cmp_ge_f32_e32 vcc, v29, v76
	v_cmp_ge_f32_e64 s[16:17], v29, v77
	s_or_b64 s[0:1], vcc, s[16:17]
	v_cndmask_b32_e32 v28, v27, v26, vcc
	v_cmp_gt_i32_e64 s[18:19], 16, v28
	s_and_b64 s[18:19], s[0:1], s[18:19]
	s_and_saveexec_b64 s[0:1], s[18:19]
	v_add_u32_e32 v28, v28, v39
	v_lshl_add_u32 v28, v28, 2, s22
	ds_write2st64_b32 v28, v29, v46 offset1:4
	s_or_b64 exec, exec, s[0:1]
	s_xor_b64 s[0:1], vcc, -1
	s_and_b64 s[0:1], s[0:1], s[16:17]
	v_cndmask_b32_e64 v28, 0, 1, s[0:1]
	v_cndmask_b32_e64 v29, 0, 1, vcc
	v_add_u32_e32 v26, v26, v29
	v_add_u32_e32 v27, v27, v28
	v_cmp_ge_f32_e32 vcc, v22, v76
	v_cmp_ge_f32_e64 s[16:17], v22, v77
	s_or_b64 s[0:1], vcc, s[16:17]
	v_cndmask_b32_e32 v28, v27, v26, vcc
	v_cmp_gt_i32_e64 s[18:19], 16, v28
	s_and_b64 s[18:19], s[0:1], s[18:19]
	s_and_saveexec_b64 s[0:1], s[18:19]
	v_add_u32_e32 v28, v28, v39
	v_lshl_add_u32 v28, v28, 2, s22
	ds_write2st64_b32 v28, v22, v47 offset1:4
	s_or_b64 exec, exec, s[0:1]
	s_xor_b64 s[0:1], vcc, -1
	s_and_b64 s[0:1], s[0:1], s[16:17]
	v_cndmask_b32_e64 v28, 0, 1, s[0:1]
	v_cndmask_b32_e64 v22, 0, 1, vcc
	v_add_u32_e32 v22, v26, v22
	v_add_u32_e32 v26, v27, v28
	v_cmp_ge_f32_e32 vcc, v23, v76
	v_cmp_ge_f32_e64 s[16:17], v23, v77
	s_or_b64 s[0:1], vcc, s[16:17]
	v_cndmask_b32_e32 v27, v26, v22, vcc
	v_cmp_gt_i32_e64 s[18:19], 16, v27
	s_and_b64 s[18:19], s[0:1], s[18:19]
	s_and_saveexec_b64 s[0:1], s[18:19]
	v_add_u32_e32 v27, v27, v39
	v_lshl_add_u32 v27, v27, 2, s22
	ds_write2st64_b32 v27, v23, v48 offset1:4
	s_or_b64 exec, exec, s[0:1]
	s_xor_b64 s[0:1], vcc, -1
	s_and_b64 s[0:1], s[0:1], s[16:17]
	v_cndmask_b32_e64 v23, 0, 1, s[0:1]
	v_cndmask_b32_e64 v27, 0, 1, vcc
	v_add_u32_e32 v22, v22, v27
	v_add_u32_e32 v23, v26, v23
	v_cmp_ge_f32_e32 vcc, v24, v76
	v_cmp_ge_f32_e64 s[16:17], v24, v77
	s_or_b64 s[0:1], vcc, s[16:17]
	v_cndmask_b32_e32 v26, v23, v22, vcc
	v_cmp_gt_i32_e64 s[18:19], 16, v26
	s_and_b64 s[18:19], s[0:1], s[18:19]
	s_and_saveexec_b64 s[0:1], s[18:19]
	v_add_u32_e32 v26, v26, v39
	v_lshl_add_u32 v26, v26, 2, s22
	ds_write2st64_b32 v26, v24, v49 offset1:4
	s_or_b64 exec, exec, s[0:1]
	s_xor_b64 s[0:1], vcc, -1
	s_and_b64 s[0:1], s[0:1], s[16:17]
	v_cndmask_b32_e64 v24, 0, 1, s[0:1]
	v_cndmask_b32_e64 v26, 0, 1, vcc
	v_add_u32_e32 v22, v22, v26
	v_add_u32_e32 v23, v23, v24
	v_cmp_ge_f32_e32 vcc, v25, v76
	v_cmp_ge_f32_e64 s[16:17], v25, v77
	s_or_b64 s[0:1], vcc, s[16:17]
	v_cndmask_b32_e32 v24, v23, v22, vcc
	v_cmp_gt_i32_e64 s[18:19], 16, v24
	s_and_b64 s[18:19], s[0:1], s[18:19]
	s_and_saveexec_b64 s[0:1], s[18:19]
	v_add_u32_e32 v24, v24, v39
	v_lshl_add_u32 v24, v24, 2, s22
	ds_write2st64_b32 v24, v25, v50 offset1:4
	s_or_b64 exec, exec, s[0:1]
	s_xor_b64 s[0:1], vcc, -1
	s_and_b64 s[0:1], s[0:1], s[16:17]
	v_cndmask_b32_e64 v24, 0, 1, s[0:1]
	v_cndmask_b32_e64 v25, 0, 1, vcc
	v_add_u32_e32 v22, v22, v25
	v_add_u32_e32 v23, v23, v24
	v_cmp_ge_f32_e32 vcc, v18, v76
	v_cmp_ge_f32_e64 s[16:17], v18, v77
	s_or_b64 s[0:1], vcc, s[16:17]
	v_cndmask_b32_e32 v24, v23, v22, vcc
	v_cmp_gt_i32_e64 s[18:19], 16, v24
	s_and_b64 s[18:19], s[0:1], s[18:19]
	s_and_saveexec_b64 s[0:1], s[18:19]
	v_add_u32_e32 v24, v24, v39
	v_lshl_add_u32 v24, v24, 2, s22
	ds_write2st64_b32 v24, v18, v51 offset1:4
	s_or_b64 exec, exec, s[0:1]
	s_xor_b64 s[0:1], vcc, -1
	s_and_b64 s[0:1], s[0:1], s[16:17]
	v_cndmask_b32_e64 v24, 0, 1, s[0:1]
	v_cndmask_b32_e64 v18, 0, 1, vcc
	v_add_u32_e32 v18, v22, v18
	v_add_u32_e32 v22, v23, v24
	v_cmp_ge_f32_e32 vcc, v19, v76
	v_cmp_ge_f32_e64 s[16:17], v19, v77
	s_or_b64 s[0:1], vcc, s[16:17]
	v_cndmask_b32_e32 v23, v22, v18, vcc
	v_cmp_gt_i32_e64 s[18:19], 16, v23
	s_and_b64 s[18:19], s[0:1], s[18:19]
	s_and_saveexec_b64 s[0:1], s[18:19]
	v_add_u32_e32 v23, v23, v39
	v_lshl_add_u32 v23, v23, 2, s22
	ds_write2st64_b32 v23, v19, v52 offset1:4
	s_or_b64 exec, exec, s[0:1]
	s_xor_b64 s[0:1], vcc, -1
	s_and_b64 s[0:1], s[0:1], s[16:17]
	v_cndmask_b32_e64 v19, 0, 1, s[0:1]
	v_cndmask_b32_e64 v23, 0, 1, vcc
	v_add_u32_e32 v18, v18, v23
	v_add_u32_e32 v19, v22, v19
	v_cmp_ge_f32_e32 vcc, v20, v76
	v_cmp_ge_f32_e64 s[16:17], v20, v77
	s_or_b64 s[0:1], vcc, s[16:17]
	v_cndmask_b32_e32 v22, v19, v18, vcc
	v_cmp_gt_i32_e64 s[18:19], 16, v22
	s_and_b64 s[18:19], s[0:1], s[18:19]
	s_and_saveexec_b64 s[0:1], s[18:19]
	v_add_u32_e32 v22, v22, v39
	v_lshl_add_u32 v22, v22, 2, s22
	ds_write2st64_b32 v22, v20, v53 offset1:4
	s_or_b64 exec, exec, s[0:1]
	s_xor_b64 s[0:1], vcc, -1
	s_and_b64 s[0:1], s[0:1], s[16:17]
	v_cndmask_b32_e64 v20, 0, 1, s[0:1]
	v_cndmask_b32_e64 v22, 0, 1, vcc
	v_add_u32_e32 v18, v18, v22
	v_add_u32_e32 v19, v19, v20
	v_cmp_ge_f32_e32 vcc, v21, v76
	v_cmp_ge_f32_e64 s[16:17], v21, v77
	s_or_b64 s[0:1], vcc, s[16:17]
	v_cndmask_b32_e32 v20, v19, v18, vcc
	v_cmp_gt_i32_e64 s[18:19], 16, v20
	s_and_b64 s[18:19], s[0:1], s[18:19]
	s_and_saveexec_b64 s[0:1], s[18:19]
	v_add_u32_e32 v20, v20, v39
	v_lshl_add_u32 v20, v20, 2, s22
	ds_write2st64_b32 v20, v21, v54 offset1:4
	s_or_b64 exec, exec, s[0:1]
	s_xor_b64 s[0:1], vcc, -1
	s_and_b64 s[0:1], s[0:1], s[16:17]
	v_cndmask_b32_e64 v20, 0, 1, s[0:1]
	v_cndmask_b32_e64 v21, 0, 1, vcc
	v_add_u32_e32 v18, v18, v21
	v_add_u32_e32 v19, v19, v20
	v_cmp_ge_f32_e32 vcc, v14, v76
; __device__ __forceinline__ void peer_select(const float* S, const int row, const int lane, LAS float* sv, LAS int* si, LAS float* fvL, LAS int* eL, int& e0o, int& e1o, float& g0o, float& g1o) {
;     ...
; #pragma unroll
;             for (int j = 0; j < 32; ++j) {
;                 const bool isA = x[j] >= hi, isB = !isA && x[j] >= lo;
;                 const int slot = isA ? pA : pB;
;                 if ((isA || isB) && slot < 16) { sv[grp * 16 + slot] = x[j]; si[grp * 16 + slot] = qtr * 32 + j; }
;                 pA += isA ? 1 : 0; pB += isB ? 1 : 0;
;             }
	v_cmp_ge_f32_e64 s[16:17], v14, v77
	s_or_b64 s[0:1], vcc, s[16:17]
	v_cndmask_b32_e32 v20, v19, v18, vcc
	v_cmp_gt_i32_e64 s[18:19], 16, v20
	s_and_b64 s[18:19], s[0:1], s[18:19]
	s_and_saveexec_b64 s[0:1], s[18:19]
	v_add_u32_e32 v20, v20, v39
	v_lshl_add_u32 v20, v20, 2, s22
	ds_write2st64_b32 v20, v14, v55 offset1:4
	s_or_b64 exec, exec, s[0:1]
	s_xor_b64 s[0:1], vcc, -1
	s_and_b64 s[0:1], s[0:1], s[16:17]
	v_cndmask_b32_e64 v20, 0, 1, s[0:1]
	v_cndmask_b32_e64 v14, 0, 1, vcc
	v_add_u32_e32 v14, v18, v14
	v_add_u32_e32 v18, v19, v20
	v_cmp_ge_f32_e32 vcc, v15, v76
	v_cmp_ge_f32_e64 s[16:17], v15, v77
	s_or_b64 s[0:1], vcc, s[16:17]
	v_cndmask_b32_e32 v19, v18, v14, vcc
	v_cmp_gt_i32_e64 s[18:19], 16, v19
	s_and_b64 s[18:19], s[0:1], s[18:19]
	s_and_saveexec_b64 s[0:1], s[18:19]
	v_add_u32_e32 v19, v19, v39
	v_lshl_add_u32 v19, v19, 2, s22
	ds_write2st64_b32 v19, v15, v56 offset1:4
	s_or_b64 exec, exec, s[0:1]
	s_xor_b64 s[0:1], vcc, -1
	s_and_b64 s[0:1], s[0:1], s[16:17]
	v_cndmask_b32_e64 v15, 0, 1, s[0:1]
	v_cndmask_b32_e64 v19, 0, 1, vcc
	v_add_u32_e32 v14, v14, v19
	v_add_u32_e32 v15, v18, v15
	v_cmp_ge_f32_e32 vcc, v16, v76
	v_cmp_ge_f32_e64 s[16:17], v16, v77
	s_or_b64 s[0:1], vcc, s[16:17]
	v_cndmask_b32_e32 v18, v15, v14, vcc
	v_cmp_gt_i32_e64 s[18:19], 16, v18
	s_and_b64 s[18:19], s[0:1], s[18:19]
	s_and_saveexec_b64 s[0:1], s[18:19]
	v_add_u32_e32 v18, v18, v39
	v_lshl_add_u32 v18, v18, 2, s22
	ds_write2st64_b32 v18, v16, v57 offset1:4
	s_or_b64 exec, exec, s[0:1]
	s_xor_b64 s[0:1], vcc, -1
	s_and_b64 s[0:1], s[0:1], s[16:17]
	v_cndmask_b32_e64 v16, 0, 1, s[0:1]
	v_cndmask_b32_e64 v18, 0, 1, vcc
	v_add_u32_e32 v14, v14, v18
	v_add_u32_e32 v15, v15, v16
	v_cmp_ge_f32_e32 vcc, v17, v76
	v_cmp_ge_f32_e64 s[16:17], v17, v77
	s_or_b64 s[0:1], vcc, s[16:17]
	v_cndmask_b32_e32 v16, v15, v14, vcc
	v_cmp_gt_i32_e64 s[18:19], 16, v16
	s_and_b64 s[18:19], s[0:1], s[18:19]
	s_and_saveexec_b64 s[0:1], s[18:19]
	v_add_u32_e32 v16, v16, v39
	v_lshl_add_u32 v16, v16, 2, s22
	ds_write2st64_b32 v16, v17, v58 offset1:4
	s_or_b64 exec, exec, s[0:1]
	s_xor_b64 s[0:1], vcc, -1
	s_and_b64 s[0:1], s[0:1], s[16:17]
	v_cndmask_b32_e64 v16, 0, 1, s[0:1]
	v_cndmask_b32_e64 v17, 0, 1, vcc
	v_add_u32_e32 v14, v14, v17
	v_add_u32_e32 v15, v15, v16
	v_cmp_ge_f32_e32 vcc, v10, v76
	v_cmp_ge_f32_e64 s[16:17], v10, v77
	s_or_b64 s[0:1], vcc, s[16:17]
	v_cndmask_b32_e32 v16, v15, v14, vcc
	v_cmp_gt_i32_e64 s[18:19], 16, v16
	s_and_b64 s[18:19], s[0:1], s[18:19]
	s_and_saveexec_b64 s[0:1], s[18:19]
	v_add_u32_e32 v16, v16, v39
	v_lshl_add_u32 v16, v16, 2, s22
	ds_write2st64_b32 v16, v10, v59 offset1:4
	s_or_b64 exec, exec, s[0:1]
	s_xor_b64 s[0:1], vcc, -1
	s_and_b64 s[0:1], s[0:1], s[16:17]
	v_cndmask_b32_e64 v16, 0, 1, s[0:1]
	v_cndmask_b32_e64 v10, 0, 1, vcc
	v_add_u32_e32 v10, v14, v10
	v_add_u32_e32 v14, v15, v16
	v_cmp_ge_f32_e32 vcc, v11, v76
	v_cmp_ge_f32_e64 s[16:17], v11, v77
	s_or_b64 s[0:1], vcc, s[16:17]
	v_cndmask_b32_e32 v15, v14, v10, vcc
	v_cmp_gt_i32_e64 s[18:19], 16, v15
	s_and_b64 s[18:19], s[0:1], s[18:19]
	s_and_saveexec_b64 s[0:1], s[18:19]
	v_add_u32_e32 v15, v15, v39
	v_lshl_add_u32 v15, v15, 2, s22
	ds_write2st64_b32 v15, v11, v60 offset1:4
	s_or_b64 exec, exec, s[0:1]
	s_xor_b64 s[0:1], vcc, -1
	s_and_b64 s[0:1], s[0:1], s[16:17]
	v_cndmask_b32_e64 v11, 0, 1, s[0:1]
	v_cndmask_b32_e64 v15, 0, 1, vcc
	v_add_u32_e32 v10, v10, v15
	v_add_u32_e32 v11, v14, v11
	v_cmp_ge_f32_e32 vcc, v12, v76
	v_cmp_ge_f32_e64 s[16:17], v12, v77
	s_or_b64 s[0:1], vcc, s[16:17]
	v_cndmask_b32_e32 v14, v11, v10, vcc
	v_cmp_gt_i32_e64 s[18:19], 16, v14
	s_and_b64 s[18:19], s[0:1], s[18:19]
	s_and_saveexec_b64 s[0:1], s[18:19]
	v_add_u32_e32 v14, v14, v39
	v_lshl_add_u32 v14, v14, 2, s22
	ds_write2st64_b32 v14, v12, v61 offset1:4
	s_or_b64 exec, exec, s[0:1]
	s_xor_b64 s[0:1], vcc, -1
	s_and_b64 s[0:1], s[0:1], s[16:17]
	v_cndmask_b32_e64 v12, 0, 1, s[0:1]
	v_cndmask_b32_e64 v14, 0, 1, vcc
	v_add_u32_e32 v10, v10, v14
	v_add_u32_e32 v11, v11, v12
	v_cmp_ge_f32_e32 vcc, v13, v76
	v_cmp_ge_f32_e64 s[16:17], v13, v77
	s_or_b64 s[0:1], vcc, s[16:17]
	v_cndmask_b32_e32 v12, v11, v10, vcc
	v_cmp_gt_i32_e64 s[18:19], 16, v12
	s_and_b64 s[18:19], s[0:1], s[18:19]
	s_and_saveexec_b64 s[0:1], s[18:19]
	v_add_u32_e32 v12, v12, v39
	v_lshl_add_u32 v12, v12, 2, s22
	ds_write2st64_b32 v12, v13, v62 offset1:4
	s_or_b64 exec, exec, s[0:1]
	s_xor_b64 s[0:1], vcc, -1
	s_and_b64 s[0:1], s[0:1], s[16:17]
	v_cndmask_b32_e64 v12, 0, 1, s[0:1]
	v_cndmask_b32_e64 v13, 0, 1, vcc
	v_add_u32_e32 v10, v10, v13
	v_add_u32_e32 v11, v11, v12
	v_cmp_ge_f32_e32 vcc, v6, v76
	v_cmp_ge_f32_e64 s[16:17], v6, v77
	s_or_b64 s[0:1], vcc, s[16:17]
	v_cndmask_b32_e32 v12, v11, v10, vcc
	v_cmp_gt_i32_e64 s[18:19], 16, v12
	s_and_b64 s[18:19], s[0:1], s[18:19]
	s_and_saveexec_b64 s[0:1], s[18:19]
	v_add_u32_e32 v12, v12, v39
	v_lshl_add_u32 v12, v12, 2, s22
	ds_write2st64_b32 v12, v6, v63 offset1:4
	s_or_b64 exec, exec, s[0:1]
	s_xor_b64 s[0:1], vcc, -1
	s_and_b64 s[0:1], s[0:1], s[16:17]
	v_cndmask_b32_e64 v12, 0, 1, s[0:1]
	v_cndmask_b32_e64 v6, 0, 1, vcc
	v_add_u32_e32 v6, v10, v6
	v_add_u32_e32 v10, v11, v12
	v_cmp_ge_f32_e32 vcc, v7, v76
	v_cmp_ge_f32_e64 s[16:17], v7, v77
	s_or_b64 s[0:1], vcc, s[16:17]
	v_cndmask_b32_e32 v11, v10, v6, vcc
	v_cmp_gt_i32_e64 s[18:19], 16, v11
	s_and_b64 s[18:19], s[0:1], s[18:19]
	s_and_saveexec_b64 s[0:1], s[18:19]
	v_add_u32_e32 v11, v11, v39
	v_lshl_add_u32 v11, v11, 2, s22
	ds_write2st64_b32 v11, v7, v64 offset1:4
	s_or_b64 exec, exec, s[0:1]
	s_xor_b64 s[0:1], vcc, -1
	s_and_b64 s[0:1], s[0:1], s[16:17]
	v_cndmask_b32_e64 v7, 0, 1, s[0:1]
; #define LAS __attribute__((address_space(3)))
; __device__ __forceinline__ void peer_select(const float* S, const int row, const int lane, LAS float* sv, LAS int* si, LAS float* fvL, LAS int* eL, int& e0o, int& e1o, float& g0o, float& g1o) {
;     ...
; #pragma unroll
;             for (int j = 0; j < 32; ++j) {
;                 const bool isA = x[j] >= hi, isB = !isA && x[j] >= lo;
;                 const int slot = isA ? pA : pB;
;                 if ((isA || isB) && slot < 16) { sv[grp * 16 + slot] = x[j]; si[grp * 16 + slot] = qtr * 32 + j; }
;                 pA += isA ? 1 : 0; pB += isB ? 1 : 0;
;             }
;         }
;         __builtin_amdgcn_wave_barrier();
;         {
;             const int hd = lane >> 3, sub = lane & 7;
;             const float s1a = sv[(2 * hd) * 16 + 2 * sub], s1b = sv[(2 * hd) * 16 + 2 * sub + 1];
;             const int i1a = si[(2 * hd) * 16 + 2 * sub], i1b = si[(2 * hd) * 16 + 2 * sub + 1];
;             float c[32]; int i2[16];
; #pragma unroll
;             for (int k = 0; k < 4; ++k) {
;                 const f32x4 v = *(const LAS f32x4*)(sv + (2 * hd + 1) * 16 + 4 * k);
;                 const u32x4 iv = *(const LAS u32x4*)(si + (2 * hd + 1) * 16 + 4 * k);
; #pragma unroll
;                 for (int e = 0; e < 4; ++e) { c[4 * k + e] = s1a + v[e]; c[16 + 4 * k + e] = s1b + v[e]; }
;                 i2[4 * k] = (int)iv.x; i2[4 * k + 1] = (int)iv.y; i2[4 * k + 2] = (int)iv.z; i2[4 * k + 3] = (int)iv.w;
;             }
;             float lo, hi;
;             bisect16<8>(c, lo, hi);
	v_cndmask_b32_e64 v11, 0, 1, vcc
	v_add_u32_e32 v6, v6, v11
	v_add_u32_e32 v7, v10, v7
	v_cmp_ge_f32_e32 vcc, v8, v76
	v_cmp_ge_f32_e64 s[16:17], v8, v77
	s_or_b64 s[0:1], vcc, s[16:17]
	v_cndmask_b32_e32 v10, v7, v6, vcc
	v_cmp_gt_i32_e64 s[18:19], 16, v10
	s_and_b64 s[18:19], s[0:1], s[18:19]
	s_and_saveexec_b64 s[0:1], s[18:19]
	v_add_u32_e32 v10, v10, v39
	v_lshl_add_u32 v10, v10, 2, s22
	ds_write2st64_b32 v10, v8, v65 offset1:4
	s_or_b64 exec, exec, s[0:1]
	s_xor_b64 s[0:1], vcc, -1
	s_and_b64 s[0:1], s[0:1], s[16:17]
	v_cndmask_b32_e64 v8, 0, 1, s[0:1]
	v_cndmask_b32_e64 v10, 0, 1, vcc
	v_add_u32_e32 v6, v6, v10
	v_add_u32_e32 v7, v7, v8
	v_cmp_ge_f32_e32 vcc, v9, v76
	v_cmp_ge_f32_e64 s[16:17], v9, v77
	s_or_b64 s[0:1], vcc, s[16:17]
	v_cndmask_b32_e32 v8, v7, v6, vcc
	v_cmp_gt_i32_e64 s[18:19], 16, v8
	s_and_b64 s[18:19], s[0:1], s[18:19]
	s_and_saveexec_b64 s[0:1], s[18:19]
	v_add_u32_e32 v8, v8, v39
	v_lshl_add_u32 v8, v8, 2, s22
	ds_write2st64_b32 v8, v9, v66 offset1:4
	s_or_b64 exec, exec, s[0:1]
	s_xor_b64 s[0:1], vcc, -1
	s_and_b64 s[0:1], s[0:1], s[16:17]
	v_cndmask_b32_e64 v8, 0, 1, s[0:1]
	v_cndmask_b32_e64 v9, 0, 1, vcc
	v_add_u32_e32 v6, v6, v9
	v_add_u32_e32 v7, v7, v8
	v_cmp_ge_f32_e32 vcc, v2, v76
	v_cmp_ge_f32_e64 s[16:17], v2, v77
	s_or_b64 s[0:1], vcc, s[16:17]
	v_cndmask_b32_e32 v8, v7, v6, vcc
	v_cmp_gt_i32_e64 s[18:19], 16, v8
	s_and_b64 s[18:19], s[0:1], s[18:19]
	s_and_saveexec_b64 s[0:1], s[18:19]
	v_add_u32_e32 v8, v8, v39
	v_lshl_add_u32 v8, v8, 2, s22
	ds_write2st64_b32 v8, v2, v67 offset1:4
	s_or_b64 exec, exec, s[0:1]
	s_xor_b64 s[0:1], vcc, -1
	s_and_b64 s[0:1], s[0:1], s[16:17]
	v_cndmask_b32_e64 v8, 0, 1, s[0:1]
	v_cndmask_b32_e64 v2, 0, 1, vcc
	v_add_u32_e32 v2, v6, v2
	v_add_u32_e32 v6, v7, v8
	v_cmp_ge_f32_e32 vcc, v3, v76
	v_cmp_ge_f32_e64 s[16:17], v3, v77
	s_or_b64 s[0:1], vcc, s[16:17]
	v_cndmask_b32_e32 v7, v6, v2, vcc
	v_cmp_gt_i32_e64 s[18:19], 16, v7
	s_and_b64 s[18:19], s[0:1], s[18:19]
	s_and_saveexec_b64 s[0:1], s[18:19]
	v_add_u32_e32 v7, v7, v39
	v_lshl_add_u32 v7, v7, 2, s22
	ds_write2st64_b32 v7, v3, v68 offset1:4
	s_or_b64 exec, exec, s[0:1]
	s_xor_b64 s[0:1], vcc, -1
	s_and_b64 s[0:1], s[0:1], s[16:17]
	v_cndmask_b32_e64 v3, 0, 1, s[0:1]
	v_cndmask_b32_e64 v7, 0, 1, vcc
	v_add_u32_e32 v2, v2, v7
	v_add_u32_e32 v3, v6, v3
	v_cmp_ge_f32_e32 vcc, v4, v76
	v_cmp_ge_f32_e64 s[16:17], v4, v77
	s_or_b64 s[0:1], vcc, s[16:17]
	v_cndmask_b32_e32 v6, v3, v2, vcc
	v_cmp_gt_i32_e64 s[18:19], 16, v6
	s_and_b64 s[18:19], s[0:1], s[18:19]
	s_and_saveexec_b64 s[0:1], s[18:19]
	v_add_u32_e32 v6, v6, v39
	v_lshl_add_u32 v6, v6, 2, s22
	ds_write2st64_b32 v6, v4, v69 offset1:4
	s_or_b64 exec, exec, s[0:1]
	s_xor_b64 s[0:1], vcc, -1
	s_and_b64 s[0:1], s[0:1], s[16:17]
	v_cndmask_b32_e64 v4, 0, 1, s[0:1]
	v_cndmask_b32_e64 v6, 0, 1, vcc
	v_add_u32_e32 v2, v2, v6
	v_add_u32_e32 v3, v3, v4
	v_cmp_ge_f32_e64 s[16:17], v5, v76
	v_cmp_ge_f32_e32 vcc, v5, v77
	s_or_b64 s[0:1], s[16:17], vcc
	v_cndmask_b32_e64 v2, v3, v2, s[16:17]
	v_cmp_gt_i32_e32 vcc, 16, v2
	s_and_b64 s[16:17], s[0:1], vcc
	s_and_saveexec_b64 s[0:1], s[16:17]
	v_add_u32_e32 v2, v2, v39
	v_lshl_add_u32 v2, v2, 2, s22
	ds_write2st64_b32 v2, v5, v70 offset1:4
	s_or_b64 exec, exec, s[0:1]
	ds_read2st64_b64 v[2:5], v71 offset1:2
	ds_read_b128 v[22:25], v72 offset:64
	ds_read_b128 v[26:29], v72 offset:80
	ds_read_b128 v[98:101], v72 offset:96
	ds_read_b128 v[102:105], v72 offset:112
	ds_read_b128 v[18:21], v72 offset:1088
	ds_read_b128 v[14:17], v72 offset:1104
	ds_read_b128 v[10:13], v72 offset:1120
	ds_read_b128 v[6:9], v72 offset:1136
	s_waitcnt lgkmcnt(7)
	v_add_f32_e32 v97, v2, v22
	v_add_f32_e32 v96, v2, v23
	v_add_f32_e32 v80, v3, v23
	s_waitcnt lgkmcnt(4)
	v_pk_mov_b32 v[22:23], v[104:105], v[22:23] op_sel:[1,0]
	v_add_f32_e32 v95, v2, v24
	v_add_f32_e32 v79, v3, v24
	v_add_f32_e32 v94, v2, v25
	v_add_f32_e32 v78, v3, v25
	v_add_f32_e32 v93, v2, v26
	v_add_f32_e32 v77, v3, v26
	v_add_f32_e32 v92, v2, v27
	v_add_f32_e32 v76, v3, v27
	v_add_f32_e32 v91, v2, v28
	v_add_f32_e32 v33, v3, v28
	v_add_f32_e32 v90, v2, v29
	v_add_f32_e32 v32, v3, v29
	v_add_f32_e32 v87, v2, v98
	v_add_f32_e32 v31, v3, v98
	v_add_f32_e32 v86, v2, v99
	v_add_f32_e32 v30, v3, v99
	v_add_f32_e32 v85, v2, v100
	v_add_f32_e32 v29, v3, v100
	v_add_f32_e32 v84, v2, v101
	v_add_f32_e32 v28, v3, v101
	v_add_f32_e32 v83, v2, v102
	v_add_f32_e32 v26, v3, v102
	v_add_f32_e32 v82, v2, v103
	v_add_f32_e32 v25, v3, v103
	v_add_f32_e32 v81, v2, v104
	v_add_f32_e32 v24, v3, v104
	v_pk_add_f32 v[22:23], v[2:3], v[22:23]
	v_add_f32_e32 v2, v3, v105
	v_max_f32_e32 v3, v97, v96
	v_max3_f32 v3, v3, v95, v94
	v_max3_f32 v3, v3, v93, v92
	v_max3_f32 v3, v3, v91, v90
	v_max3_f32 v3, v3, v87, v86
	v_max3_f32 v3, v3, v85, v84
	v_max3_f32 v3, v3, v83, v82
	v_max3_f32 v3, v3, v81, v22
	v_max3_f32 v3, v3, v23, v80
	v_min_f32_e32 v27, v97, v96
	v_max3_f32 v3, v3, v79, v78
	v_min3_f32 v27, v27, v95, v94
	v_max3_f32 v3, v3, v77, v76
	v_min3_f32 v27, v27, v93, v92
	v_max3_f32 v3, v3, v33, v32
	v_min3_f32 v27, v27, v91, v90
	v_max3_f32 v3, v3, v31, v30
	v_min3_f32 v27, v27, v87, v86
	v_max3_f32 v3, v3, v29, v28
	v_min3_f32 v27, v27, v85, v84
	v_max3_f32 v3, v3, v26, v25
	v_min3_f32 v27, v27, v83, v82
	v_max3_f32 v3, v3, v24, v2
	v_mov_b32_e32 v98, 0
	v_min3_f32 v27, v27, v81, v22
	v_min3_f32 v27, v27, v23, v80
	v_mov_b32_dpp v98, v3 quad_perm:[1,0,3,2] row_mask:0xf bank_mask:0xf
	v_max_f32_e32 v98, v98, v98
	v_min3_f32 v27, v27, v79, v78
	v_max_f32_e32 v3, v3, v98
	v_mov_b32_e32 v98, 0
	v_min3_f32 v27, v27, v77, v76
	v_min3_f32 v27, v27, v33, v32
	v_mov_b32_dpp v98, v3 quad_perm:[2,3,0,1] row_mask:0xf bank_mask:0xf
	v_max_f32_e32 v98, v98, v98
	v_min3_f32 v27, v27, v31, v30
	v_max_f32_e32 v3, v3, v98
	v_mov_b32_e32 v98, 0
	v_min3_f32 v27, v27, v29, v28
	v_min3_f32 v27, v27, v26, v25
	v_mov_b32_dpp v98, v3 row_half_mirror row_mask:0xf bank_mask:0xf
	v_max_f32_e32 v98, v98, v98
	v_min3_f32 v27, v27, v24, v2
	v_max_f32_e32 v3, v3, v98
	v_mov_b32_e32 v98, 0
	s_mov_b64 s[0:1], 0
	s_nop 0
	v_mov_b32_dpp v98, v27 quad_perm:[1,0,3,2] row_mask:0xf bank_mask:0xf
	v_max_f32_e32 v98, v98, v98
	v_min_f32_e32 v27, v27, v98
	v_mov_b32_e32 v98, 0
	s_nop 1
	v_mov_b32_dpp v98, v27 quad_perm:[2,3,0,1] row_mask:0xf bank_mask:0xf
	v_max_f32_e32 v98, v98, v98
	v_min_f32_e32 v27, v27, v98
	v_mov_b32_e32 v98, 0
	s_nop 1
	v_mov_b32_dpp v98, v27 row_half_mirror row_mask:0xf bank_mask:0xf
	v_max_f32_e32 v98, v98, v98
	v_min_f32_e32 v27, v27, v98
	v_mov_b32_e32 v98, 47
; template <int GS> __device__ __forceinline__ int grp_sum_i(int v) { v += dpp_i<0xB1>(v); v += dpp_i<0x4E>(v); if (GS == 8) v += dpp_i<0x141>(v); return v; }
; template <int GS> __device__ __forceinline__ void bisect16(const float (&x)[32], float& lo, float& hi) {
;     ...
;     for (int it = 0; it < 48; ++it) {
;         const float t = 0.5f * (lo + hi);
;         const bool conv = !(t > lo && t < hi);
;         int cnt = 0;
; #pragma unroll
;         for (int j = 0; j < 32; ++j) cnt += (x[j] >= t) ? 1 : 0;
;         cnt = grp_sum_i<GS>(cnt);
;         const bool upd = !done && !conv, ex = cnt == 16, gt = cnt > 16;
;         const float nlo = (ex || gt) ? t : lo, nhi = (ex || !gt) ? t : hi;
;         lo = upd ? nlo : lo; hi = upd ? nhi : hi;
;         done = done || conv || ex;
;         if (__ballot(!done) == 0ull) break;
;     }
; __device__ __forceinline__ void peer_select(const float* S, const int row, const int lane, LAS float* sv, LAS int* si, LAS float* fvL, LAS int* eL, int& e0o, int& e1o, float& g0o, float& g1o) {
;     ...
;             int cA = 0, cB = 0;
; #pragma unroll
;             for (int j = 0; j < 32; ++j) { cA += (c[j] >= hi) ? 1 : 0; cB += (c[j] >= lo && c[j] < hi) ? 1 : 0; }
.LBB0_999:
	v_add_f32_e32 v99, v27, v3
	v_mul_f32_e32 v99, 0.5, v99
	v_cmp_nlt_f32_e64 s[16:17], v99, v3
	v_cmp_ngt_f32_e64 s[18:19], v99, v27
	v_subrev_co_u32_e32 v98, vcc, 1, v98
	v_mov_b32_e32 v100, 0
	s_or_b64 s[28:29], s[18:19], s[16:17]
	v_cmp_ge_f32_e64 s[18:19], v96, v99
	v_cmp_ge_f32_e64 s[20:21], v97, v99
	v_cmp_ge_f32_e64 s[16:17], v95, v99
	v_addc_co_u32_e64 v100, s[18:19], 0, v100, s[18:19]
	v_cmp_ge_f32_e64 s[18:19], v93, v99
	v_addc_co_u32_e64 v100, s[20:21], 0, v100, s[20:21]
	v_cmp_ge_f32_e64 s[20:21], v91, v99
	v_addc_co_u32_e64 v100, s[16:17], 0, v100, s[16:17]
	v_cmp_ge_f32_e64 s[16:17], v87, v99
	v_addc_co_u32_e64 v100, s[18:19], 0, v100, s[18:19]
	v_cmp_ge_f32_e64 s[18:19], v85, v99
	v_addc_co_u32_e64 v100, s[20:21], 0, v100, s[20:21]
	v_cmp_ge_f32_e64 s[20:21], v83, v99
	v_addc_co_u32_e64 v100, s[16:17], 0, v100, s[16:17]
	v_cmp_ge_f32_e64 s[16:17], v81, v99
	v_addc_co_u32_e64 v100, s[18:19], 0, v100, s[18:19]
	v_cmp_ge_f32_e64 s[18:19], v23, v99
	v_addc_co_u32_e64 v100, s[20:21], 0, v100, s[20:21]
	v_cmp_ge_f32_e64 s[20:21], v79, v99
	v_addc_co_u32_e64 v100, s[16:17], 0, v100, s[16:17]
	v_cmp_ge_f32_e64 s[16:17], v77, v99
	v_addc_co_u32_e64 v100, s[18:19], 0, v100, s[18:19]
	v_cmp_ge_f32_e64 s[18:19], v33, v99
	v_addc_co_u32_e64 v100, s[20:21], 0, v100, s[20:21]
	v_cmp_ge_f32_e64 s[20:21], v31, v99
	v_addc_co_u32_e64 v100, s[16:17], 0, v100, s[16:17]
	v_cmp_ge_f32_e64 s[16:17], v29, v99
	v_addc_co_u32_e64 v100, s[18:19], 0, v100, s[18:19]
	v_cmp_ge_f32_e64 s[18:19], v26, v99
	v_addc_co_u32_e64 v100, s[20:21], 0, v100, s[20:21]
	v_cmp_ge_f32_e64 s[20:21], v24, v99
	v_addc_co_u32_e64 v100, s[16:17], 0, v100, s[16:17]
	v_cmp_ge_f32_e64 s[16:17], v94, v99
	v_addc_co_u32_e64 v100, s[18:19], 0, v100, s[18:19]
	v_cmp_ge_f32_e64 s[18:19], v92, v99
	v_addc_co_u32_e64 v100, s[20:21], 0, v100, s[20:21]
	v_cmp_ge_f32_e64 s[20:21], v90, v99
	v_addc_co_u32_e64 v100, s[16:17], 0, v100, s[16:17]
	v_cmp_ge_f32_e64 s[16:17], v86, v99
	v_addc_co_u32_e64 v100, s[18:19], 0, v100, s[18:19]
	v_cmp_ge_f32_e64 s[18:19], v84, v99
	v_addc_co_u32_e64 v100, s[20:21], 0, v100, s[20:21]
	v_cmp_ge_f32_e64 s[20:21], v82, v99
	v_addc_co_u32_e64 v100, s[16:17], 0, v100, s[16:17]
	v_cmp_ge_f32_e64 s[16:17], v22, v99
	v_addc_co_u32_e64 v100, s[18:19], 0, v100, s[18:19]
	v_cmp_ge_f32_e64 s[18:19], v80, v99
	v_addc_co_u32_e64 v100, s[20:21], 0, v100, s[20:21]
	v_cmp_ge_f32_e64 s[20:21], v78, v99
	v_addc_co_u32_e64 v100, s[16:17], 0, v100, s[16:17]
	v_cmp_ge_f32_e64 s[16:17], v76, v99
	v_addc_co_u32_e64 v100, s[18:19], 0, v100, s[18:19]
	v_cmp_ge_f32_e64 s[18:19], v32, v99
	v_addc_co_u32_e64 v100, s[20:21], 0, v100, s[20:21]
	v_cmp_ge_f32_e64 s[20:21], v30, v99
	v_addc_co_u32_e64 v100, s[16:17], 0, v100, s[16:17]
	v_cmp_ge_f32_e64 s[16:17], v28, v99
	v_addc_co_u32_e64 v100, s[18:19], 0, v100, s[18:19]
	v_cmp_ge_f32_e64 s[18:19], v25, v99
	v_addc_co_u32_e64 v100, s[20:21], 0, v100, s[20:21]
	v_cmp_ge_f32_e64 s[20:21], v2, v99
	v_addc_co_u32_e64 v100, s[16:17], 0, v100, s[16:17]
	v_addc_co_u32_e64 v100, s[18:19], 0, v100, s[18:19]
	v_addc_co_u32_e64 v100, s[20:21], 0, v100, s[20:21]
	s_nop 1
	v_add_u32_dpp v100, v100, v100 quad_perm:[1,0,3,2] row_mask:0xf bank_mask:0xf bound_ctrl:1
	s_nop 1
	v_add_u32_dpp v100, v100, v100 quad_perm:[2,3,0,1] row_mask:0xf bank_mask:0xf bound_ctrl:1
	s_nop 1
	v_add_u32_dpp v100, v100, v100 row_half_mirror row_mask:0xf bank_mask:0xf bound_ctrl:1
	v_cmp_lt_i32_e64 s[20:21], 15, v100
	v_cmp_eq_u32_e64 s[16:17], 16, v100
	v_cmp_lt_i32_e64 s[18:19], 16, v100
	v_cndmask_b32_e64 v100, v27, v99, s[20:21]
	s_or_b64 s[20:21], s[0:1], s[28:29]
	s_or_b64 s[0:1], s[20:21], s[16:17]
	s_xor_b64 s[16:17], s[0:1], -1
	v_cndmask_b32_e64 v27, v100, v27, s[20:21]
	v_cndmask_b32_e64 v100, 0, 1, s[16:17]
	s_or_b64 s[18:19], s[20:21], s[18:19]
	v_cmp_ne_u32_e64 s[16:17], 0, v100
	s_cmp_eq_u64 s[16:17], 0
	s_cselect_b64 s[16:17], -1, 0
	s_or_b64 s[16:17], s[16:17], vcc
	s_andn2_b64 vcc, exec, s[16:17]
	v_cndmask_b32_e64 v3, v99, v3, s[18:19]
	s_cbranch_vccnz .LBB0_999
	v_cmp_ge_f32_e64 s[18:19], v96, v3
	v_cmp_lt_f32_e64 s[20:21], v96, v3
	v_cmp_ge_f32_e32 vcc, v97, v27
	v_cndmask_b32_e64 v98, 0, 1, s[18:19]
	v_cmp_ge_f32_e64 s[18:19], v97, v3
	v_cmp_lt_f32_e64 s[16:17], v97, v3
	s_and_b64 vcc, vcc, s[16:17]
	v_addc_co_u32_e64 v98, s[18:19], 0, v98, s[18:19]
	v_cmp_ge_f32_e64 s[18:19], v96, v27
	s_and_b64 s[0:1], s[18:19], s[20:21]
	v_cndmask_b32_e64 v99, 0, 1, s[0:1]
	v_addc_co_u32_e32 v99, vcc, 0, v99, vcc
	v_cmp_ge_f32_e32 vcc, v95, v3
	v_cmp_lt_f32_e64 s[16:17], v95, v3
	v_cmp_lt_f32_e64 s[18:19], v22, v3
	v_cndmask_b32_e64 v100, 0, 1, vcc
	v_cmp_ge_f32_e32 vcc, v95, v27
	s_and_b64 s[0:1], vcc, s[16:17]
	v_cmp_ge_f32_e32 vcc, v94, v3
	v_cmp_lt_f32_e64 s[16:17], v94, v3
	v_cndmask_b32_e64 v101, 0, 1, s[0:1]
	v_addc_co_u32_e32 v98, vcc, v98, v100, vcc
	v_cmp_ge_f32_e32 vcc, v94, v27
	s_and_b64 vcc, vcc, s[16:17]
	v_cmp_lt_f32_e64 s[16:17], v93, v3
	v_addc_co_u32_e32 v99, vcc, v99, v101, vcc
	v_cmp_ge_f32_e32 vcc, v93, v3
	s_nop 1
	v_cndmask_b32_e64 v100, 0, 1, vcc
	v_cmp_ge_f32_e32 vcc, v93, v27
	s_and_b64 s[0:1], vcc, s[16:17]
	v_cmp_ge_f32_e32 vcc, v92, v3
	v_cmp_lt_f32_e64 s[16:17], v92, v3
	v_cndmask_b32_e64 v101, 0, 1, s[0:1]
	v_addc_co_u32_e32 v98, vcc, v98, v100, vcc
	v_cmp_ge_f32_e32 vcc, v92, v27
	s_and_b64 vcc, vcc, s[16:17]
	v_cmp_lt_f32_e64 s[16:17], v91, v3
	v_addc_co_u32_e32 v99, vcc, v99, v101, vcc
	v_cmp_ge_f32_e32 vcc, v91, v3
	s_nop 1
	v_cndmask_b32_e64 v100, 0, 1, vcc
	v_cmp_ge_f32_e32 vcc, v91, v27
	s_and_b64 s[0:1], vcc, s[16:17]
	v_cmp_ge_f32_e32 vcc, v90, v3
	v_cmp_lt_f32_e64 s[16:17], v90, v3
	v_cndmask_b32_e64 v101, 0, 1, s[0:1]
; __device__ __forceinline__ void peer_select(const float* S, const int row, const int lane, LAS float* sv, LAS int* si, LAS float* fvL, LAS int* eL, int& e0o, int& e1o, float& g0o, float& g1o) {
;     ...
;             int cA = 0, cB = 0;
; #pragma unroll
;             for (int j = 0; j < 32; ++j) { cA += (c[j] >= hi) ? 1 : 0; cB += (c[j] >= lo && c[j] < hi) ? 1 : 0; }
;             const int pk = cA | (cB << 8);
;             int inc = pk;
;             { int t = __shfl_up(inc, 1, 8); if (sub >= 1) inc += t; t = __shfl_up(inc, 2, 8); if (sub >= 2) inc += t; t = __shfl_up(inc, 4, 8); if (sub >= 4) inc += t; }
;             const int tot = __shfl(inc, 7, 8), pre = inc - pk;
	v_addc_co_u32_e32 v98, vcc, v98, v100, vcc
	v_cmp_ge_f32_e32 vcc, v90, v27
	s_and_b64 vcc, vcc, s[16:17]
	v_cmp_lt_f32_e64 s[16:17], v87, v3
	v_addc_co_u32_e32 v99, vcc, v99, v101, vcc
	v_cmp_ge_f32_e32 vcc, v87, v3
	s_nop 1
	v_cndmask_b32_e64 v100, 0, 1, vcc
	v_cmp_ge_f32_e32 vcc, v87, v27
	s_and_b64 s[0:1], vcc, s[16:17]
	v_cmp_ge_f32_e32 vcc, v86, v3
	v_cmp_lt_f32_e64 s[16:17], v86, v3
	v_cndmask_b32_e64 v101, 0, 1, s[0:1]
	v_addc_co_u32_e32 v98, vcc, v98, v100, vcc
	v_cmp_ge_f32_e32 vcc, v86, v27
	s_and_b64 vcc, vcc, s[16:17]
	v_cmp_lt_f32_e64 s[16:17], v85, v3
	v_addc_co_u32_e32 v99, vcc, v99, v101, vcc
	v_cmp_ge_f32_e32 vcc, v85, v3
	s_nop 1
	v_cndmask_b32_e64 v100, 0, 1, vcc
	v_cmp_ge_f32_e32 vcc, v85, v27
	s_and_b64 s[0:1], vcc, s[16:17]
	v_cmp_ge_f32_e32 vcc, v84, v3
	v_cmp_lt_f32_e64 s[16:17], v84, v3
	v_cndmask_b32_e64 v101, 0, 1, s[0:1]
	v_addc_co_u32_e32 v98, vcc, v98, v100, vcc
	v_cmp_ge_f32_e32 vcc, v84, v27
	s_and_b64 vcc, vcc, s[16:17]
	v_cmp_lt_f32_e64 s[16:17], v83, v3
	v_addc_co_u32_e32 v99, vcc, v99, v101, vcc
	v_cmp_ge_f32_e32 vcc, v83, v3
	s_nop 1
	v_cndmask_b32_e64 v100, 0, 1, vcc
	v_cmp_ge_f32_e32 vcc, v83, v27
	s_and_b64 s[0:1], vcc, s[16:17]
	v_cmp_ge_f32_e32 vcc, v82, v3
	v_cmp_lt_f32_e64 s[16:17], v82, v3
	v_cndmask_b32_e64 v101, 0, 1, s[0:1]
	v_addc_co_u32_e32 v98, vcc, v98, v100, vcc
	v_cmp_ge_f32_e32 vcc, v82, v27
	s_and_b64 vcc, vcc, s[16:17]
	v_cmp_lt_f32_e64 s[16:17], v81, v3
	v_addc_co_u32_e32 v99, vcc, v99, v101, vcc
	v_cmp_ge_f32_e32 vcc, v81, v3
	s_nop 1
	v_cndmask_b32_e64 v100, 0, 1, vcc
	v_cmp_ge_f32_e32 vcc, v81, v27
	s_and_b64 s[0:1], vcc, s[16:17]
	v_cmp_ge_f32_e32 vcc, v22, v3
	v_cndmask_b32_e64 v101, 0, 1, s[0:1]
	v_cmp_lt_f32_e64 s[16:17], v23, v3
	v_addc_co_u32_e32 v98, vcc, v98, v100, vcc
	v_cmp_ge_f32_e32 vcc, v22, v27
	s_and_b64 vcc, vcc, s[18:19]
	s_nop 0
	v_addc_co_u32_e32 v99, vcc, v99, v101, vcc
	v_cmp_ge_f32_e32 vcc, v23, v3
	s_nop 1
	v_cndmask_b32_e64 v100, 0, 1, vcc
	v_cmp_ge_f32_e32 vcc, v23, v27
	s_and_b64 s[0:1], vcc, s[16:17]
	v_cmp_ge_f32_e32 vcc, v80, v3
	v_cmp_lt_f32_e64 s[16:17], v80, v3
	v_cndmask_b32_e64 v101, 0, 1, s[0:1]
	v_addc_co_u32_e32 v98, vcc, v98, v100, vcc
	v_cmp_ge_f32_e32 vcc, v80, v27
	s_and_b64 vcc, vcc, s[16:17]
	v_cmp_lt_f32_e64 s[16:17], v79, v3
	v_addc_co_u32_e32 v99, vcc, v99, v101, vcc
	v_cmp_ge_f32_e32 vcc, v79, v3
	s_nop 1
	v_cndmask_b32_e64 v100, 0, 1, vcc
	v_cmp_ge_f32_e32 vcc, v79, v27
	s_and_b64 s[0:1], vcc, s[16:17]
	v_cmp_ge_f32_e32 vcc, v78, v3
	v_cmp_lt_f32_e64 s[16:17], v78, v3
	v_cndmask_b32_e64 v101, 0, 1, s[0:1]
	v_addc_co_u32_e32 v98, vcc, v98, v100, vcc
	v_cmp_ge_f32_e32 vcc, v78, v27
	s_and_b64 vcc, vcc, s[16:17]
	v_cmp_lt_f32_e64 s[16:17], v77, v3
	v_addc_co_u32_e32 v99, vcc, v99, v101, vcc
	v_cmp_ge_f32_e32 vcc, v77, v3
	s_nop 1
	v_cndmask_b32_e64 v100, 0, 1, vcc
	v_cmp_ge_f32_e32 vcc, v77, v27
	s_and_b64 s[0:1], vcc, s[16:17]
	v_cmp_ge_f32_e32 vcc, v76, v3
	v_cmp_lt_f32_e64 s[16:17], v76, v3
	v_cndmask_b32_e64 v101, 0, 1, s[0:1]
	v_addc_co_u32_e32 v98, vcc, v98, v100, vcc
	v_cmp_ge_f32_e32 vcc, v76, v27
	s_and_b64 vcc, vcc, s[16:17]
	v_cmp_lt_f32_e64 s[16:17], v33, v3
	v_addc_co_u32_e32 v99, vcc, v99, v101, vcc
	v_cmp_ge_f32_e32 vcc, v33, v3
	s_nop 1
	v_cndmask_b32_e64 v100, 0, 1, vcc
	v_cmp_ge_f32_e32 vcc, v33, v27
	s_and_b64 s[0:1], vcc, s[16:17]
	v_cmp_ge_f32_e32 vcc, v32, v3
	v_cmp_lt_f32_e64 s[16:17], v32, v3
	v_cndmask_b32_e64 v101, 0, 1, s[0:1]
	v_addc_co_u32_e32 v98, vcc, v98, v100, vcc
	v_cmp_ge_f32_e32 vcc, v32, v27
	s_and_b64 vcc, vcc, s[16:17]
	v_cmp_lt_f32_e64 s[16:17], v31, v3
	v_addc_co_u32_e32 v99, vcc, v99, v101, vcc
	v_cmp_ge_f32_e32 vcc, v31, v3
	s_nop 1
	v_cndmask_b32_e64 v100, 0, 1, vcc
	v_cmp_ge_f32_e32 vcc, v31, v27
	s_and_b64 s[0:1], vcc, s[16:17]
	v_cmp_ge_f32_e32 vcc, v30, v3
	v_cmp_lt_f32_e64 s[16:17], v30, v3
	v_cndmask_b32_e64 v101, 0, 1, s[0:1]
	v_addc_co_u32_e32 v98, vcc, v98, v100, vcc
	v_cmp_ge_f32_e32 vcc, v30, v27
	s_and_b64 vcc, vcc, s[16:17]
	v_cmp_lt_f32_e64 s[16:17], v29, v3
	v_addc_co_u32_e32 v99, vcc, v99, v101, vcc
	v_cmp_ge_f32_e32 vcc, v29, v3
	s_nop 1
	v_cndmask_b32_e64 v100, 0, 1, vcc
	v_cmp_ge_f32_e32 vcc, v29, v27
	s_and_b64 s[0:1], vcc, s[16:17]
	v_cmp_ge_f32_e32 vcc, v28, v3
	v_cmp_lt_f32_e64 s[16:17], v28, v3
	v_cndmask_b32_e64 v101, 0, 1, s[0:1]
	v_addc_co_u32_e32 v98, vcc, v98, v100, vcc
	v_cmp_ge_f32_e32 vcc, v28, v27
	s_and_b64 vcc, vcc, s[16:17]
	v_cmp_lt_f32_e64 s[16:17], v26, v3
	v_addc_co_u32_e32 v99, vcc, v99, v101, vcc
	v_cmp_ge_f32_e32 vcc, v26, v3
	s_nop 1
	v_cndmask_b32_e64 v100, 0, 1, vcc
	v_cmp_ge_f32_e32 vcc, v26, v27
	s_and_b64 s[0:1], vcc, s[16:17]
	v_cmp_ge_f32_e32 vcc, v25, v3
	v_cmp_lt_f32_e64 s[16:17], v25, v3
	v_cndmask_b32_e64 v101, 0, 1, s[0:1]
	v_addc_co_u32_e32 v98, vcc, v98, v100, vcc
	v_cmp_ge_f32_e32 vcc, v25, v27
	s_and_b64 vcc, vcc, s[16:17]
	v_cmp_lt_f32_e64 s[16:17], v24, v3
	v_addc_co_u32_e32 v99, vcc, v99, v101, vcc
	v_cmp_ge_f32_e32 vcc, v24, v3
	s_nop 1
	v_cndmask_b32_e64 v100, 0, 1, vcc
	v_cmp_ge_f32_e32 vcc, v24, v27
	s_and_b64 s[0:1], vcc, s[16:17]
	v_cmp_ge_f32_e32 vcc, v2, v3
	v_cmp_lt_f32_e64 s[16:17], v2, v3
	v_cndmask_b32_e64 v101, 0, 1, s[0:1]
	v_addc_co_u32_e32 v98, vcc, v98, v100, vcc
	v_cmp_ge_f32_e32 vcc, v2, v27
	s_and_b64 vcc, vcc, s[16:17]
	v_and_b32_e32 v100, 0x78, v1
	v_addc_co_u32_e32 v99, vcc, v99, v101, vcc
	v_lshl_or_b32 v98, v99, 8, v98
	v_add_u32_e32 v99, -1, v1
	v_cmp_lt_i32_e32 vcc, v99, v100
	v_add_u32_e32 v101, -2, v1
	s_nop 0
	v_cndmask_b32_e32 v99, v99, v1, vcc
	v_lshlrev_b32_e32 v99, 2, v99
	ds_bpermute_b32 v99, v99, v98
	v_cmp_lt_i32_e32 vcc, v101, v100
	v_cmp_ge_f32_e64 s[16:17], v97, v27
	s_waitcnt lgkmcnt(0)
; __device__ __forceinline__ void peer_select(const float* S, const int row, const int lane, LAS float* sv, LAS int* si, LAS float* fvL, LAS int* eL, int& e0o, int& e1o, float& g0o, float& g1o) {
;     ...
;             { int t = __shfl_up(inc, 1, 8); if (sub >= 1) inc += t; t = __shfl_up(inc, 2, 8); if (sub >= 2) inc += t; t = __shfl_up(inc, 4, 8); if (sub >= 4) inc += t; }
;             const int tot = __shfl(inc, 7, 8), pre = inc - pk;
;             int pA = pre & 255, pB = (tot & 255) + (pre >> 8);
;             asm volatile("" : "+v"(lo), "+v"(hi));
; #pragma unroll
;             for (int j = 0; j < 32; ++j) {
;                 const bool isA = c[j] >= hi, isB = !isA && c[j] >= lo;
;                 const int slot = isA ? pA : pB;
;                 if ((isA || isB) && slot < 16) { fvL[hd * 16 + slot] = c[j]; eL[hd * 16 + slot] = (j < 16 ? i1a : i1b) * 128 + i2[j & 15]; }
;                 pA += isA ? 1 : 0; pB += isB ? 1 : 0;
;             }
	v_cndmask_b32_e64 v99, v99, 0, s[10:11]
	v_cndmask_b32_e32 v101, v101, v1, vcc
	v_add_u32_e32 v99, v99, v98
	v_lshlrev_b32_e32 v101, 2, v101
	ds_bpermute_b32 v101, v101, v99
	s_waitcnt lgkmcnt(0)
	v_cndmask_b32_e64 v101, 0, v101, s[12:13]
	v_add_u32_e32 v99, v99, v101
	v_add_u32_e32 v101, -4, v1
	v_cmp_lt_i32_e32 vcc, v101, v100
	s_nop 1
	v_cndmask_b32_e32 v100, v101, v1, vcc
	v_lshlrev_b32_e32 v100, 2, v100
	ds_bpermute_b32 v100, v100, v99
	v_cmp_ge_f32_e32 vcc, v97, v3
	s_or_b64 s[0:1], vcc, s[16:17]
	s_waitcnt lgkmcnt(0)
	v_cndmask_b32_e64 v100, 0, v100, s[14:15]
	v_add_u32_e32 v99, v99, v100
	ds_bpermute_b32 v100, v75, v99
	v_sub_u32_e32 v99, v99, v98
	v_and_b32_e32 v98, 0xff, v99
	v_ashrrev_i32_e32 v99, 8, v99
	s_waitcnt lgkmcnt(0)
	v_add_u32_sdwa v99, v99, v100 dst_sel:DWORD dst_unused:UNUSED_PAD src0_sel:DWORD src1_sel:BYTE_0
	v_cndmask_b32_e32 v100, v99, v98, vcc
	v_cmp_gt_i32_e64 s[18:19], 16, v100
	s_and_b64 s[18:19], s[0:1], s[18:19]
	s_and_saveexec_b64 s[0:1], s[18:19]
	v_add_u32_e32 v100, v100, v73
	v_lshl_add_u32 v100, v100, 2, s22
	v_lshl_add_u32 v101, v4, 7, v18
	ds_write2st64_b32 v100, v97, v101 offset0:8 offset1:10
	s_or_b64 exec, exec, s[0:1]
	s_xor_b64 s[0:1], vcc, -1
	s_and_b64 s[0:1], s[0:1], s[16:17]
	v_cndmask_b32_e64 v100, 0, 1, s[0:1]
	v_cndmask_b32_e64 v97, 0, 1, vcc
	v_add_u32_e32 v97, v98, v97
	v_add_u32_e32 v98, v99, v100
	v_cmp_ge_f32_e32 vcc, v96, v3
	v_cmp_ge_f32_e64 s[16:17], v96, v27
	s_or_b64 s[0:1], vcc, s[16:17]
	v_cndmask_b32_e32 v99, v98, v97, vcc
	v_cmp_gt_i32_e64 s[18:19], 16, v99
	s_and_b64 s[18:19], s[0:1], s[18:19]
	s_and_saveexec_b64 s[0:1], s[18:19]
	v_add_u32_e32 v99, v99, v73
	v_lshl_add_u32 v99, v99, 2, s22
	v_lshl_add_u32 v100, v4, 7, v19
	ds_write2st64_b32 v99, v96, v100 offset0:8 offset1:10
	s_or_b64 exec, exec, s[0:1]
	s_xor_b64 s[0:1], vcc, -1
	s_and_b64 s[0:1], s[0:1], s[16:17]
	v_cndmask_b32_e64 v99, 0, 1, s[0:1]
	v_cndmask_b32_e64 v96, 0, 1, vcc
	v_add_u32_e32 v96, v97, v96
	v_add_u32_e32 v97, v98, v99
	v_cmp_ge_f32_e32 vcc, v95, v3
	v_cmp_ge_f32_e64 s[16:17], v95, v27
	s_or_b64 s[0:1], vcc, s[16:17]
	v_cndmask_b32_e32 v98, v97, v96, vcc
	v_cmp_gt_i32_e64 s[18:19], 16, v98
	s_and_b64 s[18:19], s[0:1], s[18:19]
	s_and_saveexec_b64 s[0:1], s[18:19]
	v_add_u32_e32 v98, v98, v73
	v_lshl_add_u32 v98, v98, 2, s22
	v_lshl_add_u32 v99, v4, 7, v20
	ds_write2st64_b32 v98, v95, v99 offset0:8 offset1:10
	s_or_b64 exec, exec, s[0:1]
	s_xor_b64 s[0:1], vcc, -1
	s_and_b64 s[0:1], s[0:1], s[16:17]
	v_cndmask_b32_e64 v98, 0, 1, s[0:1]
	v_cndmask_b32_e64 v95, 0, 1, vcc
	v_add_u32_e32 v95, v96, v95
	v_add_u32_e32 v96, v97, v98
	v_cmp_ge_f32_e32 vcc, v94, v3
	v_cmp_ge_f32_e64 s[16:17], v94, v27
	s_or_b64 s[0:1], vcc, s[16:17]
	v_cndmask_b32_e32 v97, v96, v95, vcc
	v_cmp_gt_i32_e64 s[18:19], 16, v97
	s_and_b64 s[18:19], s[0:1], s[18:19]
	s_and_saveexec_b64 s[0:1], s[18:19]
	v_add_u32_e32 v97, v97, v73
	v_lshl_add_u32 v97, v97, 2, s22
	v_lshl_add_u32 v98, v4, 7, v21
	ds_write2st64_b32 v97, v94, v98 offset0:8 offset1:10
	s_or_b64 exec, exec, s[0:1]
	s_xor_b64 s[0:1], vcc, -1
	s_and_b64 s[0:1], s[0:1], s[16:17]
	v_cndmask_b32_e64 v97, 0, 1, s[0:1]
	v_cndmask_b32_e64 v94, 0, 1, vcc
	v_add_u32_e32 v94, v95, v94
	v_add_u32_e32 v95, v96, v97
	v_cmp_ge_f32_e32 vcc, v93, v3
	v_cmp_ge_f32_e64 s[16:17], v93, v27
	s_or_b64 s[0:1], vcc, s[16:17]
	v_cndmask_b32_e32 v96, v95, v94, vcc
	v_cmp_gt_i32_e64 s[18:19], 16, v96
	s_and_b64 s[18:19], s[0:1], s[18:19]
	s_and_saveexec_b64 s[0:1], s[18:19]
	v_add_u32_e32 v96, v96, v73
	v_lshl_add_u32 v96, v96, 2, s22
	v_lshl_add_u32 v97, v4, 7, v14
	ds_write2st64_b32 v96, v93, v97 offset0:8 offset1:10
	s_or_b64 exec, exec, s[0:1]
	s_xor_b64 s[0:1], vcc, -1
	s_and_b64 s[0:1], s[0:1], s[16:17]
	v_cndmask_b32_e64 v96, 0, 1, s[0:1]
	v_cndmask_b32_e64 v93, 0, 1, vcc
	v_add_u32_e32 v93, v94, v93
	v_add_u32_e32 v94, v95, v96
	v_cmp_ge_f32_e32 vcc, v92, v3
	v_cmp_ge_f32_e64 s[16:17], v92, v27
	s_or_b64 s[0:1], vcc, s[16:17]
	v_cndmask_b32_e32 v95, v94, v93, vcc
	v_cmp_gt_i32_e64 s[18:19], 16, v95
	s_and_b64 s[18:19], s[0:1], s[18:19]
	s_and_saveexec_b64 s[0:1], s[18:19]
	v_add_u32_e32 v95, v95, v73
	v_lshl_add_u32 v95, v95, 2, s22
	v_lshl_add_u32 v96, v4, 7, v15
	ds_write2st64_b32 v95, v92, v96 offset0:8 offset1:10
	s_or_b64 exec, exec, s[0:1]
	s_xor_b64 s[0:1], vcc, -1
	s_and_b64 s[0:1], s[0:1], s[16:17]
	v_cndmask_b32_e64 v95, 0, 1, s[0:1]
	v_cndmask_b32_e64 v92, 0, 1, vcc
	v_add_u32_e32 v92, v93, v92
	v_add_u32_e32 v93, v94, v95
	v_cmp_ge_f32_e32 vcc, v91, v3
	v_cmp_ge_f32_e64 s[16:17], v91, v27
	s_or_b64 s[0:1], vcc, s[16:17]
	v_cndmask_b32_e32 v94, v93, v92, vcc
	v_cmp_gt_i32_e64 s[18:19], 16, v94
	s_and_b64 s[18:19], s[0:1], s[18:19]
	s_and_saveexec_b64 s[0:1], s[18:19]
	v_add_u32_e32 v94, v94, v73
	v_lshl_add_u32 v94, v94, 2, s22
	v_lshl_add_u32 v95, v4, 7, v16
	ds_write2st64_b32 v94, v91, v95 offset0:8 offset1:10
	s_or_b64 exec, exec, s[0:1]
	s_xor_b64 s[0:1], vcc, -1
	s_and_b64 s[0:1], s[0:1], s[16:17]
	v_cndmask_b32_e64 v94, 0, 1, s[0:1]
	v_cndmask_b32_e64 v91, 0, 1, vcc
	v_add_u32_e32 v91, v92, v91
	v_add_u32_e32 v92, v93, v94
	v_cmp_ge_f32_e32 vcc, v90, v3
	v_cmp_ge_f32_e64 s[16:17], v90, v27
	s_or_b64 s[0:1], vcc, s[16:17]
	v_cndmask_b32_e32 v93, v92, v91, vcc
	v_cmp_gt_i32_e64 s[18:19], 16, v93
	s_and_b64 s[18:19], s[0:1], s[18:19]
	s_and_saveexec_b64 s[0:1], s[18:19]
	v_add_u32_e32 v93, v93, v73
	v_lshl_add_u32 v93, v93, 2, s22
	v_lshl_add_u32 v94, v4, 7, v17
	ds_write2st64_b32 v93, v90, v94 offset0:8 offset1:10
	s_or_b64 exec, exec, s[0:1]
	s_xor_b64 s[0:1], vcc, -1
	s_and_b64 s[0:1], s[0:1], s[16:17]
	v_cndmask_b32_e64 v93, 0, 1, s[0:1]
	v_cndmask_b32_e64 v90, 0, 1, vcc
; __device__ __forceinline__ void peer_select(const float* S, const int row, const int lane, LAS float* sv, LAS int* si, LAS float* fvL, LAS int* eL, int& e0o, int& e1o, float& g0o, float& g1o) {
;     ...
; #pragma unroll
;             for (int j = 0; j < 32; ++j) {
;                 const bool isA = c[j] >= hi, isB = !isA && c[j] >= lo;
;                 const int slot = isA ? pA : pB;
;                 if ((isA || isB) && slot < 16) { fvL[hd * 16 + slot] = c[j]; eL[hd * 16 + slot] = (j < 16 ? i1a : i1b) * 128 + i2[j & 15]; }
;                 pA += isA ? 1 : 0; pB += isB ? 1 : 0;
;             }
	v_add_u32_e32 v90, v91, v90
	v_add_u32_e32 v91, v92, v93
	v_cmp_ge_f32_e32 vcc, v87, v3
	v_cmp_ge_f32_e64 s[16:17], v87, v27
	s_or_b64 s[0:1], vcc, s[16:17]
	v_cndmask_b32_e32 v92, v91, v90, vcc
	v_cmp_gt_i32_e64 s[18:19], 16, v92
	s_and_b64 s[18:19], s[0:1], s[18:19]
	s_and_saveexec_b64 s[0:1], s[18:19]
	v_add_u32_e32 v92, v92, v73
	v_lshl_add_u32 v92, v92, 2, s22
	v_lshl_add_u32 v93, v4, 7, v10
	ds_write2st64_b32 v92, v87, v93 offset0:8 offset1:10
	s_or_b64 exec, exec, s[0:1]
	s_xor_b64 s[0:1], vcc, -1
	s_and_b64 s[0:1], s[0:1], s[16:17]
	v_cndmask_b32_e64 v92, 0, 1, s[0:1]
	v_cndmask_b32_e64 v87, 0, 1, vcc
	v_add_u32_e32 v87, v90, v87
	v_add_u32_e32 v90, v91, v92
	v_cmp_ge_f32_e32 vcc, v86, v3
	v_cmp_ge_f32_e64 s[16:17], v86, v27
	s_or_b64 s[0:1], vcc, s[16:17]
	v_cndmask_b32_e32 v91, v90, v87, vcc
	v_cmp_gt_i32_e64 s[18:19], 16, v91
	s_and_b64 s[18:19], s[0:1], s[18:19]
	s_and_saveexec_b64 s[0:1], s[18:19]
	v_add_u32_e32 v91, v91, v73
	v_lshl_add_u32 v91, v91, 2, s22
	v_lshl_add_u32 v92, v4, 7, v11
	ds_write2st64_b32 v91, v86, v92 offset0:8 offset1:10
	s_or_b64 exec, exec, s[0:1]
	s_xor_b64 s[0:1], vcc, -1
	s_and_b64 s[0:1], s[0:1], s[16:17]
	v_cndmask_b32_e64 v91, 0, 1, s[0:1]
	v_cndmask_b32_e64 v86, 0, 1, vcc
	v_add_u32_e32 v86, v87, v86
	v_add_u32_e32 v87, v90, v91
	v_cmp_ge_f32_e32 vcc, v85, v3
	v_cmp_ge_f32_e64 s[16:17], v85, v27
	s_or_b64 s[0:1], vcc, s[16:17]
	v_cndmask_b32_e32 v90, v87, v86, vcc
	v_cmp_gt_i32_e64 s[18:19], 16, v90
	s_and_b64 s[18:19], s[0:1], s[18:19]
	s_and_saveexec_b64 s[0:1], s[18:19]
	v_add_u32_e32 v90, v90, v73
	v_lshl_add_u32 v90, v90, 2, s22
	v_lshl_add_u32 v91, v4, 7, v12
	ds_write2st64_b32 v90, v85, v91 offset0:8 offset1:10
	s_or_b64 exec, exec, s[0:1]
	s_xor_b64 s[0:1], vcc, -1
	s_and_b64 s[0:1], s[0:1], s[16:17]
	v_cndmask_b32_e64 v90, 0, 1, s[0:1]
	v_cndmask_b32_e64 v85, 0, 1, vcc
	v_add_u32_e32 v85, v86, v85
	v_add_u32_e32 v86, v87, v90
	v_cmp_ge_f32_e32 vcc, v84, v3
	v_cmp_ge_f32_e64 s[16:17], v84, v27
	s_or_b64 s[0:1], vcc, s[16:17]
	v_cndmask_b32_e32 v87, v86, v85, vcc
	v_cmp_gt_i32_e64 s[18:19], 16, v87
	s_and_b64 s[18:19], s[0:1], s[18:19]
	s_and_saveexec_b64 s[0:1], s[18:19]
	v_add_u32_e32 v87, v87, v73
	v_lshl_add_u32 v87, v87, 2, s22
	v_lshl_add_u32 v90, v4, 7, v13
	ds_write2st64_b32 v87, v84, v90 offset0:8 offset1:10
	s_or_b64 exec, exec, s[0:1]
	s_xor_b64 s[0:1], vcc, -1
	s_and_b64 s[0:1], s[0:1], s[16:17]
	v_cndmask_b32_e64 v87, 0, 1, s[0:1]
	v_cndmask_b32_e64 v84, 0, 1, vcc
	v_add_u32_e32 v84, v85, v84
	v_add_u32_e32 v85, v86, v87
	v_cmp_ge_f32_e32 vcc, v83, v3
	v_cmp_ge_f32_e64 s[16:17], v83, v27
	s_or_b64 s[0:1], vcc, s[16:17]
	v_cndmask_b32_e32 v86, v85, v84, vcc
	v_cmp_gt_i32_e64 s[18:19], 16, v86
	s_and_b64 s[18:19], s[0:1], s[18:19]
	s_and_saveexec_b64 s[0:1], s[18:19]
	v_add_u32_e32 v86, v86, v73
	v_lshl_add_u32 v86, v86, 2, s22
	v_lshl_add_u32 v87, v4, 7, v6
	ds_write2st64_b32 v86, v83, v87 offset0:8 offset1:10
	s_or_b64 exec, exec, s[0:1]
	s_xor_b64 s[0:1], vcc, -1
	s_and_b64 s[0:1], s[0:1], s[16:17]
	v_cndmask_b32_e64 v86, 0, 1, s[0:1]
	v_cndmask_b32_e64 v83, 0, 1, vcc
	v_add_u32_e32 v83, v84, v83
	v_add_u32_e32 v84, v85, v86
	v_cmp_ge_f32_e32 vcc, v82, v3
	v_cmp_ge_f32_e64 s[16:17], v82, v27
	s_or_b64 s[0:1], vcc, s[16:17]
	v_cndmask_b32_e32 v85, v84, v83, vcc
	v_cmp_gt_i32_e64 s[18:19], 16, v85
	s_and_b64 s[18:19], s[0:1], s[18:19]
	s_and_saveexec_b64 s[0:1], s[18:19]
	v_add_u32_e32 v85, v85, v73
	v_lshl_add_u32 v85, v85, 2, s22
	v_lshl_add_u32 v86, v4, 7, v7
	ds_write2st64_b32 v85, v82, v86 offset0:8 offset1:10
	s_or_b64 exec, exec, s[0:1]
	s_xor_b64 s[0:1], vcc, -1
	s_and_b64 s[0:1], s[0:1], s[16:17]
	v_cndmask_b32_e64 v85, 0, 1, s[0:1]
	v_cndmask_b32_e64 v82, 0, 1, vcc
	v_add_u32_e32 v82, v83, v82
	v_add_u32_e32 v83, v84, v85
	v_cmp_ge_f32_e32 vcc, v81, v3
	v_cmp_ge_f32_e64 s[16:17], v81, v27
	s_or_b64 s[0:1], vcc, s[16:17]
	v_cndmask_b32_e32 v84, v83, v82, vcc
	v_cmp_gt_i32_e64 s[18:19], 16, v84
	s_and_b64 s[18:19], s[0:1], s[18:19]
	s_and_saveexec_b64 s[0:1], s[18:19]
	v_add_u32_e32 v84, v84, v73
	v_lshl_add_u32 v84, v84, 2, s22
	v_lshl_add_u32 v85, v4, 7, v8
	ds_write2st64_b32 v84, v81, v85 offset0:8 offset1:10
	s_or_b64 exec, exec, s[0:1]
	s_xor_b64 s[0:1], vcc, -1
	s_and_b64 s[0:1], s[0:1], s[16:17]
	v_cndmask_b32_e64 v84, 0, 1, s[0:1]
	v_cndmask_b32_e64 v81, 0, 1, vcc
	v_add_u32_e32 v81, v82, v81
	v_add_u32_e32 v82, v83, v84
	v_cmp_ge_f32_e32 vcc, v22, v3
	v_cmp_ge_f32_e64 s[16:17], v22, v27
	s_or_b64 s[0:1], vcc, s[16:17]
	v_cndmask_b32_e32 v83, v82, v81, vcc
	v_cmp_gt_i32_e64 s[18:19], 16, v83
	s_and_b64 s[18:19], s[0:1], s[18:19]
	s_and_saveexec_b64 s[0:1], s[18:19]
	v_add_u32_e32 v83, v83, v73
	v_lshl_add_u32 v83, v83, 2, s22
	v_lshl_add_u32 v4, v4, 7, v9
	ds_write2st64_b32 v83, v22, v4 offset0:8 offset1:10
	s_or_b64 exec, exec, s[0:1]
	s_xor_b64 s[0:1], vcc, -1
	s_and_b64 s[0:1], s[0:1], s[16:17]
	v_cndmask_b32_e64 v22, 0, 1, s[0:1]
	v_cndmask_b32_e64 v4, 0, 1, vcc
	v_add_u32_e32 v4, v81, v4
	v_add_u32_e32 v22, v82, v22
	v_cmp_ge_f32_e32 vcc, v23, v3
	v_cmp_ge_f32_e64 s[16:17], v23, v27
	s_or_b64 s[0:1], vcc, s[16:17]
	v_cndmask_b32_e32 v81, v22, v4, vcc
	v_cmp_gt_i32_e64 s[18:19], 16, v81
	s_and_b64 s[18:19], s[0:1], s[18:19]
	s_and_saveexec_b64 s[0:1], s[18:19]
	v_add_u32_e32 v81, v81, v73
	v_lshl_add_u32 v81, v81, 2, s22
	v_lshl_add_u32 v18, v5, 7, v18
	ds_write2st64_b32 v81, v23, v18 offset0:8 offset1:10
	s_or_b64 exec, exec, s[0:1]
	s_xor_b64 s[0:1], vcc, -1
	s_and_b64 s[0:1], s[0:1], s[16:17]
	v_cndmask_b32_e64 v18, 0, 1, s[0:1]
	v_cndmask_b32_e64 v23, 0, 1, vcc
	v_add_u32_e32 v4, v4, v23
	v_add_u32_e32 v18, v22, v18
	v_cmp_ge_f32_e32 vcc, v80, v3
; __device__ __forceinline__ void peer_select(const float* S, const int row, const int lane, LAS float* sv, LAS int* si, LAS float* fvL, LAS int* eL, int& e0o, int& e1o, float& g0o, float& g1o) {
;     ...
; #pragma unroll
;             for (int j = 0; j < 32; ++j) {
;                 const bool isA = c[j] >= hi, isB = !isA && c[j] >= lo;
;                 const int slot = isA ? pA : pB;
;                 if ((isA || isB) && slot < 16) { fvL[hd * 16 + slot] = c[j]; eL[hd * 16 + slot] = (j < 16 ? i1a : i1b) * 128 + i2[j & 15]; }
;                 pA += isA ? 1 : 0; pB += isB ? 1 : 0;
;             }
	v_cmp_ge_f32_e64 s[16:17], v80, v27
	s_or_b64 s[0:1], vcc, s[16:17]
	v_cndmask_b32_e32 v22, v18, v4, vcc
	v_cmp_gt_i32_e64 s[18:19], 16, v22
	s_and_b64 s[18:19], s[0:1], s[18:19]
	s_and_saveexec_b64 s[0:1], s[18:19]
	v_add_u32_e32 v22, v22, v73
	v_lshl_add_u32 v22, v22, 2, s22
	v_lshl_add_u32 v19, v5, 7, v19
	ds_write2st64_b32 v22, v80, v19 offset0:8 offset1:10
	s_or_b64 exec, exec, s[0:1]
	s_xor_b64 s[0:1], vcc, -1
	s_and_b64 s[0:1], s[0:1], s[16:17]
	v_cndmask_b32_e64 v19, 0, 1, s[0:1]
	v_cndmask_b32_e64 v22, 0, 1, vcc
	v_add_u32_e32 v4, v4, v22
	v_add_u32_e32 v18, v18, v19
	v_cmp_ge_f32_e32 vcc, v79, v3
	v_cmp_ge_f32_e64 s[16:17], v79, v27
	s_or_b64 s[0:1], vcc, s[16:17]
	v_cndmask_b32_e32 v19, v18, v4, vcc
	v_cmp_gt_i32_e64 s[18:19], 16, v19
	s_and_b64 s[18:19], s[0:1], s[18:19]
	s_and_saveexec_b64 s[0:1], s[18:19]
	v_add_u32_e32 v19, v19, v73
	v_lshl_add_u32 v19, v19, 2, s22
	v_lshl_add_u32 v20, v5, 7, v20
	ds_write2st64_b32 v19, v79, v20 offset0:8 offset1:10
	s_or_b64 exec, exec, s[0:1]
	s_xor_b64 s[0:1], vcc, -1
	s_and_b64 s[0:1], s[0:1], s[16:17]
	v_cndmask_b32_e64 v19, 0, 1, s[0:1]
	v_cndmask_b32_e64 v20, 0, 1, vcc
	v_add_u32_e32 v4, v4, v20
	v_add_u32_e32 v18, v18, v19
	v_cmp_ge_f32_e32 vcc, v78, v3
	v_cmp_ge_f32_e64 s[16:17], v78, v27
	s_or_b64 s[0:1], vcc, s[16:17]
	v_cndmask_b32_e32 v19, v18, v4, vcc
	v_cmp_gt_i32_e64 s[18:19], 16, v19
	s_and_b64 s[18:19], s[0:1], s[18:19]
	s_and_saveexec_b64 s[0:1], s[18:19]
	v_add_u32_e32 v19, v19, v73
	v_lshl_add_u32 v19, v19, 2, s22
	v_lshl_add_u32 v20, v5, 7, v21
	ds_write2st64_b32 v19, v78, v20 offset0:8 offset1:10
	s_or_b64 exec, exec, s[0:1]
	s_xor_b64 s[0:1], vcc, -1
	s_and_b64 s[0:1], s[0:1], s[16:17]
	v_cndmask_b32_e64 v19, 0, 1, s[0:1]
	v_cndmask_b32_e64 v20, 0, 1, vcc
	v_add_u32_e32 v4, v4, v20
	v_add_u32_e32 v18, v18, v19
	v_cmp_ge_f32_e32 vcc, v77, v3
	v_cmp_ge_f32_e64 s[16:17], v77, v27
	s_or_b64 s[0:1], vcc, s[16:17]
	v_cndmask_b32_e32 v19, v18, v4, vcc
	v_cmp_gt_i32_e64 s[18:19], 16, v19
	s_and_b64 s[18:19], s[0:1], s[18:19]
	s_and_saveexec_b64 s[0:1], s[18:19]
	v_add_u32_e32 v19, v19, v73
	v_lshl_add_u32 v19, v19, 2, s22
	v_lshl_add_u32 v14, v5, 7, v14
	ds_write2st64_b32 v19, v77, v14 offset0:8 offset1:10
	s_or_b64 exec, exec, s[0:1]
	s_xor_b64 s[0:1], vcc, -1
	s_and_b64 s[0:1], s[0:1], s[16:17]
	v_cndmask_b32_e64 v14, 0, 1, s[0:1]
	v_cndmask_b32_e64 v19, 0, 1, vcc
	v_add_u32_e32 v4, v4, v19
	v_add_u32_e32 v14, v18, v14
	v_cmp_ge_f32_e32 vcc, v76, v3
	v_cmp_ge_f32_e64 s[16:17], v76, v27
	s_or_b64 s[0:1], vcc, s[16:17]
	v_cndmask_b32_e32 v18, v14, v4, vcc
	v_cmp_gt_i32_e64 s[18:19], 16, v18
	s_and_b64 s[18:19], s[0:1], s[18:19]
	s_and_saveexec_b64 s[0:1], s[18:19]
	v_add_u32_e32 v18, v18, v73
	v_lshl_add_u32 v18, v18, 2, s22
	v_lshl_add_u32 v15, v5, 7, v15
	ds_write2st64_b32 v18, v76, v15 offset0:8 offset1:10
	s_or_b64 exec, exec, s[0:1]
	s_xor_b64 s[0:1], vcc, -1
	s_and_b64 s[0:1], s[0:1], s[16:17]
	v_cndmask_b32_e64 v15, 0, 1, s[0:1]
	v_cndmask_b32_e64 v18, 0, 1, vcc
	v_add_u32_e32 v4, v4, v18
	v_add_u32_e32 v14, v14, v15
	v_cmp_ge_f32_e32 vcc, v33, v3
	v_cmp_ge_f32_e64 s[16:17], v33, v27
	s_or_b64 s[0:1], vcc, s[16:17]
	v_cndmask_b32_e32 v15, v14, v4, vcc
	v_cmp_gt_i32_e64 s[18:19], 16, v15
	s_and_b64 s[18:19], s[0:1], s[18:19]
	s_and_saveexec_b64 s[0:1], s[18:19]
	v_add_u32_e32 v15, v15, v73
	v_lshl_add_u32 v15, v15, 2, s22
	v_lshl_add_u32 v16, v5, 7, v16
	ds_write2st64_b32 v15, v33, v16 offset0:8 offset1:10
	s_or_b64 exec, exec, s[0:1]
	s_xor_b64 s[0:1], vcc, -1
	s_and_b64 s[0:1], s[0:1], s[16:17]
	v_cndmask_b32_e64 v15, 0, 1, s[0:1]
	v_cndmask_b32_e64 v16, 0, 1, vcc
	v_add_u32_e32 v4, v4, v16
	v_add_u32_e32 v14, v14, v15
	v_cmp_ge_f32_e32 vcc, v32, v3
	v_cmp_ge_f32_e64 s[16:17], v32, v27
	s_or_b64 s[0:1], vcc, s[16:17]
	v_cndmask_b32_e32 v15, v14, v4, vcc
	v_cmp_gt_i32_e64 s[18:19], 16, v15
	s_and_b64 s[18:19], s[0:1], s[18:19]
	s_and_saveexec_b64 s[0:1], s[18:19]
	v_add_u32_e32 v15, v15, v73
	v_lshl_add_u32 v15, v15, 2, s22
	v_lshl_add_u32 v16, v5, 7, v17
	ds_write2st64_b32 v15, v32, v16 offset0:8 offset1:10
	s_or_b64 exec, exec, s[0:1]
	s_xor_b64 s[0:1], vcc, -1
	s_and_b64 s[0:1], s[0:1], s[16:17]
	v_cndmask_b32_e64 v15, 0, 1, s[0:1]
	v_cndmask_b32_e64 v16, 0, 1, vcc
	v_add_u32_e32 v4, v4, v16
	v_add_u32_e32 v14, v14, v15
	v_cmp_ge_f32_e32 vcc, v31, v3
	v_cmp_ge_f32_e64 s[16:17], v31, v27
	s_or_b64 s[0:1], vcc, s[16:17]
	v_cndmask_b32_e32 v15, v14, v4, vcc
	v_cmp_gt_i32_e64 s[18:19], 16, v15
	s_and_b64 s[18:19], s[0:1], s[18:19]
; __device__ __forceinline__ void peer_select(const float* S, const int row, const int lane, LAS float* sv, LAS int* si, LAS float* fvL, LAS int* eL, int& e0o, int& e1o, float& g0o, float& g1o) {
;     ...
; #pragma unroll
;             for (int j = 0; j < 32; ++j) {
;                 const bool isA = c[j] >= hi, isB = !isA && c[j] >= lo;
;                 const int slot = isA ? pA : pB;
;                 if ((isA || isB) && slot < 16) { fvL[hd * 16 + slot] = c[j]; eL[hd * 16 + slot] = (j < 16 ? i1a : i1b) * 128 + i2[j & 15]; }
;                 pA += isA ? 1 : 0; pB += isB ? 1 : 0;
;             }
;         }
;         __builtin_amdgcn_wave_barrier();
;         const int e0 = eL[lane], e1 = eL[64 + lane];
	s_and_saveexec_b64 s[0:1], s[18:19]
	v_add_u32_e32 v15, v15, v73
	v_lshl_add_u32 v15, v15, 2, s22
	v_lshl_add_u32 v10, v5, 7, v10
	ds_write2st64_b32 v15, v31, v10 offset0:8 offset1:10
	s_or_b64 exec, exec, s[0:1]
	s_xor_b64 s[0:1], vcc, -1
	s_and_b64 s[0:1], s[0:1], s[16:17]
	v_cndmask_b32_e64 v10, 0, 1, s[0:1]
	v_cndmask_b32_e64 v15, 0, 1, vcc
	v_add_u32_e32 v4, v4, v15
	v_add_u32_e32 v10, v14, v10
	v_cmp_ge_f32_e32 vcc, v30, v3
	v_cmp_ge_f32_e64 s[16:17], v30, v27
	s_or_b64 s[0:1], vcc, s[16:17]
	v_cndmask_b32_e32 v14, v10, v4, vcc
	v_cmp_gt_i32_e64 s[18:19], 16, v14
	s_and_b64 s[18:19], s[0:1], s[18:19]
	s_and_saveexec_b64 s[0:1], s[18:19]
	v_add_u32_e32 v14, v14, v73
	v_lshl_add_u32 v14, v14, 2, s22
	v_lshl_add_u32 v11, v5, 7, v11
	ds_write2st64_b32 v14, v30, v11 offset0:8 offset1:10
	s_or_b64 exec, exec, s[0:1]
	s_xor_b64 s[0:1], vcc, -1
	s_and_b64 s[0:1], s[0:1], s[16:17]
	v_cndmask_b32_e64 v11, 0, 1, s[0:1]
	v_cndmask_b32_e64 v14, 0, 1, vcc
	v_add_u32_e32 v4, v4, v14
	v_add_u32_e32 v10, v10, v11
	v_cmp_ge_f32_e32 vcc, v29, v3
	v_cmp_ge_f32_e64 s[16:17], v29, v27
	s_or_b64 s[0:1], vcc, s[16:17]
	v_cndmask_b32_e32 v11, v10, v4, vcc
	v_cmp_gt_i32_e64 s[18:19], 16, v11
	s_and_b64 s[18:19], s[0:1], s[18:19]
	s_and_saveexec_b64 s[0:1], s[18:19]
	v_add_u32_e32 v11, v11, v73
	v_lshl_add_u32 v11, v11, 2, s22
	v_lshl_add_u32 v12, v5, 7, v12
	ds_write2st64_b32 v11, v29, v12 offset0:8 offset1:10
	s_or_b64 exec, exec, s[0:1]
	s_xor_b64 s[0:1], vcc, -1
	s_and_b64 s[0:1], s[0:1], s[16:17]
	v_cndmask_b32_e64 v11, 0, 1, s[0:1]
	v_cndmask_b32_e64 v12, 0, 1, vcc
	v_add_u32_e32 v4, v4, v12
	v_add_u32_e32 v10, v10, v11
	v_cmp_ge_f32_e32 vcc, v28, v3
	v_cmp_ge_f32_e64 s[16:17], v28, v27
	s_or_b64 s[0:1], vcc, s[16:17]
	v_cndmask_b32_e32 v11, v10, v4, vcc
	v_cmp_gt_i32_e64 s[18:19], 16, v11
	s_and_b64 s[18:19], s[0:1], s[18:19]
	s_and_saveexec_b64 s[0:1], s[18:19]
	v_add_u32_e32 v11, v11, v73
	v_lshl_add_u32 v11, v11, 2, s22
	v_lshl_add_u32 v12, v5, 7, v13
	ds_write2st64_b32 v11, v28, v12 offset0:8 offset1:10
	s_or_b64 exec, exec, s[0:1]
	s_xor_b64 s[0:1], vcc, -1
	s_and_b64 s[0:1], s[0:1], s[16:17]
	v_cndmask_b32_e64 v11, 0, 1, s[0:1]
	v_cndmask_b32_e64 v12, 0, 1, vcc
	v_add_u32_e32 v4, v4, v12
	v_add_u32_e32 v10, v10, v11
	v_cmp_ge_f32_e32 vcc, v26, v3
	v_cmp_ge_f32_e64 s[16:17], v26, v27
	s_or_b64 s[0:1], vcc, s[16:17]
	v_cndmask_b32_e32 v11, v10, v4, vcc
	v_cmp_gt_i32_e64 s[18:19], 16, v11
	s_and_b64 s[18:19], s[0:1], s[18:19]
	s_and_saveexec_b64 s[0:1], s[18:19]
	v_add_u32_e32 v11, v11, v73
	v_lshl_add_u32 v11, v11, 2, s22
	v_lshl_add_u32 v6, v5, 7, v6
	ds_write2st64_b32 v11, v26, v6 offset0:8 offset1:10
	s_or_b64 exec, exec, s[0:1]
	s_xor_b64 s[0:1], vcc, -1
	s_and_b64 s[0:1], s[0:1], s[16:17]
	v_cndmask_b32_e64 v6, 0, 1, s[0:1]
	v_cndmask_b32_e64 v11, 0, 1, vcc
	v_add_u32_e32 v4, v4, v11
	v_add_u32_e32 v6, v10, v6
	v_cmp_ge_f32_e32 vcc, v25, v3
	v_cmp_ge_f32_e64 s[16:17], v25, v27
	s_or_b64 s[0:1], vcc, s[16:17]
	v_cndmask_b32_e32 v10, v6, v4, vcc
	v_cmp_gt_i32_e64 s[18:19], 16, v10
	s_and_b64 s[18:19], s[0:1], s[18:19]
	s_and_saveexec_b64 s[0:1], s[18:19]
	v_add_u32_e32 v10, v10, v73
	v_lshl_add_u32 v10, v10, 2, s22
	v_lshl_add_u32 v7, v5, 7, v7
	ds_write2st64_b32 v10, v25, v7 offset0:8 offset1:10
	s_or_b64 exec, exec, s[0:1]
	s_xor_b64 s[0:1], vcc, -1
	s_and_b64 s[0:1], s[0:1], s[16:17]
	v_cndmask_b32_e64 v7, 0, 1, s[0:1]
	v_cndmask_b32_e64 v10, 0, 1, vcc
	v_add_u32_e32 v4, v4, v10
	v_add_u32_e32 v6, v6, v7
	v_cmp_ge_f32_e32 vcc, v24, v3
	v_cmp_ge_f32_e64 s[16:17], v24, v27
	s_or_b64 s[0:1], vcc, s[16:17]
	v_cndmask_b32_e32 v7, v6, v4, vcc
	v_cmp_gt_i32_e64 s[18:19], 16, v7
	s_and_b64 s[18:19], s[0:1], s[18:19]
	s_and_saveexec_b64 s[0:1], s[18:19]
	v_add_u32_e32 v7, v7, v73
	v_lshl_add_u32 v7, v7, 2, s22
	v_lshl_add_u32 v8, v5, 7, v8
	ds_write2st64_b32 v7, v24, v8 offset0:8 offset1:10
	s_or_b64 exec, exec, s[0:1]
	s_xor_b64 s[0:1], vcc, -1
	s_and_b64 s[0:1], s[0:1], s[16:17]
	v_cndmask_b32_e64 v7, 0, 1, s[0:1]
	v_cndmask_b32_e64 v8, 0, 1, vcc
	v_add_u32_e32 v4, v4, v8
	v_add_u32_e32 v6, v6, v7
	v_cmp_ge_f32_e64 s[16:17], v2, v3
	v_cmp_ge_f32_e32 vcc, v2, v27
	s_or_b64 s[0:1], s[16:17], vcc
	v_cndmask_b32_e64 v3, v6, v4, s[16:17]
	v_cmp_gt_i32_e32 vcc, 16, v3
	s_and_b64 s[16:17], s[0:1], vcc
	s_and_saveexec_b64 s[0:1], s[16:17]
	s_cbranch_execz .LBB0_931
	v_add_u32_e32 v3, v3, v73
	v_lshl_add_u32 v3, v3, 2, s22
	v_lshl_add_u32 v4, v5, 7, v9
	ds_write2st64_b32 v3, v2, v4 offset0:8 offset1:10
	s_branch .LBB0_931

; template <int GS> __device__ __forceinline__ int grp_sum_i(int v) { v += dpp_i<0xB1>(v); v += dpp_i<0x4E>(v); if (GS == 8) v += dpp_i<0x141>(v); return v; }
; template <int GS> __device__ __forceinline__ void bisect16(const float (&x)[32], float& lo, float& hi) {
;     ...
;     for (int it = 0; it < 48; ++it) {
;         const float t = 0.5f * (lo + hi);
;         const bool conv = !(t > lo && t < hi);
;         int cnt = 0;
; #pragma unroll
;         for (int j = 0; j < 32; ++j) cnt += (x[j] >= t) ? 1 : 0;
;         cnt = grp_sum_i<GS>(cnt);
;         const bool upd = !done && !conv, ex = cnt == 16, gt = cnt > 16;
;         const float nlo = (ex || gt) ? t : lo, nhi = (ex || !gt) ? t : hi;
;         lo = upd ? nlo : lo; hi = upd ? nhi : hi;
;         done = done || conv || ex;
;         if (__ballot(!done) == 0ull) break;
;     }
; __device__ __forceinline__ void peer_select(const float* S, const int row, const int lane, LAS float* sv, LAS int* si, LAS float* fvL, LAS int* eL, int& e0o, int& e1o, float& g0o, float& g1o) {
;     ...
;             int cA = 0, cB = 0;
; #pragma unroll
;             for (int j = 0; j < 32; ++j) { cA += (x[j] >= hi) ? 1 : 0; cB += (x[j] >= lo && x[j] < hi) ? 1 : 0; }
.LBB0_1379:
	v_add_f32_e32 v79, v77, v76
	v_mul_f32_e32 v79, 0.5, v79
	v_cmp_nlt_f32_e64 s[14:15], v79, v76
	v_cmp_ngt_f32_e64 s[16:17], v79, v77
	v_subrev_co_u32_e32 v78, vcc, 1, v78
	v_mov_b32_e32 v80, 0
	s_or_b64 s[36:37], s[16:17], s[14:15]
	v_cmp_ge_f32_e64 s[16:17], v31, v79
	v_cmp_ge_f32_e64 s[18:19], v30, v79
	v_cmp_ge_f32_e64 s[14:15], v32, v79
	v_addc_co_u32_e64 v80, s[16:17], 0, v80, s[16:17]
	v_cmp_ge_f32_e64 s[16:17], v26, v79
	v_addc_co_u32_e64 v80, s[18:19], 0, v80, s[18:19]
	v_cmp_ge_f32_e64 s[18:19], v28, v79
	v_addc_co_u32_e64 v80, s[14:15], 0, v80, s[14:15]
	v_cmp_ge_f32_e64 s[14:15], v22, v79
	v_addc_co_u32_e64 v80, s[16:17], 0, v80, s[16:17]
	v_cmp_ge_f32_e64 s[16:17], v24, v79
	v_addc_co_u32_e64 v80, s[18:19], 0, v80, s[18:19]
	v_cmp_ge_f32_e64 s[18:19], v18, v79
	v_addc_co_u32_e64 v80, s[14:15], 0, v80, s[14:15]
	v_cmp_ge_f32_e64 s[14:15], v20, v79
	v_addc_co_u32_e64 v80, s[16:17], 0, v80, s[16:17]
	v_cmp_ge_f32_e64 s[16:17], v14, v79
	v_addc_co_u32_e64 v80, s[18:19], 0, v80, s[18:19]
	v_cmp_ge_f32_e64 s[18:19], v16, v79
	v_addc_co_u32_e64 v80, s[14:15], 0, v80, s[14:15]
	v_cmp_ge_f32_e64 s[14:15], v10, v79
	v_addc_co_u32_e64 v80, s[16:17], 0, v80, s[16:17]
	v_cmp_ge_f32_e64 s[16:17], v12, v79
	v_addc_co_u32_e64 v80, s[18:19], 0, v80, s[18:19]
	v_cmp_ge_f32_e64 s[18:19], v6, v79
	v_addc_co_u32_e64 v80, s[14:15], 0, v80, s[14:15]
	v_cmp_ge_f32_e64 s[14:15], v8, v79
	v_addc_co_u32_e64 v80, s[16:17], 0, v80, s[16:17]
	v_cmp_ge_f32_e64 s[16:17], v2, v79
	v_addc_co_u32_e64 v80, s[18:19], 0, v80, s[18:19]
	v_cmp_ge_f32_e64 s[18:19], v4, v79
	v_addc_co_u32_e64 v80, s[14:15], 0, v80, s[14:15]
	v_cmp_ge_f32_e64 s[14:15], v33, v79
	v_addc_co_u32_e64 v80, s[16:17], 0, v80, s[16:17]
	v_cmp_ge_f32_e64 s[16:17], v27, v79
	v_addc_co_u32_e64 v80, s[18:19], 0, v80, s[18:19]
	v_cmp_ge_f32_e64 s[18:19], v29, v79
	v_addc_co_u32_e64 v80, s[14:15], 0, v80, s[14:15]
	v_cmp_ge_f32_e64 s[14:15], v23, v79
	v_addc_co_u32_e64 v80, s[16:17], 0, v80, s[16:17]
	v_cmp_ge_f32_e64 s[16:17], v25, v79
	v_addc_co_u32_e64 v80, s[18:19], 0, v80, s[18:19]
	v_cmp_ge_f32_e64 s[18:19], v19, v79
	v_addc_co_u32_e64 v80, s[14:15], 0, v80, s[14:15]
	v_cmp_ge_f32_e64 s[14:15], v21, v79
	v_addc_co_u32_e64 v80, s[16:17], 0, v80, s[16:17]
	v_cmp_ge_f32_e64 s[16:17], v15, v79
	v_addc_co_u32_e64 v80, s[18:19], 0, v80, s[18:19]
	v_cmp_ge_f32_e64 s[18:19], v17, v79
	v_addc_co_u32_e64 v80, s[14:15], 0, v80, s[14:15]
	v_cmp_ge_f32_e64 s[14:15], v11, v79
	v_addc_co_u32_e64 v80, s[16:17], 0, v80, s[16:17]
	v_cmp_ge_f32_e64 s[16:17], v13, v79
	v_addc_co_u32_e64 v80, s[18:19], 0, v80, s[18:19]
	v_cmp_ge_f32_e64 s[18:19], v7, v79
	v_addc_co_u32_e64 v80, s[14:15], 0, v80, s[14:15]
	v_cmp_ge_f32_e64 s[14:15], v9, v79
	v_addc_co_u32_e64 v80, s[16:17], 0, v80, s[16:17]
	v_cmp_ge_f32_e64 s[16:17], v3, v79
	v_addc_co_u32_e64 v80, s[18:19], 0, v80, s[18:19]
	v_cmp_ge_f32_e64 s[18:19], v5, v79
	v_addc_co_u32_e64 v80, s[14:15], 0, v80, s[14:15]
	v_addc_co_u32_e64 v80, s[16:17], 0, v80, s[16:17]
	v_addc_co_u32_e64 v80, s[18:19], 0, v80, s[18:19]
	s_nop 1
	v_add_u32_dpp v80, v80, v80 quad_perm:[1,0,3,2] row_mask:0xf bank_mask:0xf bound_ctrl:1
	s_nop 1
	v_add_u32_dpp v80, v80, v80 quad_perm:[2,3,0,1] row_mask:0xf bank_mask:0xf bound_ctrl:1
	v_cmp_lt_i32_e64 s[18:19], 15, v80
	v_cmp_eq_u32_e64 s[14:15], 16, v80
	v_cmp_lt_i32_e64 s[16:17], 16, v80
	v_cndmask_b32_e64 v80, v77, v79, s[18:19]
	s_or_b64 s[18:19], s[34:35], s[36:37]
	s_or_b64 s[34:35], s[18:19], s[14:15]
	s_xor_b64 s[14:15], s[34:35], -1
	v_cndmask_b32_e64 v77, v80, v77, s[18:19]
	v_cndmask_b32_e64 v80, 0, 1, s[14:15]
	s_or_b64 s[16:17], s[18:19], s[16:17]
	v_cmp_ne_u32_e64 s[14:15], 0, v80
	s_cmp_eq_u64 s[14:15], 0
	s_cselect_b64 s[14:15], -1, 0
	s_or_b64 s[14:15], s[14:15], vcc
	s_andn2_b64 vcc, exec, s[14:15]
	v_cndmask_b32_e64 v76, v79, v76, s[16:17]
	s_cbranch_vccnz .LBB0_1379
	v_cmp_ge_f32_e64 s[16:17], v31, v76
	v_cmp_lt_f32_e64 s[18:19], v31, v76
	v_cmp_ge_f32_e32 vcc, v30, v77
	v_cndmask_b32_e64 v78, 0, 1, s[16:17]
	v_cmp_ge_f32_e64 s[16:17], v30, v76
	v_cmp_lt_f32_e64 s[14:15], v30, v76
	s_and_b64 vcc, vcc, s[14:15]
	v_addc_co_u32_e64 v78, s[16:17], 0, v78, s[16:17]
	v_cmp_ge_f32_e64 s[16:17], v31, v77
	s_and_b64 s[16:17], s[16:17], s[18:19]
	v_cmp_lt_f32_e64 s[14:15], v32, v76
	v_cndmask_b32_e64 v79, 0, 1, s[16:17]
	v_addc_co_u32_e32 v79, vcc, 0, v79, vcc
	v_cmp_ge_f32_e32 vcc, v32, v76
	v_mov_b32_e32 v82, 0
	s_nop 0
	v_cndmask_b32_e64 v80, 0, 1, vcc
	v_cmp_ge_f32_e32 vcc, v32, v77
	s_and_b64 s[14:15], vcc, s[14:15]
	v_cmp_ge_f32_e32 vcc, v33, v76
	v_cndmask_b32_e64 v81, 0, 1, s[14:15]
	v_cmp_lt_f32_e64 s[14:15], v33, v76
	v_addc_co_u32_e32 v78, vcc, v78, v80, vcc
	v_cmp_ge_f32_e32 vcc, v33, v77
	s_and_b64 vcc, vcc, s[14:15]
	v_cmp_lt_f32_e64 s[14:15], v26, v76
	v_addc_co_u32_e32 v79, vcc, v79, v81, vcc
	v_cmp_ge_f32_e32 vcc, v26, v76
	s_nop 1
	v_cndmask_b32_e64 v80, 0, 1, vcc
	v_cmp_ge_f32_e32 vcc, v26, v77
	s_and_b64 s[14:15], vcc, s[14:15]
	v_cmp_ge_f32_e32 vcc, v27, v76
	v_cndmask_b32_e64 v81, 0, 1, s[14:15]
	v_cmp_lt_f32_e64 s[14:15], v27, v76
	v_addc_co_u32_e32 v78, vcc, v78, v80, vcc
	v_cmp_ge_f32_e32 vcc, v27, v77
	s_and_b64 vcc, vcc, s[14:15]
	v_cmp_lt_f32_e64 s[14:15], v28, v76
	v_addc_co_u32_e32 v79, vcc, v79, v81, vcc
	v_cmp_ge_f32_e32 vcc, v28, v76
	s_nop 1
	v_cndmask_b32_e64 v80, 0, 1, vcc
	v_cmp_ge_f32_e32 vcc, v28, v77
	s_and_b64 s[14:15], vcc, s[14:15]
	v_cmp_ge_f32_e32 vcc, v29, v76
	v_cndmask_b32_e64 v81, 0, 1, s[14:15]
	v_cmp_lt_f32_e64 s[14:15], v29, v76
	v_addc_co_u32_e32 v78, vcc, v78, v80, vcc
	v_cmp_ge_f32_e32 vcc, v29, v77
	s_and_b64 vcc, vcc, s[14:15]
	v_cmp_lt_f32_e64 s[14:15], v22, v76
; template <int CTRL> __device__ __forceinline__ int dpp_i(int x) { return __builtin_amdgcn_update_dpp(0, x, CTRL, 0xf, 0xf, false); }
; __device__ __forceinline__ void peer_select(const float* S, const int row, const int lane, LAS float* sv, LAS int* si, LAS float* fvL, LAS int* eL, int& e0o, int& e1o, float& g0o, float& g1o) {
;     ...
;             int cA = 0, cB = 0;
; #pragma unroll
;             for (int j = 0; j < 32; ++j) { cA += (x[j] >= hi) ? 1 : 0; cB += (x[j] >= lo && x[j] < hi) ? 1 : 0; }
;             const int pk = cA | (cB << 8);
;             const int q0 = dpp_i<0x00>(pk), q1 = dpp_i<0x55>(pk), q2 = dpp_i<0xAA>(pk), q3 = dpp_i<0xFF>(pk);
;             const int tot = q0 + q1 + q2 + q3, pre = (qtr > 0 ? q0 : 0) + (qtr > 1 ? q1 : 0) + (qtr > 2 ? q2 : 0);
	v_addc_co_u32_e32 v79, vcc, v79, v81, vcc
	v_cmp_ge_f32_e32 vcc, v22, v76
	s_nop 1
	v_cndmask_b32_e64 v80, 0, 1, vcc
	v_cmp_ge_f32_e32 vcc, v22, v77
	s_and_b64 s[14:15], vcc, s[14:15]
	v_cmp_ge_f32_e32 vcc, v23, v76
	v_cndmask_b32_e64 v81, 0, 1, s[14:15]
	v_cmp_lt_f32_e64 s[14:15], v23, v76
	v_addc_co_u32_e32 v78, vcc, v78, v80, vcc
	v_cmp_ge_f32_e32 vcc, v23, v77
	s_and_b64 vcc, vcc, s[14:15]
	v_cmp_lt_f32_e64 s[14:15], v24, v76
	v_addc_co_u32_e32 v79, vcc, v79, v81, vcc
	v_cmp_ge_f32_e32 vcc, v24, v76
	s_nop 1
	v_cndmask_b32_e64 v80, 0, 1, vcc
	v_cmp_ge_f32_e32 vcc, v24, v77
	s_and_b64 s[14:15], vcc, s[14:15]
	v_cmp_ge_f32_e32 vcc, v25, v76
	v_cndmask_b32_e64 v81, 0, 1, s[14:15]
	v_cmp_lt_f32_e64 s[14:15], v25, v76
	v_addc_co_u32_e32 v78, vcc, v78, v80, vcc
	v_cmp_ge_f32_e32 vcc, v25, v77
	s_and_b64 vcc, vcc, s[14:15]
	v_cmp_lt_f32_e64 s[14:15], v18, v76
	v_addc_co_u32_e32 v79, vcc, v79, v81, vcc
	v_cmp_ge_f32_e32 vcc, v18, v76
	s_nop 1
	v_cndmask_b32_e64 v80, 0, 1, vcc
	v_cmp_ge_f32_e32 vcc, v18, v77
	s_and_b64 s[14:15], vcc, s[14:15]
	v_cmp_ge_f32_e32 vcc, v19, v76
	v_cndmask_b32_e64 v81, 0, 1, s[14:15]
	v_cmp_lt_f32_e64 s[14:15], v19, v76
	v_addc_co_u32_e32 v78, vcc, v78, v80, vcc
	v_cmp_ge_f32_e32 vcc, v19, v77
	s_and_b64 vcc, vcc, s[14:15]
	v_cmp_lt_f32_e64 s[14:15], v20, v76
	v_addc_co_u32_e32 v79, vcc, v79, v81, vcc
	v_cmp_ge_f32_e32 vcc, v20, v76
	s_nop 1
	v_cndmask_b32_e64 v80, 0, 1, vcc
	v_cmp_ge_f32_e32 vcc, v20, v77
	s_and_b64 s[14:15], vcc, s[14:15]
	v_cmp_ge_f32_e32 vcc, v21, v76
	v_cndmask_b32_e64 v81, 0, 1, s[14:15]
	v_cmp_lt_f32_e64 s[14:15], v21, v76
	v_addc_co_u32_e32 v78, vcc, v78, v80, vcc
	v_cmp_ge_f32_e32 vcc, v21, v77
	s_and_b64 vcc, vcc, s[14:15]
	v_cmp_lt_f32_e64 s[14:15], v14, v76
	v_addc_co_u32_e32 v79, vcc, v79, v81, vcc
	v_cmp_ge_f32_e32 vcc, v14, v76
	s_nop 1
	v_cndmask_b32_e64 v80, 0, 1, vcc
	v_cmp_ge_f32_e32 vcc, v14, v77
	s_and_b64 s[14:15], vcc, s[14:15]
	v_cmp_ge_f32_e32 vcc, v15, v76
	v_cndmask_b32_e64 v81, 0, 1, s[14:15]
	v_cmp_lt_f32_e64 s[14:15], v15, v76
	v_addc_co_u32_e32 v78, vcc, v78, v80, vcc
	v_cmp_ge_f32_e32 vcc, v15, v77
	s_and_b64 vcc, vcc, s[14:15]
	v_cmp_lt_f32_e64 s[14:15], v16, v76
	v_addc_co_u32_e32 v79, vcc, v79, v81, vcc
	v_cmp_ge_f32_e32 vcc, v16, v76
	s_nop 1
	v_cndmask_b32_e64 v80, 0, 1, vcc
	v_cmp_ge_f32_e32 vcc, v16, v77
	s_and_b64 s[14:15], vcc, s[14:15]
	v_cmp_ge_f32_e32 vcc, v17, v76
	v_cndmask_b32_e64 v81, 0, 1, s[14:15]
	v_cmp_lt_f32_e64 s[14:15], v17, v76
	v_addc_co_u32_e32 v78, vcc, v78, v80, vcc
	v_cmp_ge_f32_e32 vcc, v17, v77
	s_and_b64 vcc, vcc, s[14:15]
	v_cmp_lt_f32_e64 s[14:15], v10, v76
	v_addc_co_u32_e32 v79, vcc, v79, v81, vcc
	v_cmp_ge_f32_e32 vcc, v10, v76
	s_nop 1
	v_cndmask_b32_e64 v80, 0, 1, vcc
	v_cmp_ge_f32_e32 vcc, v10, v77
	s_and_b64 s[14:15], vcc, s[14:15]
	v_cmp_ge_f32_e32 vcc, v11, v76
	v_cndmask_b32_e64 v81, 0, 1, s[14:15]
	v_cmp_lt_f32_e64 s[14:15], v11, v76
	v_addc_co_u32_e32 v78, vcc, v78, v80, vcc
	v_cmp_ge_f32_e32 vcc, v11, v77
	s_and_b64 vcc, vcc, s[14:15]
	v_cmp_lt_f32_e64 s[14:15], v12, v76
	v_addc_co_u32_e32 v79, vcc, v79, v81, vcc
	v_cmp_ge_f32_e32 vcc, v12, v76
	s_nop 1
	v_cndmask_b32_e64 v80, 0, 1, vcc
	v_cmp_ge_f32_e32 vcc, v12, v77
	s_and_b64 s[14:15], vcc, s[14:15]
	v_cmp_ge_f32_e32 vcc, v13, v76
	v_cndmask_b32_e64 v81, 0, 1, s[14:15]
	v_cmp_lt_f32_e64 s[14:15], v13, v76
	v_addc_co_u32_e32 v78, vcc, v78, v80, vcc
	v_cmp_ge_f32_e32 vcc, v13, v77
	s_and_b64 vcc, vcc, s[14:15]
	v_cmp_lt_f32_e64 s[14:15], v6, v76
	v_addc_co_u32_e32 v79, vcc, v79, v81, vcc
	v_cmp_ge_f32_e32 vcc, v6, v76
	s_nop 1
	v_cndmask_b32_e64 v80, 0, 1, vcc
	v_cmp_ge_f32_e32 vcc, v6, v77
	s_and_b64 s[14:15], vcc, s[14:15]
	v_cmp_ge_f32_e32 vcc, v7, v76
	v_cndmask_b32_e64 v81, 0, 1, s[14:15]
	v_cmp_lt_f32_e64 s[14:15], v7, v76
	v_addc_co_u32_e32 v78, vcc, v78, v80, vcc
	v_cmp_ge_f32_e32 vcc, v7, v77
	s_and_b64 vcc, vcc, s[14:15]
	v_cmp_lt_f32_e64 s[14:15], v8, v76
	v_addc_co_u32_e32 v79, vcc, v79, v81, vcc
	v_cmp_ge_f32_e32 vcc, v8, v76
	s_nop 1
	v_cndmask_b32_e64 v80, 0, 1, vcc
	v_cmp_ge_f32_e32 vcc, v8, v77
	s_and_b64 s[14:15], vcc, s[14:15]
	v_cmp_ge_f32_e32 vcc, v9, v76
	v_cndmask_b32_e64 v81, 0, 1, s[14:15]
	v_cmp_lt_f32_e64 s[14:15], v9, v76
	v_addc_co_u32_e32 v78, vcc, v78, v80, vcc
	v_cmp_ge_f32_e32 vcc, v9, v77
	s_and_b64 vcc, vcc, s[14:15]
	v_cmp_lt_f32_e64 s[14:15], v2, v76
	v_addc_co_u32_e32 v79, vcc, v79, v81, vcc
	v_cmp_ge_f32_e32 vcc, v2, v76
	s_nop 1
	v_cndmask_b32_e64 v80, 0, 1, vcc
	v_cmp_ge_f32_e32 vcc, v2, v77
	s_and_b64 s[14:15], vcc, s[14:15]
	v_cmp_ge_f32_e32 vcc, v3, v76
	v_cndmask_b32_e64 v81, 0, 1, s[14:15]
	v_cmp_lt_f32_e64 s[14:15], v3, v76
	v_addc_co_u32_e32 v78, vcc, v78, v80, vcc
	v_cmp_ge_f32_e32 vcc, v3, v77
	s_and_b64 vcc, vcc, s[14:15]
	v_cmp_lt_f32_e64 s[14:15], v4, v76
	v_addc_co_u32_e32 v79, vcc, v79, v81, vcc
	v_cmp_ge_f32_e32 vcc, v4, v76
	s_nop 1
	v_cndmask_b32_e64 v80, 0, 1, vcc
	v_cmp_ge_f32_e32 vcc, v4, v77
	s_and_b64 s[14:15], vcc, s[14:15]
	v_cmp_ge_f32_e32 vcc, v5, v76
	v_cndmask_b32_e64 v81, 0, 1, s[14:15]
	v_cmp_lt_f32_e64 s[14:15], v5, v76
	v_addc_co_u32_e32 v78, vcc, v78, v80, vcc
	v_cmp_ge_f32_e32 vcc, v5, v77
	s_and_b64 vcc, vcc, s[14:15]
	v_mov_b32_e32 v80, 0
	v_addc_co_u32_e32 v79, vcc, v79, v81, vcc
	v_lshl_or_b32 v78, v79, 8, v78
	v_mov_b32_e32 v79, 0
	v_mov_b32_e32 v81, 0
	v_mov_b32_dpp v80, v78 quad_perm:[1,1,1,1] row_mask:0xf bank_mask:0xf
	v_mov_b32_dpp v79, v78 quad_perm:[0,0,0,0] row_mask:0xf bank_mask:0xf
	v_mov_b32_dpp v81, v78 quad_perm:[2,2,2,2] row_mask:0xf bank_mask:0xf
	v_mov_b32_dpp v82, v78 quad_perm:[3,3,3,3] row_mask:0xf bank_mask:0xf
	v_add_u32_e32 v78, v80, v79
	v_add3_u32 v82, v78, v81, v82
; template <int CTRL> __device__ __forceinline__ int dpp_i(int x) { return __builtin_amdgcn_update_dpp(0, x, CTRL, 0xf, 0xf, false); }
; __device__ __forceinline__ void peer_select(const float* S, const int row, const int lane, LAS float* sv, LAS int* si, LAS float* fvL, LAS int* eL, int& e0o, int& e1o, float& g0o, float& g1o) {
;     ...
;             const int pk = cA | (cB << 8);
;             const int q0 = dpp_i<0x00>(pk), q1 = dpp_i<0x55>(pk), q2 = dpp_i<0xAA>(pk), q3 = dpp_i<0xFF>(pk);
;             const int tot = q0 + q1 + q2 + q3, pre = (qtr > 0 ? q0 : 0) + (qtr > 1 ? q1 : 0) + (qtr > 2 ? q2 : 0);
;             int pA = pre & 255, pB = (tot & 255) + (pre >> 8);
;             asm volatile("" : "+v"(lo), "+v"(hi));
; #pragma unroll
;             for (int j = 0; j < 32; ++j) {
;                 const bool isA = x[j] >= hi, isB = !isA && x[j] >= lo;
;                 const int slot = isA ? pA : pB;
;                 if ((isA || isB) && slot < 16) { sv[grp * 16 + slot] = x[j]; si[grp * 16 + slot] = qtr * 32 + j; }
;                 pA += isA ? 1 : 0; pB += isB ? 1 : 0;
	v_cndmask_b32_e64 v78, v79, 0, s[0:1]
	v_cndmask_b32_e64 v79, 0, v80, s[4:5]
	v_cndmask_b32_e64 v80, 0, v81, s[6:7]
	v_add3_u32 v79, v79, v78, v80
	v_and_b32_e32 v78, 0xff, v79
	v_ashrrev_i32_e32 v79, 8, v79
	v_add_u32_sdwa v79, v82, v79 dst_sel:DWORD dst_unused:UNUSED_PAD src0_sel:BYTE_0 src1_sel:DWORD
	s_nop 0
	v_cmp_ge_f32_e32 vcc, v30, v76
	v_cmp_ge_f32_e64 s[14:15], v30, v77
	s_or_b64 s[18:19], vcc, s[14:15]
	v_cndmask_b32_e32 v80, v79, v78, vcc
	v_cmp_gt_i32_e64 s[16:17], 16, v80
	s_and_b64 s[18:19], s[18:19], s[16:17]
	s_and_saveexec_b64 s[16:17], s[18:19]
	v_add_u32_e32 v80, v80, v38
	v_lshl_add_u32 v80, v80, 2, s22
	ds_write2st64_b32 v80, v30, v1 offset1:4
	s_or_b64 exec, exec, s[16:17]
	s_xor_b64 s[16:17], vcc, -1
	s_and_b64 s[14:15], s[16:17], s[14:15]
	v_cndmask_b32_e64 v80, 0, 1, s[14:15]
	v_cndmask_b32_e64 v30, 0, 1, vcc
	v_add_u32_e32 v30, v78, v30
	v_add_u32_e32 v78, v79, v80
	v_cmp_ge_f32_e32 vcc, v31, v76
	v_cmp_ge_f32_e64 s[14:15], v31, v77
	s_or_b64 s[18:19], vcc, s[14:15]
	v_cndmask_b32_e32 v79, v78, v30, vcc
	v_cmp_gt_i32_e64 s[16:17], 16, v79
	s_and_b64 s[18:19], s[18:19], s[16:17]
	s_and_saveexec_b64 s[16:17], s[18:19]
	v_add_u32_e32 v79, v79, v38
	v_lshl_add_u32 v79, v79, 2, s22
	ds_write2st64_b32 v79, v31, v39 offset1:4
	s_or_b64 exec, exec, s[16:17]
	s_xor_b64 s[16:17], vcc, -1
	s_and_b64 s[14:15], s[16:17], s[14:15]
	v_cndmask_b32_e64 v31, 0, 1, s[14:15]
	v_cndmask_b32_e64 v79, 0, 1, vcc
	v_add_u32_e32 v30, v30, v79
	v_add_u32_e32 v31, v78, v31
	v_cmp_ge_f32_e32 vcc, v32, v76
	v_cmp_ge_f32_e64 s[14:15], v32, v77
	s_or_b64 s[18:19], vcc, s[14:15]
	v_cndmask_b32_e32 v78, v31, v30, vcc
	v_cmp_gt_i32_e64 s[16:17], 16, v78
	s_and_b64 s[18:19], s[18:19], s[16:17]
	s_and_saveexec_b64 s[16:17], s[18:19]
	v_add_u32_e32 v78, v78, v38
	v_lshl_add_u32 v78, v78, 2, s22
	ds_write2st64_b32 v78, v32, v40 offset1:4
	s_or_b64 exec, exec, s[16:17]
	s_xor_b64 s[16:17], vcc, -1
	s_and_b64 s[14:15], s[16:17], s[14:15]
	v_cndmask_b32_e64 v32, 0, 1, s[14:15]
	v_cndmask_b32_e64 v78, 0, 1, vcc
	v_add_u32_e32 v30, v30, v78
	v_add_u32_e32 v31, v31, v32
	v_cmp_ge_f32_e32 vcc, v33, v76
	v_cmp_ge_f32_e64 s[14:15], v33, v77
	s_or_b64 s[18:19], vcc, s[14:15]
	v_cndmask_b32_e32 v32, v31, v30, vcc
	v_cmp_gt_i32_e64 s[16:17], 16, v32
	s_and_b64 s[18:19], s[18:19], s[16:17]
	s_and_saveexec_b64 s[16:17], s[18:19]
	v_add_u32_e32 v32, v32, v38
	v_lshl_add_u32 v32, v32, 2, s22
	ds_write2st64_b32 v32, v33, v41 offset1:4
	s_or_b64 exec, exec, s[16:17]
	s_xor_b64 s[16:17], vcc, -1
	s_and_b64 s[14:15], s[16:17], s[14:15]
	v_cndmask_b32_e64 v32, 0, 1, s[14:15]
	v_cndmask_b32_e64 v33, 0, 1, vcc
	v_add_u32_e32 v30, v30, v33
	v_add_u32_e32 v31, v31, v32
	v_cmp_ge_f32_e32 vcc, v26, v76
	v_cmp_ge_f32_e64 s[14:15], v26, v77
	s_or_b64 s[18:19], vcc, s[14:15]
	v_cndmask_b32_e32 v32, v31, v30, vcc
	v_cmp_gt_i32_e64 s[16:17], 16, v32
	s_and_b64 s[18:19], s[18:19], s[16:17]
	s_and_saveexec_b64 s[16:17], s[18:19]
	v_add_u32_e32 v32, v32, v38
	v_lshl_add_u32 v32, v32, 2, s22
	ds_write2st64_b32 v32, v26, v42 offset1:4
	s_or_b64 exec, exec, s[16:17]
	s_xor_b64 s[16:17], vcc, -1
	s_and_b64 s[14:15], s[16:17], s[14:15]
	v_cndmask_b32_e64 v32, 0, 1, s[14:15]
	v_cndmask_b32_e64 v26, 0, 1, vcc
	v_add_u32_e32 v26, v30, v26
	v_add_u32_e32 v30, v31, v32
	v_cmp_ge_f32_e32 vcc, v27, v76
	v_cmp_ge_f32_e64 s[14:15], v27, v77
	s_or_b64 s[18:19], vcc, s[14:15]
	v_cndmask_b32_e32 v31, v30, v26, vcc
	v_cmp_gt_i32_e64 s[16:17], 16, v31
	s_and_b64 s[18:19], s[18:19], s[16:17]
	s_and_saveexec_b64 s[16:17], s[18:19]
	v_add_u32_e32 v31, v31, v38
	v_lshl_add_u32 v31, v31, 2, s22
	ds_write2st64_b32 v31, v27, v43 offset1:4
	s_or_b64 exec, exec, s[16:17]
	s_xor_b64 s[16:17], vcc, -1
	s_and_b64 s[14:15], s[16:17], s[14:15]
	v_cndmask_b32_e64 v27, 0, 1, s[14:15]
	v_cndmask_b32_e64 v31, 0, 1, vcc
	v_add_u32_e32 v26, v26, v31
	v_add_u32_e32 v27, v30, v27
	v_cmp_ge_f32_e32 vcc, v28, v76
	v_cmp_ge_f32_e64 s[14:15], v28, v77
	s_or_b64 s[18:19], vcc, s[14:15]
	v_cndmask_b32_e32 v30, v27, v26, vcc
	v_cmp_gt_i32_e64 s[16:17], 16, v30
	s_and_b64 s[18:19], s[18:19], s[16:17]
	s_and_saveexec_b64 s[16:17], s[18:19]
	v_add_u32_e32 v30, v30, v38
	v_lshl_add_u32 v30, v30, 2, s22
	ds_write2st64_b32 v30, v28, v44 offset1:4
	s_or_b64 exec, exec, s[16:17]
	s_xor_b64 s[16:17], vcc, -1
	s_and_b64 s[14:15], s[16:17], s[14:15]
	v_cndmask_b32_e64 v28, 0, 1, s[14:15]
	v_cndmask_b32_e64 v30, 0, 1, vcc
	v_add_u32_e32 v26, v26, v30
	v_add_u32_e32 v27, v27, v28
	v_cmp_ge_f32_e32 vcc, v29, v76
	v_cmp_ge_f32_e64 s[14:15], v29, v77
	s_or_b64 s[18:19], vcc, s[14:15]
	v_cndmask_b32_e32 v28, v27, v26, vcc
	v_cmp_gt_i32_e64 s[16:17], 16, v28
	s_and_b64 s[18:19], s[18:19], s[16:17]
	s_and_saveexec_b64 s[16:17], s[18:19]
	v_add_u32_e32 v28, v28, v38
	v_lshl_add_u32 v28, v28, 2, s22
	ds_write2st64_b32 v28, v29, v45 offset1:4
	s_or_b64 exec, exec, s[16:17]
	s_xor_b64 s[16:17], vcc, -1
	s_and_b64 s[14:15], s[16:17], s[14:15]
	v_cndmask_b32_e64 v28, 0, 1, s[14:15]
	v_cndmask_b32_e64 v29, 0, 1, vcc
	v_add_u32_e32 v26, v26, v29
	v_add_u32_e32 v27, v27, v28
	v_cmp_ge_f32_e32 vcc, v22, v76
	v_cmp_ge_f32_e64 s[14:15], v22, v77
	s_or_b64 s[18:19], vcc, s[14:15]
	v_cndmask_b32_e32 v28, v27, v26, vcc
	v_cmp_gt_i32_e64 s[16:17], 16, v28
	s_and_b64 s[18:19], s[18:19], s[16:17]
	s_and_saveexec_b64 s[16:17], s[18:19]
	v_add_u32_e32 v28, v28, v38
	v_lshl_add_u32 v28, v28, 2, s22
	ds_write2st64_b32 v28, v22, v46 offset1:4
	s_or_b64 exec, exec, s[16:17]
	s_xor_b64 s[16:17], vcc, -1
	s_and_b64 s[14:15], s[16:17], s[14:15]
	v_cndmask_b32_e64 v28, 0, 1, s[14:15]
	v_cndmask_b32_e64 v22, 0, 1, vcc
	v_add_u32_e32 v22, v26, v22
	v_add_u32_e32 v26, v27, v28
; __device__ __forceinline__ void peer_select(const float* S, const int row, const int lane, LAS float* sv, LAS int* si, LAS float* fvL, LAS int* eL, int& e0o, int& e1o, float& g0o, float& g1o) {
;     ...
; #pragma unroll
;             for (int j = 0; j < 32; ++j) {
;                 const bool isA = x[j] >= hi, isB = !isA && x[j] >= lo;
;                 const int slot = isA ? pA : pB;
;                 if ((isA || isB) && slot < 16) { sv[grp * 16 + slot] = x[j]; si[grp * 16 + slot] = qtr * 32 + j; }
;                 pA += isA ? 1 : 0; pB += isB ? 1 : 0;
;             }
	v_cmp_ge_f32_e32 vcc, v23, v76
	v_cmp_ge_f32_e64 s[14:15], v23, v77
	s_or_b64 s[18:19], vcc, s[14:15]
	v_cndmask_b32_e32 v27, v26, v22, vcc
	v_cmp_gt_i32_e64 s[16:17], 16, v27
	s_and_b64 s[18:19], s[18:19], s[16:17]
	s_and_saveexec_b64 s[16:17], s[18:19]
	v_add_u32_e32 v27, v27, v38
	v_lshl_add_u32 v27, v27, 2, s22
	ds_write2st64_b32 v27, v23, v47 offset1:4
	s_or_b64 exec, exec, s[16:17]
	s_xor_b64 s[16:17], vcc, -1
	s_and_b64 s[14:15], s[16:17], s[14:15]
	v_cndmask_b32_e64 v23, 0, 1, s[14:15]
	v_cndmask_b32_e64 v27, 0, 1, vcc
	v_add_u32_e32 v22, v22, v27
	v_add_u32_e32 v23, v26, v23
	v_cmp_ge_f32_e32 vcc, v24, v76
	v_cmp_ge_f32_e64 s[14:15], v24, v77
	s_or_b64 s[18:19], vcc, s[14:15]
	v_cndmask_b32_e32 v26, v23, v22, vcc
	v_cmp_gt_i32_e64 s[16:17], 16, v26
	s_and_b64 s[18:19], s[18:19], s[16:17]
	s_and_saveexec_b64 s[16:17], s[18:19]
	v_add_u32_e32 v26, v26, v38
	v_lshl_add_u32 v26, v26, 2, s22
	ds_write2st64_b32 v26, v24, v48 offset1:4
	s_or_b64 exec, exec, s[16:17]
	s_xor_b64 s[16:17], vcc, -1
	s_and_b64 s[14:15], s[16:17], s[14:15]
	v_cndmask_b32_e64 v24, 0, 1, s[14:15]
	v_cndmask_b32_e64 v26, 0, 1, vcc
	v_add_u32_e32 v22, v22, v26
	v_add_u32_e32 v23, v23, v24
	v_cmp_ge_f32_e32 vcc, v25, v76
	v_cmp_ge_f32_e64 s[14:15], v25, v77
	s_or_b64 s[18:19], vcc, s[14:15]
	v_cndmask_b32_e32 v24, v23, v22, vcc
	v_cmp_gt_i32_e64 s[16:17], 16, v24
	s_and_b64 s[18:19], s[18:19], s[16:17]
	s_and_saveexec_b64 s[16:17], s[18:19]
	v_add_u32_e32 v24, v24, v38
	v_lshl_add_u32 v24, v24, 2, s22
	ds_write2st64_b32 v24, v25, v49 offset1:4
	s_or_b64 exec, exec, s[16:17]
	s_xor_b64 s[16:17], vcc, -1
	s_and_b64 s[14:15], s[16:17], s[14:15]
	v_cndmask_b32_e64 v24, 0, 1, s[14:15]
	v_cndmask_b32_e64 v25, 0, 1, vcc
	v_add_u32_e32 v22, v22, v25
	v_add_u32_e32 v23, v23, v24
	v_cmp_ge_f32_e32 vcc, v18, v76
	v_cmp_ge_f32_e64 s[14:15], v18, v77
	s_or_b64 s[18:19], vcc, s[14:15]
	v_cndmask_b32_e32 v24, v23, v22, vcc
	v_cmp_gt_i32_e64 s[16:17], 16, v24
	s_and_b64 s[18:19], s[18:19], s[16:17]
	s_and_saveexec_b64 s[16:17], s[18:19]
	v_add_u32_e32 v24, v24, v38
	v_lshl_add_u32 v24, v24, 2, s22
	ds_write2st64_b32 v24, v18, v50 offset1:4
	s_or_b64 exec, exec, s[16:17]
	s_xor_b64 s[16:17], vcc, -1
	s_and_b64 s[14:15], s[16:17], s[14:15]
	v_cndmask_b32_e64 v24, 0, 1, s[14:15]
	v_cndmask_b32_e64 v18, 0, 1, vcc
	v_add_u32_e32 v18, v22, v18
	v_add_u32_e32 v22, v23, v24
	v_cmp_ge_f32_e32 vcc, v19, v76
	v_cmp_ge_f32_e64 s[14:15], v19, v77
	s_or_b64 s[18:19], vcc, s[14:15]
	v_cndmask_b32_e32 v23, v22, v18, vcc
	v_cmp_gt_i32_e64 s[16:17], 16, v23
	s_and_b64 s[18:19], s[18:19], s[16:17]
	s_and_saveexec_b64 s[16:17], s[18:19]
	v_add_u32_e32 v23, v23, v38
	v_lshl_add_u32 v23, v23, 2, s22
	ds_write2st64_b32 v23, v19, v51 offset1:4
	s_or_b64 exec, exec, s[16:17]
	s_xor_b64 s[16:17], vcc, -1
	s_and_b64 s[14:15], s[16:17], s[14:15]
	v_cndmask_b32_e64 v19, 0, 1, s[14:15]
	v_cndmask_b32_e64 v23, 0, 1, vcc
	v_add_u32_e32 v18, v18, v23
	v_add_u32_e32 v19, v22, v19
	v_cmp_ge_f32_e32 vcc, v20, v76
	v_cmp_ge_f32_e64 s[14:15], v20, v77
	s_or_b64 s[18:19], vcc, s[14:15]
	v_cndmask_b32_e32 v22, v19, v18, vcc
	v_cmp_gt_i32_e64 s[16:17], 16, v22
	s_and_b64 s[18:19], s[18:19], s[16:17]
	s_and_saveexec_b64 s[16:17], s[18:19]
	v_add_u32_e32 v22, v22, v38
	v_lshl_add_u32 v22, v22, 2, s22
	ds_write2st64_b32 v22, v20, v52 offset1:4
	s_or_b64 exec, exec, s[16:17]
	s_xor_b64 s[16:17], vcc, -1
	s_and_b64 s[14:15], s[16:17], s[14:15]
	v_cndmask_b32_e64 v20, 0, 1, s[14:15]
	v_cndmask_b32_e64 v22, 0, 1, vcc
	v_add_u32_e32 v18, v18, v22
	v_add_u32_e32 v19, v19, v20
	v_cmp_ge_f32_e32 vcc, v21, v76
	v_cmp_ge_f32_e64 s[14:15], v21, v77
	s_or_b64 s[18:19], vcc, s[14:15]
	v_cndmask_b32_e32 v20, v19, v18, vcc
	v_cmp_gt_i32_e64 s[16:17], 16, v20
	s_and_b64 s[18:19], s[18:19], s[16:17]
	s_and_saveexec_b64 s[16:17], s[18:19]
	v_add_u32_e32 v20, v20, v38
	v_lshl_add_u32 v20, v20, 2, s22
	ds_write2st64_b32 v20, v21, v53 offset1:4
	s_or_b64 exec, exec, s[16:17]
	s_xor_b64 s[16:17], vcc, -1
	s_and_b64 s[14:15], s[16:17], s[14:15]
	v_cndmask_b32_e64 v20, 0, 1, s[14:15]
	v_cndmask_b32_e64 v21, 0, 1, vcc
	v_add_u32_e32 v18, v18, v21
	v_add_u32_e32 v19, v19, v20
	v_cmp_ge_f32_e32 vcc, v14, v76
	v_cmp_ge_f32_e64 s[14:15], v14, v77
	s_or_b64 s[18:19], vcc, s[14:15]
	v_cndmask_b32_e32 v20, v19, v18, vcc
	v_cmp_gt_i32_e64 s[16:17], 16, v20
	s_and_b64 s[18:19], s[18:19], s[16:17]
	s_and_saveexec_b64 s[16:17], s[18:19]
	v_add_u32_e32 v20, v20, v38
	v_lshl_add_u32 v20, v20, 2, s22
	ds_write2st64_b32 v20, v14, v54 offset1:4
	s_or_b64 exec, exec, s[16:17]
	s_xor_b64 s[16:17], vcc, -1
	s_and_b64 s[14:15], s[16:17], s[14:15]
	v_cndmask_b32_e64 v20, 0, 1, s[14:15]
	v_cndmask_b32_e64 v14, 0, 1, vcc
	v_add_u32_e32 v14, v18, v14
	v_add_u32_e32 v18, v19, v20
	v_cmp_ge_f32_e32 vcc, v15, v76
	v_cmp_ge_f32_e64 s[14:15], v15, v77
	s_or_b64 s[18:19], vcc, s[14:15]
	v_cndmask_b32_e32 v19, v18, v14, vcc
	v_cmp_gt_i32_e64 s[16:17], 16, v19
	s_and_b64 s[18:19], s[18:19], s[16:17]
	s_and_saveexec_b64 s[16:17], s[18:19]
	v_add_u32_e32 v19, v19, v38
	v_lshl_add_u32 v19, v19, 2, s22
	ds_write2st64_b32 v19, v15, v55 offset1:4
	s_or_b64 exec, exec, s[16:17]
	s_xor_b64 s[16:17], vcc, -1
	s_and_b64 s[14:15], s[16:17], s[14:15]
	v_cndmask_b32_e64 v15, 0, 1, s[14:15]
	v_cndmask_b32_e64 v19, 0, 1, vcc
	v_add_u32_e32 v14, v14, v19
	v_add_u32_e32 v15, v18, v15
	v_cmp_ge_f32_e32 vcc, v16, v76
	v_cmp_ge_f32_e64 s[14:15], v16, v77
	s_or_b64 s[18:19], vcc, s[14:15]
	v_cndmask_b32_e32 v18, v15, v14, vcc
	v_cmp_gt_i32_e64 s[16:17], 16, v18
	s_and_b64 s[18:19], s[18:19], s[16:17]
	s_and_saveexec_b64 s[16:17], s[18:19]
	v_add_u32_e32 v18, v18, v38
	v_lshl_add_u32 v18, v18, 2, s22
; __device__ __forceinline__ void peer_select(const float* S, const int row, const int lane, LAS float* sv, LAS int* si, LAS float* fvL, LAS int* eL, int& e0o, int& e1o, float& g0o, float& g1o) {
;     ...
; #pragma unroll
;             for (int j = 0; j < 32; ++j) {
;                 const bool isA = x[j] >= hi, isB = !isA && x[j] >= lo;
;                 const int slot = isA ? pA : pB;
;                 if ((isA || isB) && slot < 16) { sv[grp * 16 + slot] = x[j]; si[grp * 16 + slot] = qtr * 32 + j; }
;                 pA += isA ? 1 : 0; pB += isB ? 1 : 0;
;             }
	ds_write2st64_b32 v18, v16, v56 offset1:4
	s_or_b64 exec, exec, s[16:17]
	s_xor_b64 s[16:17], vcc, -1
	s_and_b64 s[14:15], s[16:17], s[14:15]
	v_cndmask_b32_e64 v16, 0, 1, s[14:15]
	v_cndmask_b32_e64 v18, 0, 1, vcc
	v_add_u32_e32 v14, v14, v18
	v_add_u32_e32 v15, v15, v16
	v_cmp_ge_f32_e32 vcc, v17, v76
	v_cmp_ge_f32_e64 s[14:15], v17, v77
	s_or_b64 s[18:19], vcc, s[14:15]
	v_cndmask_b32_e32 v16, v15, v14, vcc
	v_cmp_gt_i32_e64 s[16:17], 16, v16
	s_and_b64 s[18:19], s[18:19], s[16:17]
	s_and_saveexec_b64 s[16:17], s[18:19]
	v_add_u32_e32 v16, v16, v38
	v_lshl_add_u32 v16, v16, 2, s22
	ds_write2st64_b32 v16, v17, v57 offset1:4
	s_or_b64 exec, exec, s[16:17]
	s_xor_b64 s[16:17], vcc, -1
	s_and_b64 s[14:15], s[16:17], s[14:15]
	v_cndmask_b32_e64 v16, 0, 1, s[14:15]
	v_cndmask_b32_e64 v17, 0, 1, vcc
	v_add_u32_e32 v14, v14, v17
	v_add_u32_e32 v15, v15, v16
	v_cmp_ge_f32_e32 vcc, v10, v76
	v_cmp_ge_f32_e64 s[14:15], v10, v77
	s_or_b64 s[18:19], vcc, s[14:15]
	v_cndmask_b32_e32 v16, v15, v14, vcc
	v_cmp_gt_i32_e64 s[16:17], 16, v16
	s_and_b64 s[18:19], s[18:19], s[16:17]
	s_and_saveexec_b64 s[16:17], s[18:19]
	v_add_u32_e32 v16, v16, v38
	v_lshl_add_u32 v16, v16, 2, s22
	ds_write2st64_b32 v16, v10, v58 offset1:4
	s_or_b64 exec, exec, s[16:17]
	s_xor_b64 s[16:17], vcc, -1
	s_and_b64 s[14:15], s[16:17], s[14:15]
	v_cndmask_b32_e64 v16, 0, 1, s[14:15]
	v_cndmask_b32_e64 v10, 0, 1, vcc
	v_add_u32_e32 v10, v14, v10
	v_add_u32_e32 v14, v15, v16
	v_cmp_ge_f32_e32 vcc, v11, v76
	v_cmp_ge_f32_e64 s[14:15], v11, v77
	s_or_b64 s[18:19], vcc, s[14:15]
	v_cndmask_b32_e32 v15, v14, v10, vcc
	v_cmp_gt_i32_e64 s[16:17], 16, v15
	s_and_b64 s[18:19], s[18:19], s[16:17]
	s_and_saveexec_b64 s[16:17], s[18:19]
	v_add_u32_e32 v15, v15, v38
	v_lshl_add_u32 v15, v15, 2, s22
	ds_write2st64_b32 v15, v11, v59 offset1:4
	s_or_b64 exec, exec, s[16:17]
	s_xor_b64 s[16:17], vcc, -1
	s_and_b64 s[14:15], s[16:17], s[14:15]
	v_cndmask_b32_e64 v11, 0, 1, s[14:15]
	v_cndmask_b32_e64 v15, 0, 1, vcc
	v_add_u32_e32 v10, v10, v15
	v_add_u32_e32 v11, v14, v11
	v_cmp_ge_f32_e32 vcc, v12, v76
	v_cmp_ge_f32_e64 s[14:15], v12, v77
	s_or_b64 s[18:19], vcc, s[14:15]
	v_cndmask_b32_e32 v14, v11, v10, vcc
	v_cmp_gt_i32_e64 s[16:17], 16, v14
	s_and_b64 s[18:19], s[18:19], s[16:17]
	s_and_saveexec_b64 s[16:17], s[18:19]
	v_add_u32_e32 v14, v14, v38
	v_lshl_add_u32 v14, v14, 2, s22
	ds_write2st64_b32 v14, v12, v60 offset1:4
	s_or_b64 exec, exec, s[16:17]
	s_xor_b64 s[16:17], vcc, -1
	s_and_b64 s[14:15], s[16:17], s[14:15]
	v_cndmask_b32_e64 v12, 0, 1, s[14:15]
	v_cndmask_b32_e64 v14, 0, 1, vcc
	v_add_u32_e32 v10, v10, v14
	v_add_u32_e32 v11, v11, v12
	v_cmp_ge_f32_e32 vcc, v13, v76
	v_cmp_ge_f32_e64 s[14:15], v13, v77
	s_or_b64 s[18:19], vcc, s[14:15]
	v_cndmask_b32_e32 v12, v11, v10, vcc
	v_cmp_gt_i32_e64 s[16:17], 16, v12
	s_and_b64 s[18:19], s[18:19], s[16:17]
	s_and_saveexec_b64 s[16:17], s[18:19]
	v_add_u32_e32 v12, v12, v38
	v_lshl_add_u32 v12, v12, 2, s22
	ds_write2st64_b32 v12, v13, v61 offset1:4
	s_or_b64 exec, exec, s[16:17]
	s_xor_b64 s[16:17], vcc, -1
	s_and_b64 s[14:15], s[16:17], s[14:15]
	v_cndmask_b32_e64 v12, 0, 1, s[14:15]
	v_cndmask_b32_e64 v13, 0, 1, vcc
	v_add_u32_e32 v10, v10, v13
	v_add_u32_e32 v11, v11, v12
	v_cmp_ge_f32_e32 vcc, v6, v76
	v_cmp_ge_f32_e64 s[14:15], v6, v77
	s_or_b64 s[18:19], vcc, s[14:15]
	v_cndmask_b32_e32 v12, v11, v10, vcc
	v_cmp_gt_i32_e64 s[16:17], 16, v12
	s_and_b64 s[18:19], s[18:19], s[16:17]
	s_and_saveexec_b64 s[16:17], s[18:19]
	v_add_u32_e32 v12, v12, v38
	v_lshl_add_u32 v12, v12, 2, s22
	ds_write2st64_b32 v12, v6, v62 offset1:4
	s_or_b64 exec, exec, s[16:17]
	s_xor_b64 s[16:17], vcc, -1
	s_and_b64 s[14:15], s[16:17], s[14:15]
	v_cndmask_b32_e64 v12, 0, 1, s[14:15]
	v_cndmask_b32_e64 v6, 0, 1, vcc
	v_add_u32_e32 v6, v10, v6
	v_add_u32_e32 v10, v11, v12
	v_cmp_ge_f32_e32 vcc, v7, v76
	v_cmp_ge_f32_e64 s[14:15], v7, v77
	s_or_b64 s[18:19], vcc, s[14:15]
	v_cndmask_b32_e32 v11, v10, v6, vcc
	v_cmp_gt_i32_e64 s[16:17], 16, v11
	s_and_b64 s[18:19], s[18:19], s[16:17]
	s_and_saveexec_b64 s[16:17], s[18:19]
	v_add_u32_e32 v11, v11, v38
	v_lshl_add_u32 v11, v11, 2, s22
	ds_write2st64_b32 v11, v7, v63 offset1:4
	s_or_b64 exec, exec, s[16:17]
	s_xor_b64 s[16:17], vcc, -1
	s_and_b64 s[14:15], s[16:17], s[14:15]
	v_cndmask_b32_e64 v7, 0, 1, s[14:15]
	v_cndmask_b32_e64 v11, 0, 1, vcc
	v_add_u32_e32 v6, v6, v11
	v_add_u32_e32 v7, v10, v7
	v_cmp_ge_f32_e32 vcc, v8, v76
	v_cmp_ge_f32_e64 s[14:15], v8, v77
	s_or_b64 s[18:19], vcc, s[14:15]
	v_cndmask_b32_e32 v10, v7, v6, vcc
	v_cmp_gt_i32_e64 s[16:17], 16, v10
	s_and_b64 s[18:19], s[18:19], s[16:17]
	s_and_saveexec_b64 s[16:17], s[18:19]
	v_add_u32_e32 v10, v10, v38
	v_lshl_add_u32 v10, v10, 2, s22
	ds_write2st64_b32 v10, v8, v64 offset1:4
	s_or_b64 exec, exec, s[16:17]
	s_xor_b64 s[16:17], vcc, -1
	s_and_b64 s[14:15], s[16:17], s[14:15]
	v_cndmask_b32_e64 v8, 0, 1, s[14:15]
	v_cndmask_b32_e64 v10, 0, 1, vcc
	v_add_u32_e32 v6, v6, v10
	v_add_u32_e32 v7, v7, v8
	v_cmp_ge_f32_e32 vcc, v9, v76
	v_cmp_ge_f32_e64 s[14:15], v9, v77
	s_or_b64 s[18:19], vcc, s[14:15]
	v_cndmask_b32_e32 v8, v7, v6, vcc
	v_cmp_gt_i32_e64 s[16:17], 16, v8
	s_and_b64 s[18:19], s[18:19], s[16:17]
	s_and_saveexec_b64 s[16:17], s[18:19]
	v_add_u32_e32 v8, v8, v38
	v_lshl_add_u32 v8, v8, 2, s22
	ds_write2st64_b32 v8, v9, v65 offset1:4
	s_or_b64 exec, exec, s[16:17]
	s_xor_b64 s[16:17], vcc, -1
	s_and_b64 s[14:15], s[16:17], s[14:15]
	v_cndmask_b32_e64 v8, 0, 1, s[14:15]
	v_cndmask_b32_e64 v9, 0, 1, vcc
	v_add_u32_e32 v6, v6, v9
	v_add_u32_e32 v7, v7, v8
	v_cmp_ge_f32_e32 vcc, v2, v76
	v_cmp_ge_f32_e64 s[14:15], v2, v77
; #define LAS __attribute__((address_space(3)))
; __device__ __forceinline__ void peer_select(const float* S, const int row, const int lane, LAS float* sv, LAS int* si, LAS float* fvL, LAS int* eL, int& e0o, int& e1o, float& g0o, float& g1o) {
;     ...
; #pragma unroll
;             for (int j = 0; j < 32; ++j) {
;                 const bool isA = x[j] >= hi, isB = !isA && x[j] >= lo;
;                 const int slot = isA ? pA : pB;
;                 if ((isA || isB) && slot < 16) { sv[grp * 16 + slot] = x[j]; si[grp * 16 + slot] = qtr * 32 + j; }
;                 pA += isA ? 1 : 0; pB += isB ? 1 : 0;
;             }
;         }
;         __builtin_amdgcn_wave_barrier();
;         {
;             const int hd = lane >> 3, sub = lane & 7;
;             const float s1a = sv[(2 * hd) * 16 + 2 * sub], s1b = sv[(2 * hd) * 16 + 2 * sub + 1];
;             const int i1a = si[(2 * hd) * 16 + 2 * sub], i1b = si[(2 * hd) * 16 + 2 * sub + 1];
;             float c[32]; int i2[16];
; #pragma unroll
;             for (int k = 0; k < 4; ++k) {
;                 const f32x4 v = *(const LAS f32x4*)(sv + (2 * hd + 1) * 16 + 4 * k);
;                 const u32x4 iv = *(const LAS u32x4*)(si + (2 * hd + 1) * 16 + 4 * k);
; #pragma unroll
;                 for (int e = 0; e < 4; ++e) { c[4 * k + e] = s1a + v[e]; c[16 + 4 * k + e] = s1b + v[e]; }
;                 i2[4 * k] = (int)iv.x; i2[4 * k + 1] = (int)iv.y; i2[4 * k + 2] = (int)iv.z; i2[4 * k + 3] = (int)iv.w;
;             }
;             float lo, hi;
;             bisect16<8>(c, lo, hi);
	s_or_b64 s[18:19], vcc, s[14:15]
	v_cndmask_b32_e32 v8, v7, v6, vcc
	v_cmp_gt_i32_e64 s[16:17], 16, v8
	s_and_b64 s[18:19], s[18:19], s[16:17]
	s_and_saveexec_b64 s[16:17], s[18:19]
	v_add_u32_e32 v8, v8, v38
	v_lshl_add_u32 v8, v8, 2, s22
	ds_write2st64_b32 v8, v2, v66 offset1:4
	s_or_b64 exec, exec, s[16:17]
	s_xor_b64 s[16:17], vcc, -1
	s_and_b64 s[14:15], s[16:17], s[14:15]
	v_cndmask_b32_e64 v8, 0, 1, s[14:15]
	v_cndmask_b32_e64 v2, 0, 1, vcc
	v_add_u32_e32 v2, v6, v2
	v_add_u32_e32 v6, v7, v8
	v_cmp_ge_f32_e32 vcc, v3, v76
	v_cmp_ge_f32_e64 s[14:15], v3, v77
	s_or_b64 s[18:19], vcc, s[14:15]
	v_cndmask_b32_e32 v7, v6, v2, vcc
	v_cmp_gt_i32_e64 s[16:17], 16, v7
	s_and_b64 s[18:19], s[18:19], s[16:17]
	s_and_saveexec_b64 s[16:17], s[18:19]
	v_add_u32_e32 v7, v7, v38
	v_lshl_add_u32 v7, v7, 2, s22
	ds_write2st64_b32 v7, v3, v67 offset1:4
	s_or_b64 exec, exec, s[16:17]
	s_xor_b64 s[16:17], vcc, -1
	s_and_b64 s[14:15], s[16:17], s[14:15]
	v_cndmask_b32_e64 v3, 0, 1, s[14:15]
	v_cndmask_b32_e64 v7, 0, 1, vcc
	v_add_u32_e32 v2, v2, v7
	v_add_u32_e32 v3, v6, v3
	v_cmp_ge_f32_e32 vcc, v4, v76
	v_cmp_ge_f32_e64 s[14:15], v4, v77
	s_or_b64 s[18:19], vcc, s[14:15]
	v_cndmask_b32_e32 v6, v3, v2, vcc
	v_cmp_gt_i32_e64 s[16:17], 16, v6
	s_and_b64 s[18:19], s[18:19], s[16:17]
	s_and_saveexec_b64 s[16:17], s[18:19]
	v_add_u32_e32 v6, v6, v38
	v_lshl_add_u32 v6, v6, 2, s22
	ds_write2st64_b32 v6, v4, v68 offset1:4
	s_or_b64 exec, exec, s[16:17]
	s_xor_b64 s[16:17], vcc, -1
	s_and_b64 s[14:15], s[16:17], s[14:15]
	v_cndmask_b32_e64 v4, 0, 1, s[14:15]
	v_cndmask_b32_e64 v6, 0, 1, vcc
	v_add_u32_e32 v2, v2, v6
	v_add_u32_e32 v3, v3, v4
	v_cmp_ge_f32_e64 s[14:15], v5, v76
	v_cmp_ge_f32_e32 vcc, v5, v77
	s_nop 0
	v_cndmask_b32_e64 v2, v3, v2, s[14:15]
	s_or_b64 s[14:15], s[14:15], vcc
	v_cmp_gt_i32_e32 vcc, 16, v2
	s_and_b64 s[16:17], s[14:15], vcc
	s_and_saveexec_b64 s[14:15], s[16:17]
	v_add_u32_e32 v2, v2, v38
	v_lshl_add_u32 v2, v2, 2, s22
	ds_write2st64_b32 v2, v5, v69 offset1:4
	s_or_b64 exec, exec, s[14:15]
	ds_read2st64_b64 v[2:5], v70 offset1:2
	ds_read_b128 v[22:25], v71 offset:64
	ds_read_b128 v[26:29], v71 offset:80
	ds_read_b128 v[96:99], v71 offset:96
	ds_read_b128 v[100:103], v71 offset:112
	ds_read_b128 v[18:21], v71 offset:1088
	ds_read_b128 v[14:17], v71 offset:1104
	ds_read_b128 v[10:13], v71 offset:1120
	ds_read_b128 v[6:9], v71 offset:1136
	s_waitcnt lgkmcnt(7)
	v_add_f32_e32 v95, v2, v22
	v_add_f32_e32 v94, v2, v23
	v_add_f32_e32 v80, v3, v23
	s_waitcnt lgkmcnt(4)
	v_pk_mov_b32 v[22:23], v[102:103], v[22:23] op_sel:[1,0]
	v_add_f32_e32 v93, v2, v24
	v_add_f32_e32 v79, v3, v24
	v_add_f32_e32 v92, v2, v25
	v_add_f32_e32 v78, v3, v25
	v_add_f32_e32 v91, v2, v26
	v_add_f32_e32 v77, v3, v26
	v_add_f32_e32 v90, v2, v27
	v_add_f32_e32 v76, v3, v27
	v_add_f32_e32 v89, v2, v28
	v_add_f32_e32 v33, v3, v28
	v_add_f32_e32 v88, v2, v29
	v_add_f32_e32 v32, v3, v29
	v_add_f32_e32 v87, v2, v96
	v_add_f32_e32 v31, v3, v96
	v_add_f32_e32 v86, v2, v97
	v_add_f32_e32 v30, v3, v97
	v_add_f32_e32 v85, v2, v98
	v_add_f32_e32 v29, v3, v98
	v_add_f32_e32 v84, v2, v99
	v_add_f32_e32 v28, v3, v99
	v_add_f32_e32 v83, v2, v100
	v_add_f32_e32 v26, v3, v100
	v_add_f32_e32 v82, v2, v101
	v_add_f32_e32 v25, v3, v101
	v_add_f32_e32 v81, v2, v102
	v_add_f32_e32 v24, v3, v102
	v_pk_add_f32 v[22:23], v[2:3], v[22:23]
	v_add_f32_e32 v2, v3, v103
	v_max_f32_e32 v3, v95, v94
	v_max3_f32 v3, v3, v93, v92
	v_max3_f32 v3, v3, v91, v90
	v_max3_f32 v3, v3, v89, v88
	v_max3_f32 v3, v3, v87, v86
	v_max3_f32 v3, v3, v85, v84
	v_max3_f32 v3, v3, v83, v82
	v_max3_f32 v3, v3, v81, v22
	v_max3_f32 v3, v3, v23, v80
	v_min_f32_e32 v27, v95, v94
	v_max3_f32 v3, v3, v79, v78
	v_min3_f32 v27, v27, v93, v92
	v_max3_f32 v3, v3, v77, v76
	v_min3_f32 v27, v27, v91, v90
	v_max3_f32 v3, v3, v33, v32
	v_min3_f32 v27, v27, v89, v88
	v_max3_f32 v3, v3, v31, v30
	v_min3_f32 v27, v27, v87, v86
	v_max3_f32 v3, v3, v29, v28
	v_min3_f32 v27, v27, v85, v84
	v_max3_f32 v3, v3, v26, v25
	v_min3_f32 v27, v27, v83, v82
	v_max3_f32 v3, v3, v24, v2
	v_mov_b32_e32 v96, 0
	v_min3_f32 v27, v27, v81, v22
	v_min3_f32 v27, v27, v23, v80
	v_mov_b32_dpp v96, v3 quad_perm:[1,0,3,2] row_mask:0xf bank_mask:0xf
	v_max_f32_e32 v96, v96, v96
	v_min3_f32 v27, v27, v79, v78
	v_max_f32_e32 v3, v3, v96
	v_mov_b32_e32 v96, 0
	v_min3_f32 v27, v27, v77, v76
	v_min3_f32 v27, v27, v33, v32
	v_mov_b32_dpp v96, v3 quad_perm:[2,3,0,1] row_mask:0xf bank_mask:0xf
	v_max_f32_e32 v96, v96, v96
	v_min3_f32 v27, v27, v31, v30
	v_max_f32_e32 v3, v3, v96
	v_mov_b32_e32 v96, 0
	v_min3_f32 v27, v27, v29, v28
	v_min3_f32 v27, v27, v26, v25
	v_mov_b32_dpp v96, v3 row_half_mirror row_mask:0xf bank_mask:0xf
	v_max_f32_e32 v96, v96, v96
	v_min3_f32 v27, v27, v24, v2
	v_max_f32_e32 v3, v3, v96
	v_mov_b32_e32 v96, 0
	s_mov_b64 s[34:35], 0
	s_nop 0
	v_mov_b32_dpp v96, v27 quad_perm:[1,0,3,2] row_mask:0xf bank_mask:0xf
	v_max_f32_e32 v96, v96, v96
	v_min_f32_e32 v27, v27, v96
	v_mov_b32_e32 v96, 0
	s_nop 1
	v_mov_b32_dpp v96, v27 quad_perm:[2,3,0,1] row_mask:0xf bank_mask:0xf
	v_max_f32_e32 v96, v96, v96
	v_min_f32_e32 v27, v27, v96
	v_mov_b32_e32 v96, 0
	s_nop 1
	v_mov_b32_dpp v96, v27 row_half_mirror row_mask:0xf bank_mask:0xf
	v_max_f32_e32 v96, v96, v96
	v_min_f32_e32 v27, v27, v96
	v_mov_b32_e32 v96, 47
; template <int GS> __device__ __forceinline__ int grp_sum_i(int v) { v += dpp_i<0xB1>(v); v += dpp_i<0x4E>(v); if (GS == 8) v += dpp_i<0x141>(v); return v; }
; template <int GS> __device__ __forceinline__ void bisect16(const float (&x)[32], float& lo, float& hi) {
;     ...
;     for (int it = 0; it < 48; ++it) {
;         const float t = 0.5f * (lo + hi);
;         const bool conv = !(t > lo && t < hi);
;         int cnt = 0;
; #pragma unroll
;         for (int j = 0; j < 32; ++j) cnt += (x[j] >= t) ? 1 : 0;
;         cnt = grp_sum_i<GS>(cnt);
;         const bool upd = !done && !conv, ex = cnt == 16, gt = cnt > 16;
;         const float nlo = (ex || gt) ? t : lo, nhi = (ex || !gt) ? t : hi;
;         lo = upd ? nlo : lo; hi = upd ? nhi : hi;
;         done = done || conv || ex;
;         if (__ballot(!done) == 0ull) break;
;     }
; __device__ __forceinline__ void peer_select(const float* S, const int row, const int lane, LAS float* sv, LAS int* si, LAS float* fvL, LAS int* eL, int& e0o, int& e1o, float& g0o, float& g1o) {
;     ...
;             int cA = 0, cB = 0;
; #pragma unroll
;             for (int j = 0; j < 32; ++j) { cA += (c[j] >= hi) ? 1 : 0; cB += (c[j] >= lo && c[j] < hi) ? 1 : 0; }
.LBB0_1445:
	v_add_f32_e32 v97, v27, v3
	v_mul_f32_e32 v97, 0.5, v97
	v_cmp_nlt_f32_e64 s[14:15], v97, v3
	v_cmp_ngt_f32_e64 s[16:17], v97, v27
	v_subrev_co_u32_e32 v96, vcc, 1, v96
	v_mov_b32_e32 v98, 0
	s_or_b64 s[36:37], s[16:17], s[14:15]
	v_cmp_ge_f32_e64 s[16:17], v94, v97
	v_cmp_ge_f32_e64 s[18:19], v95, v97
	v_cmp_ge_f32_e64 s[14:15], v93, v97
	v_addc_co_u32_e64 v98, s[16:17], 0, v98, s[16:17]
	v_cmp_ge_f32_e64 s[16:17], v91, v97
	v_addc_co_u32_e64 v98, s[18:19], 0, v98, s[18:19]
	v_cmp_ge_f32_e64 s[18:19], v89, v97
	v_addc_co_u32_e64 v98, s[14:15], 0, v98, s[14:15]
	v_cmp_ge_f32_e64 s[14:15], v87, v97
	v_addc_co_u32_e64 v98, s[16:17], 0, v98, s[16:17]
	v_cmp_ge_f32_e64 s[16:17], v85, v97
	v_addc_co_u32_e64 v98, s[18:19], 0, v98, s[18:19]
	v_cmp_ge_f32_e64 s[18:19], v83, v97
	v_addc_co_u32_e64 v98, s[14:15], 0, v98, s[14:15]
	v_cmp_ge_f32_e64 s[14:15], v81, v97
	v_addc_co_u32_e64 v98, s[16:17], 0, v98, s[16:17]
	v_cmp_ge_f32_e64 s[16:17], v23, v97
	v_addc_co_u32_e64 v98, s[18:19], 0, v98, s[18:19]
	v_cmp_ge_f32_e64 s[18:19], v79, v97
	v_addc_co_u32_e64 v98, s[14:15], 0, v98, s[14:15]
	v_cmp_ge_f32_e64 s[14:15], v77, v97
	v_addc_co_u32_e64 v98, s[16:17], 0, v98, s[16:17]
	v_cmp_ge_f32_e64 s[16:17], v33, v97
	v_addc_co_u32_e64 v98, s[18:19], 0, v98, s[18:19]
	v_cmp_ge_f32_e64 s[18:19], v31, v97
	v_addc_co_u32_e64 v98, s[14:15], 0, v98, s[14:15]
	v_cmp_ge_f32_e64 s[14:15], v29, v97
	v_addc_co_u32_e64 v98, s[16:17], 0, v98, s[16:17]
	v_cmp_ge_f32_e64 s[16:17], v26, v97
	v_addc_co_u32_e64 v98, s[18:19], 0, v98, s[18:19]
	v_cmp_ge_f32_e64 s[18:19], v24, v97
	v_addc_co_u32_e64 v98, s[14:15], 0, v98, s[14:15]
	v_cmp_ge_f32_e64 s[14:15], v92, v97
	v_addc_co_u32_e64 v98, s[16:17], 0, v98, s[16:17]
	v_cmp_ge_f32_e64 s[16:17], v90, v97
	v_addc_co_u32_e64 v98, s[18:19], 0, v98, s[18:19]
	v_cmp_ge_f32_e64 s[18:19], v88, v97
	v_addc_co_u32_e64 v98, s[14:15], 0, v98, s[14:15]
	v_cmp_ge_f32_e64 s[14:15], v86, v97
	v_addc_co_u32_e64 v98, s[16:17], 0, v98, s[16:17]
	v_cmp_ge_f32_e64 s[16:17], v84, v97
	v_addc_co_u32_e64 v98, s[18:19], 0, v98, s[18:19]
	v_cmp_ge_f32_e64 s[18:19], v82, v97
	v_addc_co_u32_e64 v98, s[14:15], 0, v98, s[14:15]
	v_cmp_ge_f32_e64 s[14:15], v22, v97
	v_addc_co_u32_e64 v98, s[16:17], 0, v98, s[16:17]
	v_cmp_ge_f32_e64 s[16:17], v80, v97
	v_addc_co_u32_e64 v98, s[18:19], 0, v98, s[18:19]
	v_cmp_ge_f32_e64 s[18:19], v78, v97
	v_addc_co_u32_e64 v98, s[14:15], 0, v98, s[14:15]
	v_cmp_ge_f32_e64 s[14:15], v76, v97
	v_addc_co_u32_e64 v98, s[16:17], 0, v98, s[16:17]
	v_cmp_ge_f32_e64 s[16:17], v32, v97
	v_addc_co_u32_e64 v98, s[18:19], 0, v98, s[18:19]
	v_cmp_ge_f32_e64 s[18:19], v30, v97
	v_addc_co_u32_e64 v98, s[14:15], 0, v98, s[14:15]
	v_cmp_ge_f32_e64 s[14:15], v28, v97
	v_addc_co_u32_e64 v98, s[16:17], 0, v98, s[16:17]
	v_cmp_ge_f32_e64 s[16:17], v25, v97
	v_addc_co_u32_e64 v98, s[18:19], 0, v98, s[18:19]
	v_cmp_ge_f32_e64 s[18:19], v2, v97
	v_addc_co_u32_e64 v98, s[14:15], 0, v98, s[14:15]
	v_addc_co_u32_e64 v98, s[16:17], 0, v98, s[16:17]
	v_addc_co_u32_e64 v98, s[18:19], 0, v98, s[18:19]
	s_nop 1
	v_add_u32_dpp v98, v98, v98 quad_perm:[1,0,3,2] row_mask:0xf bank_mask:0xf bound_ctrl:1
	s_nop 1
	v_add_u32_dpp v98, v98, v98 quad_perm:[2,3,0,1] row_mask:0xf bank_mask:0xf bound_ctrl:1
	s_nop 1
	v_add_u32_dpp v98, v98, v98 row_half_mirror row_mask:0xf bank_mask:0xf bound_ctrl:1
	v_cmp_lt_i32_e64 s[18:19], 15, v98
	v_cmp_eq_u32_e64 s[14:15], 16, v98
	v_cmp_lt_i32_e64 s[16:17], 16, v98
	v_cndmask_b32_e64 v98, v27, v97, s[18:19]
	s_or_b64 s[18:19], s[34:35], s[36:37]
	s_or_b64 s[34:35], s[18:19], s[14:15]
	s_xor_b64 s[14:15], s[34:35], -1
	v_cndmask_b32_e64 v27, v98, v27, s[18:19]
	v_cndmask_b32_e64 v98, 0, 1, s[14:15]
	s_or_b64 s[16:17], s[18:19], s[16:17]
	v_cmp_ne_u32_e64 s[14:15], 0, v98
	s_cmp_eq_u64 s[14:15], 0
	s_cselect_b64 s[14:15], -1, 0
	s_or_b64 s[14:15], s[14:15], vcc
	s_andn2_b64 vcc, exec, s[14:15]
	v_cndmask_b32_e64 v3, v97, v3, s[16:17]
	s_cbranch_vccnz .LBB0_1445
	v_cmp_ge_f32_e64 s[16:17], v94, v3
	v_cmp_lt_f32_e64 s[18:19], v94, v3
	v_cmp_ge_f32_e32 vcc, v95, v27
	v_cndmask_b32_e64 v96, 0, 1, s[16:17]
	v_cmp_ge_f32_e64 s[16:17], v95, v3
	v_cmp_lt_f32_e64 s[14:15], v95, v3
	s_and_b64 vcc, vcc, s[14:15]
	v_addc_co_u32_e64 v96, s[16:17], 0, v96, s[16:17]
	v_cmp_ge_f32_e64 s[16:17], v94, v27
	s_and_b64 s[16:17], s[16:17], s[18:19]
	v_cmp_lt_f32_e64 s[14:15], v93, v3
	v_cndmask_b32_e64 v97, 0, 1, s[16:17]
	v_addc_co_u32_e32 v97, vcc, 0, v97, vcc
	v_cmp_ge_f32_e32 vcc, v93, v3
	v_cmp_lt_f32_e64 s[16:17], v22, v3
	s_nop 0
	v_cndmask_b32_e64 v98, 0, 1, vcc
	v_cmp_ge_f32_e32 vcc, v93, v27
	s_and_b64 s[14:15], vcc, s[14:15]
	v_cmp_ge_f32_e32 vcc, v92, v3
	v_cndmask_b32_e64 v99, 0, 1, s[14:15]
	v_cmp_lt_f32_e64 s[14:15], v92, v3
	v_addc_co_u32_e32 v96, vcc, v96, v98, vcc
	v_cmp_ge_f32_e32 vcc, v92, v27
	s_and_b64 vcc, vcc, s[14:15]
	v_cmp_lt_f32_e64 s[14:15], v91, v3
	v_addc_co_u32_e32 v97, vcc, v97, v99, vcc
	v_cmp_ge_f32_e32 vcc, v91, v3
	s_nop 1
	v_cndmask_b32_e64 v98, 0, 1, vcc
	v_cmp_ge_f32_e32 vcc, v91, v27
	s_and_b64 s[14:15], vcc, s[14:15]
	v_cmp_ge_f32_e32 vcc, v90, v3
	v_cndmask_b32_e64 v99, 0, 1, s[14:15]
	v_cmp_lt_f32_e64 s[14:15], v90, v3
	v_addc_co_u32_e32 v96, vcc, v96, v98, vcc
	v_cmp_ge_f32_e32 vcc, v90, v27
	s_and_b64 vcc, vcc, s[14:15]
	v_cmp_lt_f32_e64 s[14:15], v89, v3
	v_addc_co_u32_e32 v97, vcc, v97, v99, vcc
	v_cmp_ge_f32_e32 vcc, v89, v3
	s_nop 1
	v_cndmask_b32_e64 v98, 0, 1, vcc
	v_cmp_ge_f32_e32 vcc, v89, v27
	s_and_b64 s[14:15], vcc, s[14:15]
	v_cmp_ge_f32_e32 vcc, v88, v3
	v_cndmask_b32_e64 v99, 0, 1, s[14:15]
	v_cmp_lt_f32_e64 s[14:15], v88, v3
	v_addc_co_u32_e32 v96, vcc, v96, v98, vcc
; __device__ __forceinline__ void peer_select(const float* S, const int row, const int lane, LAS float* sv, LAS int* si, LAS float* fvL, LAS int* eL, int& e0o, int& e1o, float& g0o, float& g1o) {
;     ...
;             int cA = 0, cB = 0;
; #pragma unroll
;             for (int j = 0; j < 32; ++j) { cA += (c[j] >= hi) ? 1 : 0; cB += (c[j] >= lo && c[j] < hi) ? 1 : 0; }
;             const int pk = cA | (cB << 8);
;             int inc = pk;
;             { int t = __shfl_up(inc, 1, 8); if (sub >= 1) inc += t; t = __shfl_up(inc, 2, 8); if (sub >= 2) inc += t; t = __shfl_up(inc, 4, 8); if (sub >= 4) inc += t; }
;             const int tot = __shfl(inc, 7, 8), pre = inc - pk;
;             int pA = pre & 255, pB = (tot & 255) + (pre >> 8);
	v_cmp_ge_f32_e32 vcc, v88, v27
	s_and_b64 vcc, vcc, s[14:15]
	v_cmp_lt_f32_e64 s[14:15], v87, v3
	v_addc_co_u32_e32 v97, vcc, v97, v99, vcc
	v_cmp_ge_f32_e32 vcc, v87, v3
	s_nop 1
	v_cndmask_b32_e64 v98, 0, 1, vcc
	v_cmp_ge_f32_e32 vcc, v87, v27
	s_and_b64 s[14:15], vcc, s[14:15]
	v_cmp_ge_f32_e32 vcc, v86, v3
	v_cndmask_b32_e64 v99, 0, 1, s[14:15]
	v_cmp_lt_f32_e64 s[14:15], v86, v3
	v_addc_co_u32_e32 v96, vcc, v96, v98, vcc
	v_cmp_ge_f32_e32 vcc, v86, v27
	s_and_b64 vcc, vcc, s[14:15]
	v_cmp_lt_f32_e64 s[14:15], v85, v3
	v_addc_co_u32_e32 v97, vcc, v97, v99, vcc
	v_cmp_ge_f32_e32 vcc, v85, v3
	s_nop 1
	v_cndmask_b32_e64 v98, 0, 1, vcc
	v_cmp_ge_f32_e32 vcc, v85, v27
	s_and_b64 s[14:15], vcc, s[14:15]
	v_cmp_ge_f32_e32 vcc, v84, v3
	v_cndmask_b32_e64 v99, 0, 1, s[14:15]
	v_cmp_lt_f32_e64 s[14:15], v84, v3
	v_addc_co_u32_e32 v96, vcc, v96, v98, vcc
	v_cmp_ge_f32_e32 vcc, v84, v27
	s_and_b64 vcc, vcc, s[14:15]
	v_cmp_lt_f32_e64 s[14:15], v83, v3
	v_addc_co_u32_e32 v97, vcc, v97, v99, vcc
	v_cmp_ge_f32_e32 vcc, v83, v3
	s_nop 1
	v_cndmask_b32_e64 v98, 0, 1, vcc
	v_cmp_ge_f32_e32 vcc, v83, v27
	s_and_b64 s[14:15], vcc, s[14:15]
	v_cmp_ge_f32_e32 vcc, v82, v3
	v_cndmask_b32_e64 v99, 0, 1, s[14:15]
	v_cmp_lt_f32_e64 s[14:15], v82, v3
	v_addc_co_u32_e32 v96, vcc, v96, v98, vcc
	v_cmp_ge_f32_e32 vcc, v82, v27
	s_and_b64 vcc, vcc, s[14:15]
	v_cmp_lt_f32_e64 s[14:15], v81, v3
	v_addc_co_u32_e32 v97, vcc, v97, v99, vcc
	v_cmp_ge_f32_e32 vcc, v81, v3
	s_nop 1
	v_cndmask_b32_e64 v98, 0, 1, vcc
	v_cmp_ge_f32_e32 vcc, v81, v27
	s_and_b64 s[14:15], vcc, s[14:15]
	v_cmp_ge_f32_e32 vcc, v22, v3
	v_cndmask_b32_e64 v99, 0, 1, s[14:15]
	v_cmp_lt_f32_e64 s[14:15], v23, v3
	v_addc_co_u32_e32 v96, vcc, v96, v98, vcc
	v_cmp_ge_f32_e32 vcc, v22, v27
	s_and_b64 vcc, vcc, s[16:17]
	s_nop 0
	v_addc_co_u32_e32 v97, vcc, v97, v99, vcc
	v_cmp_ge_f32_e32 vcc, v23, v3
	s_nop 1
	v_cndmask_b32_e64 v98, 0, 1, vcc
	v_cmp_ge_f32_e32 vcc, v23, v27
	s_and_b64 s[14:15], vcc, s[14:15]
	v_cmp_ge_f32_e32 vcc, v80, v3
	v_cndmask_b32_e64 v99, 0, 1, s[14:15]
	v_cmp_lt_f32_e64 s[14:15], v80, v3
	v_addc_co_u32_e32 v96, vcc, v96, v98, vcc
	v_cmp_ge_f32_e32 vcc, v80, v27
	s_and_b64 vcc, vcc, s[14:15]
	v_cmp_lt_f32_e64 s[14:15], v79, v3
	v_addc_co_u32_e32 v97, vcc, v97, v99, vcc
	v_cmp_ge_f32_e32 vcc, v79, v3
	s_nop 1
	v_cndmask_b32_e64 v98, 0, 1, vcc
	v_cmp_ge_f32_e32 vcc, v79, v27
	s_and_b64 s[14:15], vcc, s[14:15]
	v_cmp_ge_f32_e32 vcc, v78, v3
	v_cndmask_b32_e64 v99, 0, 1, s[14:15]
	v_cmp_lt_f32_e64 s[14:15], v78, v3
	v_addc_co_u32_e32 v96, vcc, v96, v98, vcc
	v_cmp_ge_f32_e32 vcc, v78, v27
	s_and_b64 vcc, vcc, s[14:15]
	v_cmp_lt_f32_e64 s[14:15], v77, v3
	v_addc_co_u32_e32 v97, vcc, v97, v99, vcc
	v_cmp_ge_f32_e32 vcc, v77, v3
	s_nop 1
	v_cndmask_b32_e64 v98, 0, 1, vcc
	v_cmp_ge_f32_e32 vcc, v77, v27
	s_and_b64 s[14:15], vcc, s[14:15]
	v_cmp_ge_f32_e32 vcc, v76, v3
	v_cndmask_b32_e64 v99, 0, 1, s[14:15]
	v_cmp_lt_f32_e64 s[14:15], v76, v3
	v_addc_co_u32_e32 v96, vcc, v96, v98, vcc
	v_cmp_ge_f32_e32 vcc, v76, v27
	s_and_b64 vcc, vcc, s[14:15]
	v_cmp_lt_f32_e64 s[14:15], v33, v3
	v_addc_co_u32_e32 v97, vcc, v97, v99, vcc
	v_cmp_ge_f32_e32 vcc, v33, v3
	s_nop 1
	v_cndmask_b32_e64 v98, 0, 1, vcc
	v_cmp_ge_f32_e32 vcc, v33, v27
	s_and_b64 s[14:15], vcc, s[14:15]
	v_cmp_ge_f32_e32 vcc, v32, v3
	v_cndmask_b32_e64 v99, 0, 1, s[14:15]
	v_cmp_lt_f32_e64 s[14:15], v32, v3
	v_addc_co_u32_e32 v96, vcc, v96, v98, vcc
	v_cmp_ge_f32_e32 vcc, v32, v27
	s_and_b64 vcc, vcc, s[14:15]
	v_cmp_lt_f32_e64 s[14:15], v31, v3
	v_addc_co_u32_e32 v97, vcc, v97, v99, vcc
	v_cmp_ge_f32_e32 vcc, v31, v3
	s_nop 1
	v_cndmask_b32_e64 v98, 0, 1, vcc
	v_cmp_ge_f32_e32 vcc, v31, v27
	s_and_b64 s[14:15], vcc, s[14:15]
	v_cmp_ge_f32_e32 vcc, v30, v3
	v_cndmask_b32_e64 v99, 0, 1, s[14:15]
	v_cmp_lt_f32_e64 s[14:15], v30, v3
	v_addc_co_u32_e32 v96, vcc, v96, v98, vcc
	v_cmp_ge_f32_e32 vcc, v30, v27
	s_and_b64 vcc, vcc, s[14:15]
	v_cmp_lt_f32_e64 s[14:15], v29, v3
	v_addc_co_u32_e32 v97, vcc, v97, v99, vcc
	v_cmp_ge_f32_e32 vcc, v29, v3
	s_nop 1
	v_cndmask_b32_e64 v98, 0, 1, vcc
	v_cmp_ge_f32_e32 vcc, v29, v27
	s_and_b64 s[14:15], vcc, s[14:15]
	v_cmp_ge_f32_e32 vcc, v28, v3
	v_cndmask_b32_e64 v99, 0, 1, s[14:15]
	v_cmp_lt_f32_e64 s[14:15], v28, v3
	v_addc_co_u32_e32 v96, vcc, v96, v98, vcc
	v_cmp_ge_f32_e32 vcc, v28, v27
	s_and_b64 vcc, vcc, s[14:15]
	v_cmp_lt_f32_e64 s[14:15], v26, v3
	v_addc_co_u32_e32 v97, vcc, v97, v99, vcc
	v_cmp_ge_f32_e32 vcc, v26, v3
	s_nop 1
	v_cndmask_b32_e64 v98, 0, 1, vcc
	v_cmp_ge_f32_e32 vcc, v26, v27
	s_and_b64 s[14:15], vcc, s[14:15]
	v_cmp_ge_f32_e32 vcc, v25, v3
	v_cndmask_b32_e64 v99, 0, 1, s[14:15]
	v_cmp_lt_f32_e64 s[14:15], v25, v3
	v_addc_co_u32_e32 v96, vcc, v96, v98, vcc
	v_cmp_ge_f32_e32 vcc, v25, v27
	s_and_b64 vcc, vcc, s[14:15]
	v_cmp_lt_f32_e64 s[14:15], v24, v3
	v_addc_co_u32_e32 v97, vcc, v97, v99, vcc
	v_cmp_ge_f32_e32 vcc, v24, v3
	s_nop 1
	v_cndmask_b32_e64 v98, 0, 1, vcc
	v_cmp_ge_f32_e32 vcc, v24, v27
	s_and_b64 s[14:15], vcc, s[14:15]
	v_cmp_ge_f32_e32 vcc, v2, v3
	v_cndmask_b32_e64 v99, 0, 1, s[14:15]
	v_cmp_lt_f32_e64 s[14:15], v2, v3
	v_addc_co_u32_e32 v96, vcc, v96, v98, vcc
	v_cmp_ge_f32_e32 vcc, v2, v27
	s_and_b64 vcc, vcc, s[14:15]
	v_and_b32_e32 v98, 0x78, v74
	v_addc_co_u32_e32 v97, vcc, v97, v99, vcc
	v_lshl_or_b32 v96, v97, 8, v96
	v_add_u32_e32 v97, -1, v74
	v_cmp_lt_i32_e32 vcc, v97, v98
	v_add_u32_e32 v99, -2, v74
	s_nop 0
	v_cndmask_b32_e32 v97, v97, v74, vcc
	v_lshlrev_b32_e32 v97, 2, v97
	ds_bpermute_b32 v97, v97, v96
	v_cmp_lt_i32_e32 vcc, v99, v98
	v_cmp_ge_f32_e64 s[14:15], v95, v27
	s_waitcnt lgkmcnt(0)
; __device__ __forceinline__ void peer_select(const float* S, const int row, const int lane, LAS float* sv, LAS int* si, LAS float* fvL, LAS int* eL, int& e0o, int& e1o, float& g0o, float& g1o) {
;     ...
;             { int t = __shfl_up(inc, 1, 8); if (sub >= 1) inc += t; t = __shfl_up(inc, 2, 8); if (sub >= 2) inc += t; t = __shfl_up(inc, 4, 8); if (sub >= 4) inc += t; }
;             const int tot = __shfl(inc, 7, 8), pre = inc - pk;
;             int pA = pre & 255, pB = (tot & 255) + (pre >> 8);
;             asm volatile("" : "+v"(lo), "+v"(hi));
; #pragma unroll
;             for (int j = 0; j < 32; ++j) {
;                 const bool isA = c[j] >= hi, isB = !isA && c[j] >= lo;
;                 const int slot = isA ? pA : pB;
;                 if ((isA || isB) && slot < 16) { fvL[hd * 16 + slot] = c[j]; eL[hd * 16 + slot] = (j < 16 ? i1a : i1b) * 128 + i2[j & 15]; }
	v_cndmask_b32_e64 v97, v97, 0, s[8:9]
	v_cndmask_b32_e32 v99, v99, v74, vcc
	v_add_u32_e32 v97, v97, v96
	v_lshlrev_b32_e32 v99, 2, v99
	ds_bpermute_b32 v99, v99, v97
	s_waitcnt lgkmcnt(0)
	v_cndmask_b32_e64 v99, 0, v99, s[10:11]
	v_add_u32_e32 v97, v97, v99
	v_add_u32_e32 v99, -4, v74
	v_cmp_lt_i32_e32 vcc, v99, v98
	s_nop 1
	v_cndmask_b32_e32 v98, v99, v74, vcc
	v_lshlrev_b32_e32 v98, 2, v98
	ds_bpermute_b32 v98, v98, v97
	v_cmp_ge_f32_e32 vcc, v95, v3
	s_or_b64 s[18:19], vcc, s[14:15]
	s_waitcnt lgkmcnt(0)
	v_cndmask_b32_e64 v98, 0, v98, s[12:13]
	v_add_u32_e32 v97, v97, v98
	ds_bpermute_b32 v98, v75, v97
	v_sub_u32_e32 v97, v97, v96
	v_and_b32_e32 v96, 0xff, v97
	v_ashrrev_i32_e32 v97, 8, v97
	s_waitcnt lgkmcnt(0)
	v_add_u32_sdwa v97, v97, v98 dst_sel:DWORD dst_unused:UNUSED_PAD src0_sel:DWORD src1_sel:BYTE_0
	v_cndmask_b32_e32 v98, v97, v96, vcc
	v_cmp_gt_i32_e64 s[16:17], 16, v98
	s_and_b64 s[18:19], s[18:19], s[16:17]
	s_and_saveexec_b64 s[16:17], s[18:19]
	v_add_u32_e32 v98, v98, v72
	v_lshl_add_u32 v98, v98, 2, s22
	v_lshl_add_u32 v99, v4, 7, v18
	ds_write2st64_b32 v98, v95, v99 offset0:8 offset1:10
	s_or_b64 exec, exec, s[16:17]
	s_xor_b64 s[16:17], vcc, -1
	s_and_b64 s[14:15], s[16:17], s[14:15]
	v_cndmask_b32_e64 v98, 0, 1, s[14:15]
	v_cndmask_b32_e64 v95, 0, 1, vcc
	v_add_u32_e32 v95, v96, v95
	v_add_u32_e32 v96, v97, v98
	v_cmp_ge_f32_e32 vcc, v94, v3
	v_cmp_ge_f32_e64 s[14:15], v94, v27
	s_or_b64 s[18:19], vcc, s[14:15]
	v_cndmask_b32_e32 v97, v96, v95, vcc
	v_cmp_gt_i32_e64 s[16:17], 16, v97
	s_and_b64 s[18:19], s[18:19], s[16:17]
	s_and_saveexec_b64 s[16:17], s[18:19]
	v_add_u32_e32 v97, v97, v72
	v_lshl_add_u32 v97, v97, 2, s22
	v_lshl_add_u32 v98, v4, 7, v19
	ds_write2st64_b32 v97, v94, v98 offset0:8 offset1:10
	s_or_b64 exec, exec, s[16:17]
	s_xor_b64 s[16:17], vcc, -1
	s_and_b64 s[14:15], s[16:17], s[14:15]
	v_cndmask_b32_e64 v97, 0, 1, s[14:15]
	v_cndmask_b32_e64 v94, 0, 1, vcc
	v_add_u32_e32 v94, v95, v94
	v_add_u32_e32 v95, v96, v97
	v_cmp_ge_f32_e32 vcc, v93, v3
	v_cmp_ge_f32_e64 s[14:15], v93, v27
	s_or_b64 s[18:19], vcc, s[14:15]
	v_cndmask_b32_e32 v96, v95, v94, vcc
	v_cmp_gt_i32_e64 s[16:17], 16, v96
	s_and_b64 s[18:19], s[18:19], s[16:17]
	s_and_saveexec_b64 s[16:17], s[18:19]
	v_add_u32_e32 v96, v96, v72
	v_lshl_add_u32 v96, v96, 2, s22
	v_lshl_add_u32 v97, v4, 7, v20
	ds_write2st64_b32 v96, v93, v97 offset0:8 offset1:10
	s_or_b64 exec, exec, s[16:17]
	s_xor_b64 s[16:17], vcc, -1
	s_and_b64 s[14:15], s[16:17], s[14:15]
	v_cndmask_b32_e64 v96, 0, 1, s[14:15]
	v_cndmask_b32_e64 v93, 0, 1, vcc
	v_add_u32_e32 v93, v94, v93
	v_add_u32_e32 v94, v95, v96
	v_cmp_ge_f32_e32 vcc, v92, v3
	v_cmp_ge_f32_e64 s[14:15], v92, v27
	s_or_b64 s[18:19], vcc, s[14:15]
	v_cndmask_b32_e32 v95, v94, v93, vcc
	v_cmp_gt_i32_e64 s[16:17], 16, v95
	s_and_b64 s[18:19], s[18:19], s[16:17]
	s_and_saveexec_b64 s[16:17], s[18:19]
	v_add_u32_e32 v95, v95, v72
	v_lshl_add_u32 v95, v95, 2, s22
	v_lshl_add_u32 v96, v4, 7, v21
	ds_write2st64_b32 v95, v92, v96 offset0:8 offset1:10
	s_or_b64 exec, exec, s[16:17]
	s_xor_b64 s[16:17], vcc, -1
	s_and_b64 s[14:15], s[16:17], s[14:15]
	v_cndmask_b32_e64 v95, 0, 1, s[14:15]
	v_cndmask_b32_e64 v92, 0, 1, vcc
	v_add_u32_e32 v92, v93, v92
	v_add_u32_e32 v93, v94, v95
	v_cmp_ge_f32_e32 vcc, v91, v3
	v_cmp_ge_f32_e64 s[14:15], v91, v27
	s_or_b64 s[18:19], vcc, s[14:15]
	v_cndmask_b32_e32 v94, v93, v92, vcc
	v_cmp_gt_i32_e64 s[16:17], 16, v94
	s_and_b64 s[18:19], s[18:19], s[16:17]
	s_and_saveexec_b64 s[16:17], s[18:19]
	v_add_u32_e32 v94, v94, v72
	v_lshl_add_u32 v94, v94, 2, s22
	v_lshl_add_u32 v95, v4, 7, v14
	ds_write2st64_b32 v94, v91, v95 offset0:8 offset1:10
	s_or_b64 exec, exec, s[16:17]
	s_xor_b64 s[16:17], vcc, -1
	s_and_b64 s[14:15], s[16:17], s[14:15]
	v_cndmask_b32_e64 v94, 0, 1, s[14:15]
	v_cndmask_b32_e64 v91, 0, 1, vcc
	v_add_u32_e32 v91, v92, v91
	v_add_u32_e32 v92, v93, v94
	v_cmp_ge_f32_e32 vcc, v90, v3
	v_cmp_ge_f32_e64 s[14:15], v90, v27
	s_or_b64 s[18:19], vcc, s[14:15]
	v_cndmask_b32_e32 v93, v92, v91, vcc
	v_cmp_gt_i32_e64 s[16:17], 16, v93
	s_and_b64 s[18:19], s[18:19], s[16:17]
	s_and_saveexec_b64 s[16:17], s[18:19]
	v_add_u32_e32 v93, v93, v72
	v_lshl_add_u32 v93, v93, 2, s22
	v_lshl_add_u32 v94, v4, 7, v15
	ds_write2st64_b32 v93, v90, v94 offset0:8 offset1:10
	s_or_b64 exec, exec, s[16:17]
	s_xor_b64 s[16:17], vcc, -1
	s_and_b64 s[14:15], s[16:17], s[14:15]
	v_cndmask_b32_e64 v93, 0, 1, s[14:15]
	v_cndmask_b32_e64 v90, 0, 1, vcc
	v_add_u32_e32 v90, v91, v90
	v_add_u32_e32 v91, v92, v93
	v_cmp_ge_f32_e32 vcc, v89, v3
	v_cmp_ge_f32_e64 s[14:15], v89, v27
	s_or_b64 s[18:19], vcc, s[14:15]
	v_cndmask_b32_e32 v92, v91, v90, vcc
	v_cmp_gt_i32_e64 s[16:17], 16, v92
	s_and_b64 s[18:19], s[18:19], s[16:17]
	s_and_saveexec_b64 s[16:17], s[18:19]
	v_add_u32_e32 v92, v92, v72
	v_lshl_add_u32 v92, v92, 2, s22
	v_lshl_add_u32 v93, v4, 7, v16
	ds_write2st64_b32 v92, v89, v93 offset0:8 offset1:10
	s_or_b64 exec, exec, s[16:17]
	s_xor_b64 s[16:17], vcc, -1
	s_and_b64 s[14:15], s[16:17], s[14:15]
	v_cndmask_b32_e64 v92, 0, 1, s[14:15]
	v_cndmask_b32_e64 v89, 0, 1, vcc
	v_add_u32_e32 v89, v90, v89
	v_add_u32_e32 v90, v91, v92
	v_cmp_ge_f32_e32 vcc, v88, v3
	v_cmp_ge_f32_e64 s[14:15], v88, v27
	s_or_b64 s[18:19], vcc, s[14:15]
	v_cndmask_b32_e32 v91, v90, v89, vcc
	v_cmp_gt_i32_e64 s[16:17], 16, v91
	s_and_b64 s[18:19], s[18:19], s[16:17]
	s_and_saveexec_b64 s[16:17], s[18:19]
	v_add_u32_e32 v91, v91, v72
	v_lshl_add_u32 v91, v91, 2, s22
	v_lshl_add_u32 v92, v4, 7, v17
	ds_write2st64_b32 v91, v88, v92 offset0:8 offset1:10
	s_or_b64 exec, exec, s[16:17]
	s_xor_b64 s[16:17], vcc, -1
; __device__ __forceinline__ void peer_select(const float* S, const int row, const int lane, LAS float* sv, LAS int* si, LAS float* fvL, LAS int* eL, int& e0o, int& e1o, float& g0o, float& g1o) {
;     ...
; #pragma unroll
;             for (int j = 0; j < 32; ++j) {
;                 const bool isA = c[j] >= hi, isB = !isA && c[j] >= lo;
;                 const int slot = isA ? pA : pB;
;                 if ((isA || isB) && slot < 16) { fvL[hd * 16 + slot] = c[j]; eL[hd * 16 + slot] = (j < 16 ? i1a : i1b) * 128 + i2[j & 15]; }
;                 pA += isA ? 1 : 0; pB += isB ? 1 : 0;
;             }
	s_and_b64 s[14:15], s[16:17], s[14:15]
	v_cndmask_b32_e64 v91, 0, 1, s[14:15]
	v_cndmask_b32_e64 v88, 0, 1, vcc
	v_add_u32_e32 v88, v89, v88
	v_add_u32_e32 v89, v90, v91
	v_cmp_ge_f32_e32 vcc, v87, v3
	v_cmp_ge_f32_e64 s[14:15], v87, v27
	s_or_b64 s[18:19], vcc, s[14:15]
	v_cndmask_b32_e32 v90, v89, v88, vcc
	v_cmp_gt_i32_e64 s[16:17], 16, v90
	s_and_b64 s[18:19], s[18:19], s[16:17]
	s_and_saveexec_b64 s[16:17], s[18:19]
	v_add_u32_e32 v90, v90, v72
	v_lshl_add_u32 v90, v90, 2, s22
	v_lshl_add_u32 v91, v4, 7, v10
	ds_write2st64_b32 v90, v87, v91 offset0:8 offset1:10
	s_or_b64 exec, exec, s[16:17]
	s_xor_b64 s[16:17], vcc, -1
	s_and_b64 s[14:15], s[16:17], s[14:15]
	v_cndmask_b32_e64 v90, 0, 1, s[14:15]
	v_cndmask_b32_e64 v87, 0, 1, vcc
	v_add_u32_e32 v87, v88, v87
	v_add_u32_e32 v88, v89, v90
	v_cmp_ge_f32_e32 vcc, v86, v3
	v_cmp_ge_f32_e64 s[14:15], v86, v27
	s_or_b64 s[18:19], vcc, s[14:15]
	v_cndmask_b32_e32 v89, v88, v87, vcc
	v_cmp_gt_i32_e64 s[16:17], 16, v89
	s_and_b64 s[18:19], s[18:19], s[16:17]
	s_and_saveexec_b64 s[16:17], s[18:19]
	v_add_u32_e32 v89, v89, v72
	v_lshl_add_u32 v89, v89, 2, s22
	v_lshl_add_u32 v90, v4, 7, v11
	ds_write2st64_b32 v89, v86, v90 offset0:8 offset1:10
	s_or_b64 exec, exec, s[16:17]
	s_xor_b64 s[16:17], vcc, -1
	s_and_b64 s[14:15], s[16:17], s[14:15]
	v_cndmask_b32_e64 v89, 0, 1, s[14:15]
	v_cndmask_b32_e64 v86, 0, 1, vcc
	v_add_u32_e32 v86, v87, v86
	v_add_u32_e32 v87, v88, v89
	v_cmp_ge_f32_e32 vcc, v85, v3
	v_cmp_ge_f32_e64 s[14:15], v85, v27
	s_or_b64 s[18:19], vcc, s[14:15]
	v_cndmask_b32_e32 v88, v87, v86, vcc
	v_cmp_gt_i32_e64 s[16:17], 16, v88
	s_and_b64 s[18:19], s[18:19], s[16:17]
	s_and_saveexec_b64 s[16:17], s[18:19]
	v_add_u32_e32 v88, v88, v72
	v_lshl_add_u32 v88, v88, 2, s22
	v_lshl_add_u32 v89, v4, 7, v12
	ds_write2st64_b32 v88, v85, v89 offset0:8 offset1:10
	s_or_b64 exec, exec, s[16:17]
	s_xor_b64 s[16:17], vcc, -1
	s_and_b64 s[14:15], s[16:17], s[14:15]
	v_cndmask_b32_e64 v88, 0, 1, s[14:15]
	v_cndmask_b32_e64 v85, 0, 1, vcc
	v_add_u32_e32 v85, v86, v85
	v_add_u32_e32 v86, v87, v88
	v_cmp_ge_f32_e32 vcc, v84, v3
	v_cmp_ge_f32_e64 s[14:15], v84, v27
	s_or_b64 s[18:19], vcc, s[14:15]
	v_cndmask_b32_e32 v87, v86, v85, vcc
	v_cmp_gt_i32_e64 s[16:17], 16, v87
	s_and_b64 s[18:19], s[18:19], s[16:17]
	s_and_saveexec_b64 s[16:17], s[18:19]
	v_add_u32_e32 v87, v87, v72
	v_lshl_add_u32 v87, v87, 2, s22
	v_lshl_add_u32 v88, v4, 7, v13
	ds_write2st64_b32 v87, v84, v88 offset0:8 offset1:10
	s_or_b64 exec, exec, s[16:17]
	s_xor_b64 s[16:17], vcc, -1
	s_and_b64 s[14:15], s[16:17], s[14:15]
	v_cndmask_b32_e64 v87, 0, 1, s[14:15]
	v_cndmask_b32_e64 v84, 0, 1, vcc
	v_add_u32_e32 v84, v85, v84
	v_add_u32_e32 v85, v86, v87
	v_cmp_ge_f32_e32 vcc, v83, v3
	v_cmp_ge_f32_e64 s[14:15], v83, v27
	s_or_b64 s[18:19], vcc, s[14:15]
	v_cndmask_b32_e32 v86, v85, v84, vcc
	v_cmp_gt_i32_e64 s[16:17], 16, v86
	s_and_b64 s[18:19], s[18:19], s[16:17]
	s_and_saveexec_b64 s[16:17], s[18:19]
	v_add_u32_e32 v86, v86, v72
	v_lshl_add_u32 v86, v86, 2, s22
	v_lshl_add_u32 v87, v4, 7, v6
	ds_write2st64_b32 v86, v83, v87 offset0:8 offset1:10
	s_or_b64 exec, exec, s[16:17]
	s_xor_b64 s[16:17], vcc, -1
	s_and_b64 s[14:15], s[16:17], s[14:15]
	v_cndmask_b32_e64 v86, 0, 1, s[14:15]
	v_cndmask_b32_e64 v83, 0, 1, vcc
	v_add_u32_e32 v83, v84, v83
	v_add_u32_e32 v84, v85, v86
	v_cmp_ge_f32_e32 vcc, v82, v3
	v_cmp_ge_f32_e64 s[14:15], v82, v27
	s_or_b64 s[18:19], vcc, s[14:15]
	v_cndmask_b32_e32 v85, v84, v83, vcc
	v_cmp_gt_i32_e64 s[16:17], 16, v85
	s_and_b64 s[18:19], s[18:19], s[16:17]
	s_and_saveexec_b64 s[16:17], s[18:19]
	v_add_u32_e32 v85, v85, v72
	v_lshl_add_u32 v85, v85, 2, s22
	v_lshl_add_u32 v86, v4, 7, v7
	ds_write2st64_b32 v85, v82, v86 offset0:8 offset1:10
	s_or_b64 exec, exec, s[16:17]
	s_xor_b64 s[16:17], vcc, -1
	s_and_b64 s[14:15], s[16:17], s[14:15]
	v_cndmask_b32_e64 v85, 0, 1, s[14:15]
	v_cndmask_b32_e64 v82, 0, 1, vcc
	v_add_u32_e32 v82, v83, v82
	v_add_u32_e32 v83, v84, v85
	v_cmp_ge_f32_e32 vcc, v81, v3
	v_cmp_ge_f32_e64 s[14:15], v81, v27
	s_or_b64 s[18:19], vcc, s[14:15]
	v_cndmask_b32_e32 v84, v83, v82, vcc
	v_cmp_gt_i32_e64 s[16:17], 16, v84
	s_and_b64 s[18:19], s[18:19], s[16:17]
	s_and_saveexec_b64 s[16:17], s[18:19]
	v_add_u32_e32 v84, v84, v72
	v_lshl_add_u32 v84, v84, 2, s22
	v_lshl_add_u32 v85, v4, 7, v8
	ds_write2st64_b32 v84, v81, v85 offset0:8 offset1:10
	s_or_b64 exec, exec, s[16:17]
	s_xor_b64 s[16:17], vcc, -1
	s_and_b64 s[14:15], s[16:17], s[14:15]
	v_cndmask_b32_e64 v84, 0, 1, s[14:15]
	v_cndmask_b32_e64 v81, 0, 1, vcc
	v_add_u32_e32 v81, v82, v81
	v_add_u32_e32 v82, v83, v84
	v_cmp_ge_f32_e32 vcc, v22, v3
	v_cmp_ge_f32_e64 s[14:15], v22, v27
	s_or_b64 s[18:19], vcc, s[14:15]
	v_cndmask_b32_e32 v83, v82, v81, vcc
	v_cmp_gt_i32_e64 s[16:17], 16, v83
	s_and_b64 s[18:19], s[18:19], s[16:17]
	s_and_saveexec_b64 s[16:17], s[18:19]
	v_add_u32_e32 v83, v83, v72
	v_lshl_add_u32 v83, v83, 2, s22
	v_lshl_add_u32 v4, v4, 7, v9
	ds_write2st64_b32 v83, v22, v4 offset0:8 offset1:10
	s_or_b64 exec, exec, s[16:17]
	s_xor_b64 s[16:17], vcc, -1
	s_and_b64 s[14:15], s[16:17], s[14:15]
	v_cndmask_b32_e64 v22, 0, 1, s[14:15]
	v_cndmask_b32_e64 v4, 0, 1, vcc
	v_add_u32_e32 v4, v81, v4
	v_add_u32_e32 v22, v82, v22
	v_cmp_ge_f32_e32 vcc, v23, v3
	v_cmp_ge_f32_e64 s[14:15], v23, v27
	s_or_b64 s[18:19], vcc, s[14:15]
	v_cndmask_b32_e32 v81, v22, v4, vcc
	v_cmp_gt_i32_e64 s[16:17], 16, v81
	s_and_b64 s[18:19], s[18:19], s[16:17]
	s_and_saveexec_b64 s[16:17], s[18:19]
	v_add_u32_e32 v81, v81, v72
	v_lshl_add_u32 v81, v81, 2, s22
	v_lshl_add_u32 v18, v5, 7, v18
	ds_write2st64_b32 v81, v23, v18 offset0:8 offset1:10
; __device__ __forceinline__ void peer_select(const float* S, const int row, const int lane, LAS float* sv, LAS int* si, LAS float* fvL, LAS int* eL, int& e0o, int& e1o, float& g0o, float& g1o) {
;     ...
; #pragma unroll
;             for (int j = 0; j < 32; ++j) {
;                 const bool isA = c[j] >= hi, isB = !isA && c[j] >= lo;
;                 const int slot = isA ? pA : pB;
;                 if ((isA || isB) && slot < 16) { fvL[hd * 16 + slot] = c[j]; eL[hd * 16 + slot] = (j < 16 ? i1a : i1b) * 128 + i2[j & 15]; }
;                 pA += isA ? 1 : 0; pB += isB ? 1 : 0;
;             }
	s_or_b64 exec, exec, s[16:17]
	s_xor_b64 s[16:17], vcc, -1
	s_and_b64 s[14:15], s[16:17], s[14:15]
	v_cndmask_b32_e64 v18, 0, 1, s[14:15]
	v_cndmask_b32_e64 v23, 0, 1, vcc
	v_add_u32_e32 v4, v4, v23
	v_add_u32_e32 v18, v22, v18
	v_cmp_ge_f32_e32 vcc, v80, v3
	v_cmp_ge_f32_e64 s[14:15], v80, v27
	s_or_b64 s[18:19], vcc, s[14:15]
	v_cndmask_b32_e32 v22, v18, v4, vcc
	v_cmp_gt_i32_e64 s[16:17], 16, v22
	s_and_b64 s[18:19], s[18:19], s[16:17]
	s_and_saveexec_b64 s[16:17], s[18:19]
	v_add_u32_e32 v22, v22, v72
	v_lshl_add_u32 v22, v22, 2, s22
	v_lshl_add_u32 v19, v5, 7, v19
	ds_write2st64_b32 v22, v80, v19 offset0:8 offset1:10
	s_or_b64 exec, exec, s[16:17]
	s_xor_b64 s[16:17], vcc, -1
	s_and_b64 s[14:15], s[16:17], s[14:15]
	v_cndmask_b32_e64 v19, 0, 1, s[14:15]
	v_cndmask_b32_e64 v22, 0, 1, vcc
	v_add_u32_e32 v4, v4, v22
	v_add_u32_e32 v18, v18, v19
	v_cmp_ge_f32_e32 vcc, v79, v3
	v_cmp_ge_f32_e64 s[14:15], v79, v27
	s_or_b64 s[18:19], vcc, s[14:15]
	v_cndmask_b32_e32 v19, v18, v4, vcc
	v_cmp_gt_i32_e64 s[16:17], 16, v19
	s_and_b64 s[18:19], s[18:19], s[16:17]
	s_and_saveexec_b64 s[16:17], s[18:19]
	v_add_u32_e32 v19, v19, v72
	v_lshl_add_u32 v19, v19, 2, s22
	v_lshl_add_u32 v20, v5, 7, v20
	ds_write2st64_b32 v19, v79, v20 offset0:8 offset1:10
	s_or_b64 exec, exec, s[16:17]
	s_xor_b64 s[16:17], vcc, -1
	s_and_b64 s[14:15], s[16:17], s[14:15]
	v_cndmask_b32_e64 v19, 0, 1, s[14:15]
	v_cndmask_b32_e64 v20, 0, 1, vcc
	v_add_u32_e32 v4, v4, v20
	v_add_u32_e32 v18, v18, v19
	v_cmp_ge_f32_e32 vcc, v78, v3
	v_cmp_ge_f32_e64 s[14:15], v78, v27
	s_or_b64 s[18:19], vcc, s[14:15]
	v_cndmask_b32_e32 v19, v18, v4, vcc
	v_cmp_gt_i32_e64 s[16:17], 16, v19
	s_and_b64 s[18:19], s[18:19], s[16:17]
	s_and_saveexec_b64 s[16:17], s[18:19]
	v_add_u32_e32 v19, v19, v72
	v_lshl_add_u32 v19, v19, 2, s22
	v_lshl_add_u32 v20, v5, 7, v21
	ds_write2st64_b32 v19, v78, v20 offset0:8 offset1:10
	s_or_b64 exec, exec, s[16:17]
	s_xor_b64 s[16:17], vcc, -1
	s_and_b64 s[14:15], s[16:17], s[14:15]
	v_cndmask_b32_e64 v19, 0, 1, s[14:15]
	v_cndmask_b32_e64 v20, 0, 1, vcc
	v_add_u32_e32 v4, v4, v20
	v_add_u32_e32 v18, v18, v19
	v_cmp_ge_f32_e32 vcc, v77, v3
	v_cmp_ge_f32_e64 s[14:15], v77, v27
	s_or_b64 s[18:19], vcc, s[14:15]
	v_cndmask_b32_e32 v19, v18, v4, vcc
	v_cmp_gt_i32_e64 s[16:17], 16, v19
	s_and_b64 s[18:19], s[18:19], s[16:17]
	s_and_saveexec_b64 s[16:17], s[18:19]
	v_add_u32_e32 v19, v19, v72
	v_lshl_add_u32 v19, v19, 2, s22
	v_lshl_add_u32 v14, v5, 7, v14
	ds_write2st64_b32 v19, v77, v14 offset0:8 offset1:10
	s_or_b64 exec, exec, s[16:17]
	s_xor_b64 s[16:17], vcc, -1
	s_and_b64 s[14:15], s[16:17], s[14:15]
	v_cndmask_b32_e64 v14, 0, 1, s[14:15]
	v_cndmask_b32_e64 v19, 0, 1, vcc
	v_add_u32_e32 v4, v4, v19
	v_add_u32_e32 v14, v18, v14
	v_cmp_ge_f32_e32 vcc, v76, v3
	v_cmp_ge_f32_e64 s[14:15], v76, v27
	s_or_b64 s[18:19], vcc, s[14:15]
	v_cndmask_b32_e32 v18, v14, v4, vcc
	v_cmp_gt_i32_e64 s[16:17], 16, v18
	s_and_b64 s[18:19], s[18:19], s[16:17]
	s_and_saveexec_b64 s[16:17], s[18:19]
	v_add_u32_e32 v18, v18, v72
	v_lshl_add_u32 v18, v18, 2, s22
	v_lshl_add_u32 v15, v5, 7, v15
	ds_write2st64_b32 v18, v76, v15 offset0:8 offset1:10
	s_or_b64 exec, exec, s[16:17]
	s_xor_b64 s[16:17], vcc, -1
	s_and_b64 s[14:15], s[16:17], s[14:15]
	v_cndmask_b32_e64 v15, 0, 1, s[14:15]
	v_cndmask_b32_e64 v18, 0, 1, vcc
	v_add_u32_e32 v4, v4, v18
	v_add_u32_e32 v14, v14, v15
	v_cmp_ge_f32_e32 vcc, v33, v3
	v_cmp_ge_f32_e64 s[14:15], v33, v27
	s_or_b64 s[18:19], vcc, s[14:15]
	v_cndmask_b32_e32 v15, v14, v4, vcc
	v_cmp_gt_i32_e64 s[16:17], 16, v15
	s_and_b64 s[18:19], s[18:19], s[16:17]
	s_and_saveexec_b64 s[16:17], s[18:19]
	v_add_u32_e32 v15, v15, v72
	v_lshl_add_u32 v15, v15, 2, s22
	v_lshl_add_u32 v16, v5, 7, v16
	ds_write2st64_b32 v15, v33, v16 offset0:8 offset1:10
	s_or_b64 exec, exec, s[16:17]
	s_xor_b64 s[16:17], vcc, -1
	s_and_b64 s[14:15], s[16:17], s[14:15]
	v_cndmask_b32_e64 v15, 0, 1, s[14:15]
	v_cndmask_b32_e64 v16, 0, 1, vcc
	v_add_u32_e32 v4, v4, v16
	v_add_u32_e32 v14, v14, v15
	v_cmp_ge_f32_e32 vcc, v32, v3
	v_cmp_ge_f32_e64 s[14:15], v32, v27
	s_or_b64 s[18:19], vcc, s[14:15]
	v_cndmask_b32_e32 v15, v14, v4, vcc
	v_cmp_gt_i32_e64 s[16:17], 16, v15
	s_and_b64 s[18:19], s[18:19], s[16:17]
	s_and_saveexec_b64 s[16:17], s[18:19]
	v_add_u32_e32 v15, v15, v72
	v_lshl_add_u32 v15, v15, 2, s22
	v_lshl_add_u32 v16, v5, 7, v17
	ds_write2st64_b32 v15, v32, v16 offset0:8 offset1:10
	s_or_b64 exec, exec, s[16:17]
	s_xor_b64 s[16:17], vcc, -1
	s_and_b64 s[14:15], s[16:17], s[14:15]
	v_cndmask_b32_e64 v15, 0, 1, s[14:15]
	v_cndmask_b32_e64 v16, 0, 1, vcc
	v_add_u32_e32 v4, v4, v16
	v_add_u32_e32 v14, v14, v15
	v_cmp_ge_f32_e32 vcc, v31, v3
	v_cmp_ge_f32_e64 s[14:15], v31, v27
	s_or_b64 s[18:19], vcc, s[14:15]
; __device__ __forceinline__ void peer_select(const float* S, const int row, const int lane, LAS float* sv, LAS int* si, LAS float* fvL, LAS int* eL, int& e0o, int& e1o, float& g0o, float& g1o) {
;     ...
; #pragma unroll
;             for (int j = 0; j < 32; ++j) {
;                 const bool isA = c[j] >= hi, isB = !isA && c[j] >= lo;
;                 const int slot = isA ? pA : pB;
;                 if ((isA || isB) && slot < 16) { fvL[hd * 16 + slot] = c[j]; eL[hd * 16 + slot] = (j < 16 ? i1a : i1b) * 128 + i2[j & 15]; }
;                 pA += isA ? 1 : 0; pB += isB ? 1 : 0;
;             }
	v_cndmask_b32_e32 v15, v14, v4, vcc
	v_cmp_gt_i32_e64 s[16:17], 16, v15
	s_and_b64 s[18:19], s[18:19], s[16:17]
	s_and_saveexec_b64 s[16:17], s[18:19]
	v_add_u32_e32 v15, v15, v72
	v_lshl_add_u32 v15, v15, 2, s22
	v_lshl_add_u32 v10, v5, 7, v10
	ds_write2st64_b32 v15, v31, v10 offset0:8 offset1:10
	s_or_b64 exec, exec, s[16:17]
	s_xor_b64 s[16:17], vcc, -1
	s_and_b64 s[14:15], s[16:17], s[14:15]
	v_cndmask_b32_e64 v10, 0, 1, s[14:15]
	v_cndmask_b32_e64 v15, 0, 1, vcc
	v_add_u32_e32 v4, v4, v15
	v_add_u32_e32 v10, v14, v10
	v_cmp_ge_f32_e32 vcc, v30, v3
	v_cmp_ge_f32_e64 s[14:15], v30, v27
	s_or_b64 s[18:19], vcc, s[14:15]
	v_cndmask_b32_e32 v14, v10, v4, vcc
	v_cmp_gt_i32_e64 s[16:17], 16, v14
	s_and_b64 s[18:19], s[18:19], s[16:17]
	s_and_saveexec_b64 s[16:17], s[18:19]
	v_add_u32_e32 v14, v14, v72
	v_lshl_add_u32 v14, v14, 2, s22
	v_lshl_add_u32 v11, v5, 7, v11
	ds_write2st64_b32 v14, v30, v11 offset0:8 offset1:10
	s_or_b64 exec, exec, s[16:17]
	s_xor_b64 s[16:17], vcc, -1
	s_and_b64 s[14:15], s[16:17], s[14:15]
	v_cndmask_b32_e64 v11, 0, 1, s[14:15]
	v_cndmask_b32_e64 v14, 0, 1, vcc
	v_add_u32_e32 v4, v4, v14
	v_add_u32_e32 v10, v10, v11
	v_cmp_ge_f32_e32 vcc, v29, v3
	v_cmp_ge_f32_e64 s[14:15], v29, v27
	s_or_b64 s[18:19], vcc, s[14:15]
	v_cndmask_b32_e32 v11, v10, v4, vcc
	v_cmp_gt_i32_e64 s[16:17], 16, v11
	s_and_b64 s[18:19], s[18:19], s[16:17]
	s_and_saveexec_b64 s[16:17], s[18:19]
	v_add_u32_e32 v11, v11, v72
	v_lshl_add_u32 v11, v11, 2, s22
	v_lshl_add_u32 v12, v5, 7, v12
	ds_write2st64_b32 v11, v29, v12 offset0:8 offset1:10
	s_or_b64 exec, exec, s[16:17]
	s_xor_b64 s[16:17], vcc, -1
	s_and_b64 s[14:15], s[16:17], s[14:15]
	v_cndmask_b32_e64 v11, 0, 1, s[14:15]
	v_cndmask_b32_e64 v12, 0, 1, vcc
	v_add_u32_e32 v4, v4, v12
	v_add_u32_e32 v10, v10, v11
	v_cmp_ge_f32_e32 vcc, v28, v3
	v_cmp_ge_f32_e64 s[14:15], v28, v27
	s_or_b64 s[18:19], vcc, s[14:15]
	v_cndmask_b32_e32 v11, v10, v4, vcc
	v_cmp_gt_i32_e64 s[16:17], 16, v11
	s_and_b64 s[18:19], s[18:19], s[16:17]
	s_and_saveexec_b64 s[16:17], s[18:19]
	v_add_u32_e32 v11, v11, v72
	v_lshl_add_u32 v11, v11, 2, s22
	v_lshl_add_u32 v12, v5, 7, v13
	ds_write2st64_b32 v11, v28, v12 offset0:8 offset1:10
	s_or_b64 exec, exec, s[16:17]
	s_xor_b64 s[16:17], vcc, -1
	s_and_b64 s[14:15], s[16:17], s[14:15]
	v_cndmask_b32_e64 v11, 0, 1, s[14:15]
	v_cndmask_b32_e64 v12, 0, 1, vcc
	v_add_u32_e32 v4, v4, v12
	v_add_u32_e32 v10, v10, v11
	v_cmp_ge_f32_e32 vcc, v26, v3
	v_cmp_ge_f32_e64 s[14:15], v26, v27
	s_or_b64 s[18:19], vcc, s[14:15]
	v_cndmask_b32_e32 v11, v10, v4, vcc
	v_cmp_gt_i32_e64 s[16:17], 16, v11
	s_and_b64 s[18:19], s[18:19], s[16:17]
	s_and_saveexec_b64 s[16:17], s[18:19]
	v_add_u32_e32 v11, v11, v72
	v_lshl_add_u32 v11, v11, 2, s22
	v_lshl_add_u32 v6, v5, 7, v6
	ds_write2st64_b32 v11, v26, v6 offset0:8 offset1:10
	s_or_b64 exec, exec, s[16:17]
	s_xor_b64 s[16:17], vcc, -1
	s_and_b64 s[14:15], s[16:17], s[14:15]
	v_cndmask_b32_e64 v6, 0, 1, s[14:15]
	v_cndmask_b32_e64 v11, 0, 1, vcc
	v_add_u32_e32 v4, v4, v11
	v_add_u32_e32 v6, v10, v6
	v_cmp_ge_f32_e32 vcc, v25, v3
	v_cmp_ge_f32_e64 s[14:15], v25, v27
	s_or_b64 s[18:19], vcc, s[14:15]
	v_cndmask_b32_e32 v10, v6, v4, vcc
	v_cmp_gt_i32_e64 s[16:17], 16, v10
	s_and_b64 s[18:19], s[18:19], s[16:17]
	s_and_saveexec_b64 s[16:17], s[18:19]
	v_add_u32_e32 v10, v10, v72
	v_lshl_add_u32 v10, v10, 2, s22
	v_lshl_add_u32 v7, v5, 7, v7
	ds_write2st64_b32 v10, v25, v7 offset0:8 offset1:10
	s_or_b64 exec, exec, s[16:17]
	s_xor_b64 s[16:17], vcc, -1
	s_and_b64 s[14:15], s[16:17], s[14:15]
	v_cndmask_b32_e64 v7, 0, 1, s[14:15]
	v_cndmask_b32_e64 v10, 0, 1, vcc
	v_add_u32_e32 v4, v4, v10
	v_add_u32_e32 v6, v6, v7
	v_cmp_ge_f32_e32 vcc, v24, v3
	v_cmp_ge_f32_e64 s[14:15], v24, v27
	s_or_b64 s[18:19], vcc, s[14:15]
	v_cndmask_b32_e32 v7, v6, v4, vcc
	v_cmp_gt_i32_e64 s[16:17], 16, v7
	s_and_b64 s[18:19], s[18:19], s[16:17]
	s_and_saveexec_b64 s[16:17], s[18:19]
	v_add_u32_e32 v7, v7, v72
	v_lshl_add_u32 v7, v7, 2, s22
	v_lshl_add_u32 v8, v5, 7, v8
	ds_write2st64_b32 v7, v24, v8 offset0:8 offset1:10
	s_or_b64 exec, exec, s[16:17]
	s_xor_b64 s[16:17], vcc, -1
	s_and_b64 s[14:15], s[16:17], s[14:15]
	v_cndmask_b32_e64 v7, 0, 1, s[14:15]
	v_cndmask_b32_e64 v8, 0, 1, vcc
	v_add_u32_e32 v4, v4, v8
	v_add_u32_e32 v6, v6, v7
	v_cmp_ge_f32_e64 s[14:15], v2, v3
	v_cmp_ge_f32_e32 vcc, v2, v27
	s_nop 0
	v_cndmask_b32_e64 v3, v6, v4, s[14:15]
	s_or_b64 s[14:15], s[14:15], vcc
	v_cmp_gt_i32_e32 vcc, 16, v3
	s_and_b64 s[16:17], s[14:15], vcc
	s_and_saveexec_b64 s[14:15], s[16:17]
	s_cbranch_execz .LBB0_1377
	v_add_u32_e32 v3, v3, v72
	v_lshl_add_u32 v3, v3, 2, s22
	v_lshl_add_u32 v4, v5, 7, v9
	ds_write2st64_b32 v3, v2, v4 offset0:8 offset1:10
	s_branch .LBB0_1377
